# GQA and MLA tile loops: next-tile loads use scalar base + 32-bit vector offset (no 64-bit VALU address math), first row-sum add folded; plus pipelined phase-0 prenorm loop
# speedup vs baseline: 1.0074x; 1.0074x over previous
; #define LAS __attribute__((address_space(3)))
; __device__ __forceinline__ unsigned cvtpk(float lo, float hi) { typedef __bf16 bf2 __attribute__((ext_vector_type(2))); f32x2 v = {lo, hi}; bf2 b = __builtin_convertvector(v, bf2); return __builtin_bit_cast(unsigned, b); }
; template <int DQK, int DV, bool BIAS> ...
;     ...
;             float ls = 0.f;
; #pragma unroll
;             for (int hs = 0; hs < 4; ++hs) {
;                 float e[8];
; #pragma unroll
;                 for (int j = 0; j < 8; ++j) { e[j] = __builtin_amdgcn_exp2f(hs < 2 ? p0[8 * (hs & 1) + j] : p1[8 * (hs & 1) + j]); ls += e[j]; }
;                 pw[hs].x = cvtpk(e[0], e[1]); pw[hs].y = cvtpk(e[2], e[3]); pw[hs].z = cvtpk(e[4], e[5]); pw[hs].w = cvtpk(e[6], e[7]);
;                 const bf16x8 pbv = __builtin_bit_cast(bf16x8, pw[hs]);
; #pragma unroll
;                 for (int d = 0; d < NDT; ++d) { const LAS unsigned char* vp = vbase + d * 4096 + hs * 1024;
;                     const v4i16_t a0 = __builtin_amdgcn_ds_read_tr16_b64_v4i16((LAS v4i16_t*)vp), a1 = __builtin_amdgcn_ds_read_tr16_b64_v4i16((LAS v4i16_t*)(vp + 512));
;                     const bf16x8 av = {a0[0], a0[1], a0[2], a0[3], a1[0], a1[1], a1[2], a1[3]};
;                     o[d] = __builtin_amdgcn_mfma_f32_32x32x16_bf16(av, pbv, o[d], 0, 0, 0); }
;                 __builtin_amdgcn_sched_barrier(0);
;             }
;             l += ls;
.LBB0_575:
	v_exp_f32_e32 v96, v150
	v_exp_f32_e32 v97, v151
	v_exp_f32_e32 v112, v152
	v_exp_f32_e32 v113, v153
	v_exp_f32_e32 v159, v154
	v_exp_f32_e32 v160, v155
	ds_read_b64_tr_b16 v[108:109], v174 offset:34816
	ds_read_b64_tr_b16 v[110:111], v174 offset:35328
	v_exp_f32_e32 v161, v156
	v_exp_f32_e32 v162, v157
	ds_read_b64_tr_b16 v[154:155], v174 offset:38912
	ds_read_b64_tr_b16 v[156:157], v174 offset:39424
	v_cvt_pk_bf16_f32 v150, v96, v97
	v_cvt_pk_bf16_f32 v151, v112, v113
	v_cvt_pk_bf16_f32 v152, v159, v160
	v_cvt_pk_bf16_f32 v153, v161, v162
	v_add_f32_e32 v96, v97, v96
	s_waitcnt lgkmcnt(2)
	v_mfma_f32_32x32x16_bf16 v[50:65], v[108:111], v[150:153], v[50:65]
	v_add_f32_e32 v96, v112, v96
	v_add_f32_e32 v96, v113, v96
	v_add_f32_e32 v96, v159, v96
	v_add_f32_e32 v96, v160, v96
	v_add_f32_e32 v96, v161, v96
	v_add_f32_e32 v96, v162, v96
	s_waitcnt lgkmcnt(0)
	v_mfma_f32_32x32x16_bf16 v[34:49], v[154:157], v[150:153], v[34:49]
	ds_read_b64_tr_b16 v[108:109], v174 offset:43008
	ds_read_b64_tr_b16 v[110:111], v174 offset:43520
	ds_read_b64_tr_b16 v[154:155], v174 offset:47104
	ds_read_b64_tr_b16 v[156:157], v174 offset:47616
	s_waitcnt lgkmcnt(2)
	v_mfma_f32_32x32x16_bf16 v[18:33], v[108:111], v[150:153], v[18:33]
	s_waitcnt lgkmcnt(0)
	v_mfma_f32_32x32x16_bf16 v[2:17], v[154:157], v[150:153], v[2:17]
	v_exp_f32_e32 v97, v104
	v_exp_f32_e32 v112, v105
	v_exp_f32_e32 v113, v106
	v_exp_f32_e32 v150, v107
	v_exp_f32_e32 v151, v92
	v_exp_f32_e32 v152, v93
	ds_read_b64_tr_b16 v[104:105], v174 offset:35840
	ds_read_b64_tr_b16 v[106:107], v174 offset:36352
	v_exp_f32_e32 v153, v94
	v_exp_f32_e32 v154, v95
	ds_read_b64_tr_b16 v[108:109], v174 offset:39936
	ds_read_b64_tr_b16 v[110:111], v174 offset:40448
	v_cvt_pk_bf16_f32 v92, v97, v112
	v_cvt_pk_bf16_f32 v93, v113, v150
	v_cvt_pk_bf16_f32 v94, v151, v152
	v_cvt_pk_bf16_f32 v95, v153, v154
	v_add_f32_e32 v96, v97, v96
	v_add_f32_e32 v96, v112, v96
	s_waitcnt lgkmcnt(2)
	v_mfma_f32_32x32x16_bf16 v[50:65], v[104:107], v[92:95], v[50:65]
	v_add_f32_e32 v96, v113, v96
	v_add_f32_e32 v96, v150, v96
	v_add_f32_e32 v96, v151, v96
	v_add_f32_e32 v96, v152, v96
	v_add_f32_e32 v96, v153, v96
	s_waitcnt lgkmcnt(0)
	v_mfma_f32_32x32x16_bf16 v[34:49], v[108:111], v[92:95], v[34:49]
	ds_read_b64_tr_b16 v[104:105], v174 offset:44032
	ds_read_b64_tr_b16 v[106:107], v174 offset:44544
	ds_read_b64_tr_b16 v[108:109], v174 offset:48128
	ds_read_b64_tr_b16 v[110:111], v174 offset:48640
	s_waitcnt lgkmcnt(2)
	v_mfma_f32_32x32x16_bf16 v[18:33], v[104:107], v[92:95], v[18:33]
	v_add_f32_e32 v104, v154, v96
	s_waitcnt lgkmcnt(0)
	v_mfma_f32_32x32x16_bf16 v[2:17], v[108:111], v[92:95], v[2:17]
	v_exp_f32_e32 v82, v82
	v_exp_f32_e32 v83, v83
	v_exp_f32_e32 v105, v98
	v_exp_f32_e32 v106, v99
	v_exp_f32_e32 v107, v100
	v_exp_f32_e32 v108, v101
	ds_read_b64_tr_b16 v[92:93], v174 offset:36864
	ds_read_b64_tr_b16 v[94:95], v174 offset:37376
	v_exp_f32_e32 v109, v102
	v_exp_f32_e32 v110, v103
	ds_read_b64_tr_b16 v[100:101], v174 offset:40960
	ds_read_b64_tr_b16 v[102:103], v174 offset:41472
	v_cvt_pk_bf16_f32 v96, v82, v83
	v_cvt_pk_bf16_f32 v97, v105, v106
	v_cvt_pk_bf16_f32 v98, v107, v108
	v_cvt_pk_bf16_f32 v99, v109, v110
	v_add_f32_e32 v82, v82, v104
	v_add_f32_e32 v82, v83, v82
	s_waitcnt lgkmcnt(2)
	v_mfma_f32_32x32x16_bf16 v[50:65], v[92:95], v[96:99], v[50:65]
	v_add_f32_e32 v82, v105, v82
	v_add_f32_e32 v82, v106, v82
	v_add_f32_e32 v82, v107, v82
	v_add_f32_e32 v82, v108, v82
	v_add_f32_e32 v82, v109, v82
	s_waitcnt lgkmcnt(0)
	v_mfma_f32_32x32x16_bf16 v[34:49], v[100:103], v[96:99], v[34:49]
	ds_read_b64_tr_b16 v[92:93], v174 offset:45056
	ds_read_b64_tr_b16 v[94:95], v174 offset:45568
	ds_read_b64_tr_b16 v[100:101], v174 offset:49152
	ds_read_b64_tr_b16 v[102:103], v174 offset:49664
	s_waitcnt lgkmcnt(2)
	v_mfma_f32_32x32x16_bf16 v[18:33], v[92:95], v[96:99], v[18:33]
	v_add_f32_e32 v94, v110, v82
	s_waitcnt lgkmcnt(0)
	v_mfma_f32_32x32x16_bf16 v[2:17], v[100:103], v[96:99], v[2:17]
	v_exp_f32_e32 v95, v84
	v_exp_f32_e32 v96, v85
	v_exp_f32_e32 v97, v86
	v_exp_f32_e32 v98, v87
	v_exp_f32_e32 v99, v88
	v_exp_f32_e32 v100, v89
	ds_read_b64_tr_b16 v[82:83], v174 offset:37888
	ds_read_b64_tr_b16 v[84:85], v174 offset:38400
	v_exp_f32_e32 v101, v90
	v_exp_f32_e32 v102, v91
	ds_read_b64_tr_b16 v[90:91], v174 offset:41984
	ds_read_b64_tr_b16 v[92:93], v174 offset:42496
	v_cvt_pk_bf16_f32 v86, v95, v96
	v_cvt_pk_bf16_f32 v87, v97, v98
	v_cvt_pk_bf16_f32 v88, v99, v100
	v_cvt_pk_bf16_f32 v89, v101, v102
	s_waitcnt lgkmcnt(2)
	s_nop 0
	v_mfma_f32_32x32x16_bf16 v[50:65], v[82:85], v[86:89], v[50:65]
	s_waitcnt lgkmcnt(0)
	v_mfma_f32_32x32x16_bf16 v[34:49], v[90:93], v[86:89], v[34:49]
	ds_read_b64_tr_b16 v[82:83], v174 offset:46080
	ds_read_b64_tr_b16 v[84:85], v174 offset:46592
	ds_read_b64_tr_b16 v[90:91], v174 offset:50176
	ds_read_b64_tr_b16 v[92:93], v174 offset:50688
	s_waitcnt lgkmcnt(2)
	v_mfma_f32_32x32x16_bf16 v[18:33], v[82:85], v[86:89], v[18:33]
	v_add_f32_e32 v82, v95, v94
	v_add_f32_e32 v82, v96, v82
	v_add_f32_e32 v82, v97, v82
	v_add_f32_e32 v82, v98, v82
	v_add_f32_e32 v82, v99, v82
	v_add_f32_e32 v82, v100, v82
	v_add_f32_e32 v82, v101, v82
	s_waitcnt lgkmcnt(0)
	v_mfma_f32_32x32x16_bf16 v[2:17], v[90:93], v[86:89], v[2:17]
	v_add_f32_e32 v82, v102, v82

; #define LAS __attribute__((address_space(3)))
; __device__ __forceinline__ float max3f(float a, float b, float c) { float r; asm("v_max3_f32 %0, %1, %2, %3" : "=v"(r) : "v"(a), "v"(b), "v"(c)); return r; }
; template <int DQK, int DV, bool BIAS> ...
;     ...
;         const LAS unsigned char* kb = lds + buf * KBUF + r32 * KP + hi * 16;
; #pragma unroll
;         for (int ks = 0; ks < NKS; ++ks) {
;             const bf16x8 k0 = *(const LAS bf16x8*)(kb + ks * 32), k1 = *(const LAS bf16x8*)(kb + 32 * KP + ks * 32);
;             if (ks == 0) { p0 = __builtin_amdgcn_mfma_f32_32x32x16_bf16(k0, qf[0], negm, 0, 0, 0); p1 = __builtin_amdgcn_mfma_f32_32x32x16_bf16(k1, qf[0], negm, 0, 0, 0); }
;             else { p0 = __builtin_amdgcn_mfma_f32_32x32x16_bf16(k0, qf[ks], p0, 0, 0, 0); p1 = __builtin_amdgcn_mfma_f32_32x32x16_bf16(k1, qf[ks], p1, 0, 0, 0); }
;         }
;         if (BIAS) {
;             asm volatile("s_nop 15\n\ts_nop 7" : "+v"(p0), "+v"(p1));
;             const float d0 = qp - (float)(t * 64 + 4 * hi);
; #pragma unroll
;             for (int r = 0; r < 16; ++r) { const float dk = d0 - (float)((r & 3) + 8 * (r >> 2)); p0[r] = p0[r] - sl2 * fabsf(dk); p1[r] = p1[r] - sl2 * fabsf(dk - 32.f); }
;         } else {
;             asm volatile("s_nop 15\n\ts_nop 7" : "+v"(p0), "+v"(p1));
;         }
;         float mxa = max3f(p0[0], p0[1], p1[0]), mxb = max3f(p0[2], p0[3], p1[1]); mxa = max3f(mxa, p1[2], p1[3]);
; #pragma unroll
;         for (int r = 4; r < 16; r += 4) { mxa = max3f(mxa, p0[r], p0[r + 1]); mxb = max3f(mxb, p0[r + 2], p0[r + 3]); mxa = max3f(mxa, p1[r], p1[r + 1]); mxb = max3f(mxb, p1[r + 2], p1[r + 3]); }
;         float mx = fmaxf(mxa, mxb);
.LBB0_584:
	ds_read_b128 v[192:195], v175 offset:9216
	ds_read_b128 v[196:199], v175 offset:9248
	v_add_f32_e32 v156, v157, v156
	v_add_f32_e32 v156, v160, v156
	s_waitcnt lgkmcnt(1)
	v_mfma_f32_32x32x16_bf16 v[98:113], v[192:195], v[114:117], v[66:81]
	ds_read_b128 v[192:195], v175 offset:13824
	ds_read_b128 v[200:203], v175 offset:13856
	v_add_f32_e32 v156, v161, v156
	v_add_f32_e32 v156, v164, v156
	v_add_f32_e32 v150, v150, v156
	v_add_f32_e32 v150, v165, v150
	v_add_f32_e32 v150, v166, v150
	v_add_f32_e32 v150, v167, v150
	s_waitcnt lgkmcnt(1)
	v_mfma_f32_32x32x16_bf16 v[82:97], v[192:195], v[114:117], v[66:81]
	v_add_f32_e32 v150, v177, v150
	v_add_f32_e32 v150, v178, v150
	v_add_f32_e32 v150, v158, v150
	v_add_f32_e32 v150, v159, v150
	ds_read_b128 v[164:167], v175 offset:9280
	v_add_f32_e32 v150, v162, v150
	v_add_f32_e32 v150, v163, v150
	v_mfma_f32_32x32x16_bf16 v[98:113], v[196:199], v[118:121], v[98:113]
	v_add_f32_e32 v150, v179, v150
	v_add_f32_e32 v150, v180, v150
	v_add_f32_e32 v150, v181, v150
	v_add_f32_e32 v150, v152, v150
	ds_read_b128 v[156:159], v175 offset:13888
	ds_read_b128 v[160:163], v175 offset:9312
	v_add_f32_e32 v150, v153, v150
	v_add_f32_e32 v150, v182, v150
	s_waitcnt lgkmcnt(3)
	v_mfma_f32_32x32x16_bf16 v[82:97], v[200:203], v[118:121], v[82:97]
	v_add_f32_e32 v150, v183, v150
	v_add_f32_e32 v150, v154, v150
	v_add_f32_e32 v150, v155, v150
	v_add_f32_e32 v150, v184, v150
	v_add_f32_e32 v150, v185, v150
	v_add_u32_e32 v152, 64, v173
	v_add_f32_e32 v150, v186, v150
	s_waitcnt lgkmcnt(2)
	v_mfma_f32_32x32x16_bf16 v[98:113], v[164:167], v[122:125], v[98:113]
	ds_read_b128 v[164:167], v175 offset:13920
	v_cvt_f32_u32_e32 v152, v152
	v_add_f32_e32 v150, v187, v150
	v_add_f32_e32 v150, v188, v150
	v_add_f32_e32 v150, v191, v150
	v_add_f32_e32 v150, v189, v150
	v_add_f32_e32 v150, v190, v150
	s_waitcnt lgkmcnt(2)
	v_mfma_f32_32x32x16_bf16 v[82:97], v[156:159], v[122:125], v[82:97]
	v_add_f32_e32 v158, v151, v150
	s_waitcnt lgkmcnt(1)
	v_mfma_f32_32x32x16_bf16 v[98:113], v[160:163], v[126:129], v[98:113]
	v_sub_f32_e32 v160, v172, v152
	v_add_f32_e32 v161, -1.0, v160
	v_and_b32_e32 v150, 0x7fffffff, v160
	v_and_b32_e32 v151, 0x7fffffff, v161
	s_waitcnt lgkmcnt(0)
	v_mfma_f32_32x32x16_bf16 v[82:97], v[164:167], v[126:129], v[82:97]
	s_nop 15
	s_nop 7
	s_nop 5
	v_pk_fma_f32 v[150:151], v[142:143], v[150:151], v[98:99] neg_lo:[1,0,0] neg_hi:[1,0,0]
	v_pk_add_f32 v[98:99], v[160:161], s[8:9] op_sel_hi:[1,0]
	s_nop 0
	v_fma_f32 v83, -v143, |v99|, v83
	v_fma_f32 v82, -v142, |v98|, v82
	s_nop 0
	v_pk_add_f32 v[98:99], v[160:161], s[10:11] op_sel_hi:[0,1]
	v_fma_f32 v153, -v143, |v99|, v101
	v_fma_f32 v152, -v142, |v98|, v100
	v_pk_add_f32 v[98:99], v[98:99], s[8:9] op_sel_hi:[1,0]
	v_fma_f32 v99, -v143, |v99|, v85
	v_fma_f32 v98, -v142, |v98|, v84
	v_pk_add_f32 v[84:85], v[160:161], s[22:23] op_sel_hi:[0,1]
	v_fma_f32 v155, -v143, |v85|, v103
	v_fma_f32 v154, -v142, |v84|, v102
	v_pk_add_f32 v[84:85], v[84:85], s[8:9] op_sel_hi:[1,0]
	v_fma_f32 v101, -v143, |v85|, v87
	v_fma_f32 v100, -v142, |v84|, v86
	v_pk_add_f32 v[84:85], v[160:161], s[34:35] op_sel_hi:[0,1]
	v_fma_f32 v157, -v143, |v85|, v105
	v_fma_f32 v156, -v142, |v84|, v104
	v_pk_add_f32 v[84:85], v[84:85], s[8:9] op_sel_hi:[1,0]
	v_fma_f32 v103, -v143, |v85|, v89
	v_fma_f32 v102, -v142, |v84|, v88
	v_pk_add_f32 v[84:85], v[160:161], s[36:37] op_sel_hi:[0,1]
	v_fma_f32 v105, -v143, |v85|, v107
	v_fma_f32 v104, -v142, |v84|, v106
	v_pk_add_f32 v[86:87], v[160:161], s[38:39] op_sel_hi:[0,1]
	v_pk_add_f32 v[84:85], v[84:85], s[8:9] op_sel_hi:[1,0]
	v_fma_f32 v107, -v143, |v87|, v109
	v_fma_f32 v106, -v142, |v86|, v108
	v_fma_f32 v85, -v143, |v85|, v91
	v_fma_f32 v84, -v142, |v84|, v90
	v_pk_add_f32 v[86:87], v[86:87], s[8:9] op_sel_hi:[1,0]
	v_pk_add_f32 v[88:89], v[160:161], s[40:41] op_sel_hi:[0,1]
	v_fma_f32 v87, -v143, |v87|, v93
	v_fma_f32 v86, -v142, |v86|, v92
	v_fma_f32 v93, -v143, |v89|, v111
	v_fma_f32 v92, -v142, |v88|, v110
	v_pk_add_f32 v[88:89], v[88:89], s[8:9] op_sel_hi:[1,0]
	v_fma_f32 v89, -v143, |v89|, v95
	v_fma_f32 v88, -v142, |v88|, v94
	v_pk_add_f32 v[90:91], v[160:161], s[42:43] op_sel_hi:[0,1]
	v_fma_f32 v95, -v143, |v91|, v113
	v_fma_f32 v94, -v142, |v90|, v112
	v_pk_add_f32 v[90:91], v[90:91], s[8:9] op_sel_hi:[1,0]
	v_fma_f32 v91, -v143, |v91|, v97
	v_fma_f32 v90, -v142, |v90|, v96
	v_max3_f32 v96, v150, v151, v82
	v_max3_f32 v97, v152, v153, v83
	v_max3_f32 v96, v96, v98, v99
	v_max3_f32 v97, v97, v156, v157
	v_max3_f32 v96, v96, v154, v155
	v_max3_f32 v97, v97, v102, v103
	v_max3_f32 v96, v96, v100, v101
	v_max3_f32 v97, v97, v106, v107
	v_max3_f32 v96, v96, v104, v105
	v_max3_f32 v97, v97, v86, v87
	v_max3_f32 v96, v96, v84, v85
	v_max3_f32 v97, v97, v94, v95
	v_max3_f32 v96, v96, v92, v93
	v_max3_f32 v97, v97, v90, v91
	v_max3_f32 v96, v96, v88, v89
	v_max_f32_e32 v96, v96, v97
	v_cmp_gt_f32_e32 vcc, 0xc3400000, v96
	s_cmp_eq_u64 vcc, exec
	s_cbranch_scc1 .Lsk2_p4a1
; template <int DQK, int DV, bool BIAS> ...
;     ...
;         if (__any(mx > 8.f)) {
;             mx = fmaxf(mx, __shfl_xor(mx, 32));
;             const float dl = fmaxf(mx, 0.f); mhat += dl;
;             const float f = __builtin_amdgcn_exp2f(-dl);
; #pragma unroll
;             for (int r = 0; r < 16; ++r) { p0[r] -= dl; p1[r] -= dl; negm[r] = -mhat; }
;             l *= f;
; #pragma unroll
;             for (int d = 0; d < NDT; ++d)
; #pragma unroll
;                 for (int r = 0; r < 16; ++r) o[d][r] *= f;
;         }
	v_cmp_lt_f32_e32 vcc, s52, v96
	s_cbranch_vccz .LBB0_575
	v_and_b32_e32 v67, 64, v170
	v_xor_b32_e32 v66, 32, v170
	v_add_u32_e32 v67, 64, v67
	v_cmp_lt_i32_e32 vcc, v66, v67
	s_nop 1
	v_cndmask_b32_e32 v66, v170, v66, vcc
	v_lshlrev_b32_e32 v66, 2, v66
	ds_bpermute_b32 v66, v66, v96
	s_waitcnt lgkmcnt(0)
	v_max3_f32 v67, v96, v66, 0
	v_exp_f32_e64 v68, -v67
	v_add_f32_e32 v176, v176, v67
	v_xor_b32_e32 v66, 0x80000000, v176
	v_sub_f32_e32 v82, v82, v67
	v_sub_f32_e32 v83, v83, v67
	v_sub_f32_e32 v98, v98, v67
	v_sub_f32_e32 v99, v99, v67
	v_sub_f32_e32 v100, v100, v67
	v_sub_f32_e32 v101, v101, v67
	v_sub_f32_e32 v102, v102, v67
	v_sub_f32_e32 v103, v103, v67
	v_sub_f32_e32 v84, v84, v67
	v_sub_f32_e32 v85, v85, v67
	v_sub_f32_e32 v86, v86, v67
	v_sub_f32_e32 v87, v87, v67
	v_sub_f32_e32 v88, v88, v67
	v_sub_f32_e32 v89, v89, v67
	v_sub_f32_e32 v90, v90, v67
	v_sub_f32_e32 v91, v91, v67
	v_pk_mul_f32 v[64:65], v[64:65], v[68:69] op_sel_hi:[1,0]
	v_pk_mul_f32 v[62:63], v[62:63], v[68:69] op_sel_hi:[1,0]
	v_pk_mul_f32 v[60:61], v[60:61], v[68:69] op_sel_hi:[1,0]
	v_pk_mul_f32 v[58:59], v[58:59], v[68:69] op_sel_hi:[1,0]
	v_pk_mul_f32 v[56:57], v[56:57], v[68:69] op_sel_hi:[1,0]
	v_pk_mul_f32 v[54:55], v[54:55], v[68:69] op_sel_hi:[1,0]
	v_pk_mul_f32 v[52:53], v[52:53], v[68:69] op_sel_hi:[1,0]
	v_pk_mul_f32 v[50:51], v[50:51], v[68:69] op_sel_hi:[1,0]
	v_pk_mul_f32 v[48:49], v[48:49], v[68:69] op_sel_hi:[1,0]
	v_pk_mul_f32 v[46:47], v[46:47], v[68:69] op_sel_hi:[1,0]
	v_pk_mul_f32 v[44:45], v[44:45], v[68:69] op_sel_hi:[1,0]
	v_pk_mul_f32 v[42:43], v[42:43], v[68:69] op_sel_hi:[1,0]
	v_pk_mul_f32 v[40:41], v[40:41], v[68:69] op_sel_hi:[1,0]
	v_pk_mul_f32 v[38:39], v[38:39], v[68:69] op_sel_hi:[1,0]
	v_pk_mul_f32 v[36:37], v[36:37], v[68:69] op_sel_hi:[1,0]
	v_pk_mul_f32 v[34:35], v[34:35], v[68:69] op_sel_hi:[1,0]
	v_pk_mul_f32 v[32:33], v[32:33], v[68:69] op_sel_hi:[1,0]
	v_pk_mul_f32 v[30:31], v[30:31], v[68:69] op_sel_hi:[1,0]
	v_pk_mul_f32 v[28:29], v[28:29], v[68:69] op_sel_hi:[1,0]
	v_pk_mul_f32 v[26:27], v[26:27], v[68:69] op_sel_hi:[1,0]
	v_pk_mul_f32 v[24:25], v[24:25], v[68:69] op_sel_hi:[1,0]
	v_pk_mul_f32 v[22:23], v[22:23], v[68:69] op_sel_hi:[1,0]
	v_pk_mul_f32 v[20:21], v[20:21], v[68:69] op_sel_hi:[1,0]
	v_pk_mul_f32 v[18:19], v[18:19], v[68:69] op_sel_hi:[1,0]
	v_pk_mul_f32 v[16:17], v[16:17], v[68:69] op_sel_hi:[1,0]
	v_pk_mul_f32 v[14:15], v[14:15], v[68:69] op_sel_hi:[1,0]
	v_pk_mul_f32 v[12:13], v[12:13], v[68:69] op_sel_hi:[1,0]
	v_pk_mul_f32 v[10:11], v[10:11], v[68:69] op_sel_hi:[1,0]
	v_pk_mul_f32 v[8:9], v[8:9], v[68:69] op_sel_hi:[1,0]
	v_pk_mul_f32 v[6:7], v[6:7], v[68:69] op_sel_hi:[1,0]
	v_pk_mul_f32 v[4:5], v[4:5], v[68:69] op_sel_hi:[1,0]
	v_pk_mul_f32 v[2:3], v[2:3], v[68:69] op_sel_hi:[1,0]
	v_sub_f32_e32 v150, v150, v67
	v_sub_f32_e32 v151, v151, v67
	v_sub_f32_e32 v152, v152, v67
	v_sub_f32_e32 v153, v153, v67
	v_sub_f32_e32 v154, v154, v67
	v_sub_f32_e32 v155, v155, v67
	v_sub_f32_e32 v156, v156, v67
	v_sub_f32_e32 v157, v157, v67
	v_sub_f32_e32 v104, v104, v67
	v_sub_f32_e32 v105, v105, v67
	v_sub_f32_e32 v106, v106, v67
	v_sub_f32_e32 v107, v107, v67
	v_sub_f32_e32 v92, v92, v67
	v_sub_f32_e32 v93, v93, v67
	v_sub_f32_e32 v94, v94, v67
	v_sub_f32_e32 v95, v95, v67
	v_mul_f32_e32 v158, v158, v68
	v_mov_b32_e32 v67, v66
	v_mov_b32_e32 v68, v66
	v_mov_b32_e32 v69, v66
	v_mov_b32_e32 v70, v66
	v_mov_b32_e32 v71, v66
	v_mov_b32_e32 v72, v66
	v_mov_b32_e32 v73, v66
	v_mov_b32_e32 v74, v66
	v_mov_b32_e32 v75, v66
	v_mov_b32_e32 v76, v66
	v_mov_b32_e32 v77, v66
	v_mov_b32_e32 v78, v66
	v_mov_b32_e32 v79, v66
	v_mov_b32_e32 v80, v66
	v_mov_b32_e32 v81, v66
	s_branch .LBB0_575

; #define LAS __attribute__((address_space(3)))
; __device__ __forceinline__ unsigned cvtpk(float lo, float hi) { typedef __bf16 bf2 __attribute__((ext_vector_type(2))); f32x2 v = {lo, hi}; bf2 b = __builtin_convertvector(v, bf2); return __builtin_bit_cast(unsigned, b); }
; template <int DQK, int DV, bool BIAS> ...
;     ...
;             float ls = 0.f;
; #pragma unroll
;             for (int hs = 0; hs < 4; ++hs) {
;                 float e[8];
; #pragma unroll
;                 for (int j = 0; j < 8; ++j) { e[j] = __builtin_amdgcn_exp2f(hs < 2 ? p0[8 * (hs & 1) + j] : p1[8 * (hs & 1) + j]); ls += e[j]; }
;                 pw[hs].x = cvtpk(e[0], e[1]); pw[hs].y = cvtpk(e[2], e[3]); pw[hs].z = cvtpk(e[4], e[5]); pw[hs].w = cvtpk(e[6], e[7]);
;                 const bf16x8 pbv = __builtin_bit_cast(bf16x8, pw[hs]);
; #pragma unroll
;                 for (int d = 0; d < NDT; ++d) { const LAS unsigned char* vp = vbase + d * 4096 + hs * 1024;
;                     const v4i16_t a0 = __builtin_amdgcn_ds_read_tr16_b64_v4i16((LAS v4i16_t*)vp), a1 = __builtin_amdgcn_ds_read_tr16_b64_v4i16((LAS v4i16_t*)(vp + 512));
;                     const bf16x8 av = {a0[0], a0[1], a0[2], a0[3], a1[0], a1[1], a1[2], a1[3]};
;                     o[d] = __builtin_amdgcn_mfma_f32_32x32x16_bf16(av, pbv, o[d], 0, 0, 0); }
;                 __builtin_amdgcn_sched_barrier(0);
;             }
;             l += ls;
.LBB0_587:
	v_exp_f32_e32 v96, v150
	v_exp_f32_e32 v97, v151
	v_exp_f32_e32 v112, v152
	v_exp_f32_e32 v113, v153
	v_exp_f32_e32 v159, v154
	v_exp_f32_e32 v160, v155
	ds_read_b64_tr_b16 v[108:109], v178 offset:34816
	ds_read_b64_tr_b16 v[110:111], v178 offset:35328
	v_exp_f32_e32 v161, v156
	v_exp_f32_e32 v162, v157
	ds_read_b64_tr_b16 v[154:155], v178 offset:38912
	ds_read_b64_tr_b16 v[156:157], v178 offset:39424
	v_cvt_pk_bf16_f32 v150, v96, v97
	v_cvt_pk_bf16_f32 v151, v112, v113
	v_cvt_pk_bf16_f32 v152, v159, v160
	v_cvt_pk_bf16_f32 v153, v161, v162
	v_add_f32_e32 v96, v97, v96
	s_waitcnt lgkmcnt(2)
	v_mfma_f32_32x32x16_bf16 v[2:17], v[108:111], v[150:153], v[2:17]
	v_add_f32_e32 v96, v112, v96
	v_add_f32_e32 v96, v113, v96
	v_add_f32_e32 v96, v159, v96
	v_add_f32_e32 v96, v160, v96
	v_add_f32_e32 v96, v161, v96
	v_add_f32_e32 v96, v162, v96
	s_waitcnt lgkmcnt(0)
	v_mfma_f32_32x32x16_bf16 v[18:33], v[154:157], v[150:153], v[18:33]
	ds_read_b64_tr_b16 v[108:109], v178 offset:43008
	ds_read_b64_tr_b16 v[110:111], v178 offset:43520
	ds_read_b64_tr_b16 v[154:155], v178 offset:47104
	ds_read_b64_tr_b16 v[156:157], v178 offset:47616
	s_waitcnt lgkmcnt(2)
	v_mfma_f32_32x32x16_bf16 v[34:49], v[108:111], v[150:153], v[34:49]
	s_waitcnt lgkmcnt(0)
	v_mfma_f32_32x32x16_bf16 v[50:65], v[154:157], v[150:153], v[50:65]
	v_exp_f32_e32 v97, v104
	v_exp_f32_e32 v112, v105
	v_exp_f32_e32 v113, v106
	v_exp_f32_e32 v150, v107
	v_exp_f32_e32 v151, v92
	v_exp_f32_e32 v152, v93
	ds_read_b64_tr_b16 v[104:105], v178 offset:35840
	ds_read_b64_tr_b16 v[106:107], v178 offset:36352
	v_exp_f32_e32 v153, v94
	v_exp_f32_e32 v154, v95
	ds_read_b64_tr_b16 v[108:109], v178 offset:39936
	ds_read_b64_tr_b16 v[110:111], v178 offset:40448
	v_cvt_pk_bf16_f32 v92, v97, v112
	v_cvt_pk_bf16_f32 v93, v113, v150
	v_cvt_pk_bf16_f32 v94, v151, v152
	v_cvt_pk_bf16_f32 v95, v153, v154
	v_add_f32_e32 v96, v97, v96
	v_add_f32_e32 v96, v112, v96
	s_waitcnt lgkmcnt(2)
	v_mfma_f32_32x32x16_bf16 v[2:17], v[104:107], v[92:95], v[2:17]
	v_add_f32_e32 v96, v113, v96
	v_add_f32_e32 v96, v150, v96
	v_add_f32_e32 v96, v151, v96
	v_add_f32_e32 v96, v152, v96
	v_add_f32_e32 v96, v153, v96
	s_waitcnt lgkmcnt(0)
	v_mfma_f32_32x32x16_bf16 v[18:33], v[108:111], v[92:95], v[18:33]
	ds_read_b64_tr_b16 v[104:105], v178 offset:44032
	ds_read_b64_tr_b16 v[106:107], v178 offset:44544
	ds_read_b64_tr_b16 v[108:109], v178 offset:48128
	ds_read_b64_tr_b16 v[110:111], v178 offset:48640
	s_waitcnt lgkmcnt(2)
	v_mfma_f32_32x32x16_bf16 v[34:49], v[104:107], v[92:95], v[34:49]
	v_add_f32_e32 v104, v154, v96
	s_waitcnt lgkmcnt(0)
	v_mfma_f32_32x32x16_bf16 v[50:65], v[108:111], v[92:95], v[50:65]
	v_exp_f32_e32 v82, v82
	v_exp_f32_e32 v83, v83
	v_exp_f32_e32 v105, v98
	v_exp_f32_e32 v106, v99
	v_exp_f32_e32 v107, v100
	v_exp_f32_e32 v108, v101
	ds_read_b64_tr_b16 v[92:93], v178 offset:36864
	ds_read_b64_tr_b16 v[94:95], v178 offset:37376
	v_exp_f32_e32 v109, v102
	v_exp_f32_e32 v110, v103
	ds_read_b64_tr_b16 v[100:101], v178 offset:40960
	ds_read_b64_tr_b16 v[102:103], v178 offset:41472
	v_cvt_pk_bf16_f32 v96, v82, v83
	v_cvt_pk_bf16_f32 v97, v105, v106
	v_cvt_pk_bf16_f32 v98, v107, v108
	v_cvt_pk_bf16_f32 v99, v109, v110
	v_add_f32_e32 v82, v82, v104
	v_add_f32_e32 v82, v83, v82
	s_waitcnt lgkmcnt(2)
	v_mfma_f32_32x32x16_bf16 v[2:17], v[92:95], v[96:99], v[2:17]
	v_add_f32_e32 v82, v105, v82
	v_add_f32_e32 v82, v106, v82
	v_add_f32_e32 v82, v107, v82
	v_add_f32_e32 v82, v108, v82
	v_add_f32_e32 v82, v109, v82
	s_waitcnt lgkmcnt(0)
	v_mfma_f32_32x32x16_bf16 v[18:33], v[100:103], v[96:99], v[18:33]
	ds_read_b64_tr_b16 v[92:93], v178 offset:45056
	ds_read_b64_tr_b16 v[94:95], v178 offset:45568
	ds_read_b64_tr_b16 v[100:101], v178 offset:49152
	ds_read_b64_tr_b16 v[102:103], v178 offset:49664
	s_waitcnt lgkmcnt(2)
	v_mfma_f32_32x32x16_bf16 v[34:49], v[92:95], v[96:99], v[34:49]
	v_add_f32_e32 v94, v110, v82
	s_waitcnt lgkmcnt(0)
	v_mfma_f32_32x32x16_bf16 v[50:65], v[100:103], v[96:99], v[50:65]
	v_exp_f32_e32 v95, v84
	v_exp_f32_e32 v96, v85
	v_exp_f32_e32 v97, v86
	v_exp_f32_e32 v98, v87
	v_exp_f32_e32 v99, v88
	v_exp_f32_e32 v100, v89
	ds_read_b64_tr_b16 v[82:83], v178 offset:37888
	ds_read_b64_tr_b16 v[84:85], v178 offset:38400
	v_exp_f32_e32 v101, v90
	v_exp_f32_e32 v102, v91
	ds_read_b64_tr_b16 v[90:91], v178 offset:41984
	ds_read_b64_tr_b16 v[92:93], v178 offset:42496
	v_cvt_pk_bf16_f32 v86, v95, v96
	v_cvt_pk_bf16_f32 v87, v97, v98
	v_cvt_pk_bf16_f32 v88, v99, v100
	v_cvt_pk_bf16_f32 v89, v101, v102
	s_waitcnt lgkmcnt(2)
	s_nop 0
	v_mfma_f32_32x32x16_bf16 v[2:17], v[82:85], v[86:89], v[2:17]
	s_waitcnt lgkmcnt(0)
	v_mfma_f32_32x32x16_bf16 v[18:33], v[90:93], v[86:89], v[18:33]
	ds_read_b64_tr_b16 v[82:83], v178 offset:46080
	ds_read_b64_tr_b16 v[84:85], v178 offset:46592
	ds_read_b64_tr_b16 v[90:91], v178 offset:50176
	ds_read_b64_tr_b16 v[92:93], v178 offset:50688
	s_waitcnt lgkmcnt(2)
	v_mfma_f32_32x32x16_bf16 v[34:49], v[82:85], v[86:89], v[34:49]
	v_add_f32_e32 v82, v95, v94
	v_add_f32_e32 v82, v96, v82
	v_add_f32_e32 v82, v97, v82
	v_add_f32_e32 v82, v98, v82
	v_add_f32_e32 v82, v99, v82
	v_add_f32_e32 v82, v100, v82
	v_add_f32_e32 v82, v101, v82
	s_waitcnt lgkmcnt(0)
	v_mfma_f32_32x32x16_bf16 v[50:65], v[90:93], v[86:89], v[50:65]
	v_add_f32_e32 v82, v102, v82

; #define LAS __attribute__((address_space(3)))
; __device__ __forceinline__ float max3f(float a, float b, float c) { float r; asm("v_max3_f32 %0, %1, %2, %3" : "=v"(r) : "v"(a), "v"(b), "v"(c)); return r; }
; template <int DQK, int DV, bool BIAS> ...
;     ...
;         const LAS unsigned char* kb = lds + buf * KBUF + r32 * KP + hi * 16;
; #pragma unroll
;         for (int ks = 0; ks < NKS; ++ks) {
;             const bf16x8 k0 = *(const LAS bf16x8*)(kb + ks * 32), k1 = *(const LAS bf16x8*)(kb + 32 * KP + ks * 32);
;             if (ks == 0) { p0 = __builtin_amdgcn_mfma_f32_32x32x16_bf16(k0, qf[0], negm, 0, 0, 0); p1 = __builtin_amdgcn_mfma_f32_32x32x16_bf16(k1, qf[0], negm, 0, 0, 0); }
;             else { p0 = __builtin_amdgcn_mfma_f32_32x32x16_bf16(k0, qf[ks], p0, 0, 0, 0); p1 = __builtin_amdgcn_mfma_f32_32x32x16_bf16(k1, qf[ks], p1, 0, 0, 0); }
;         }
;         if (BIAS) {
;             asm volatile("s_nop 15\n\ts_nop 7" : "+v"(p0), "+v"(p1));
;             const float d0 = qp - (float)(t * 64 + 4 * hi);
; #pragma unroll
;             for (int r = 0; r < 16; ++r) { const float dk = d0 - (float)((r & 3) + 8 * (r >> 2)); p0[r] = p0[r] - sl2 * fabsf(dk); p1[r] = p1[r] - sl2 * fabsf(dk - 32.f); }
;         } else {
;             asm volatile("s_nop 15\n\ts_nop 7" : "+v"(p0), "+v"(p1));
;         }
;         float mxa = max3f(p0[0], p0[1], p1[0]), mxb = max3f(p0[2], p0[3], p1[1]); mxa = max3f(mxa, p1[2], p1[3]);
; #pragma unroll
;         for (int r = 4; r < 16; r += 4) { mxa = max3f(mxa, p0[r], p0[r + 1]); mxb = max3f(mxb, p0[r + 2], p0[r + 3]); mxa = max3f(mxa, p1[r], p1[r + 1]); mxb = max3f(mxb, p1[r + 2], p1[r + 3]); }
;         float mx = fmaxf(mxa, mxb);
.LBB0_596:
	ds_read_b128 v[196:199], v179 offset:9216
	ds_read_b128 v[200:203], v179 offset:9248
	v_add_f32_e32 v156, v157, v156
	v_add_f32_e32 v156, v160, v156
	s_waitcnt lgkmcnt(1)
	v_mfma_f32_32x32x16_bf16 v[98:113], v[196:199], v[114:117], v[66:81]
	ds_read_b128 v[196:199], v179 offset:13824
	ds_read_b128 v[204:207], v179 offset:13856
	v_add_f32_e32 v156, v161, v156
	v_add_f32_e32 v156, v164, v156
	v_add_f32_e32 v150, v150, v156
	v_add_f32_e32 v150, v165, v150
	v_add_f32_e32 v150, v166, v150
	v_add_f32_e32 v150, v167, v150
	s_waitcnt lgkmcnt(1)
	v_mfma_f32_32x32x16_bf16 v[82:97], v[196:199], v[114:117], v[66:81]
	v_add_f32_e32 v150, v181, v150
	v_add_f32_e32 v150, v182, v150
	v_add_f32_e32 v150, v158, v150
	v_add_f32_e32 v150, v159, v150
	ds_read_b128 v[164:167], v179 offset:9280
	v_add_f32_e32 v150, v162, v150
	v_add_f32_e32 v150, v163, v150
	v_mfma_f32_32x32x16_bf16 v[98:113], v[200:203], v[118:121], v[98:113]
	v_add_f32_e32 v150, v183, v150
	v_add_f32_e32 v150, v184, v150
	v_add_f32_e32 v150, v185, v150
	v_add_f32_e32 v150, v152, v150
	ds_read_b128 v[156:159], v179 offset:13888
	ds_read_b128 v[160:163], v179 offset:9312
	v_add_f32_e32 v150, v153, v150
	v_add_f32_e32 v150, v186, v150
	s_waitcnt lgkmcnt(3)
	v_mfma_f32_32x32x16_bf16 v[82:97], v[204:207], v[118:121], v[82:97]
	v_add_f32_e32 v150, v187, v150
	v_add_f32_e32 v150, v154, v150
	v_add_f32_e32 v150, v155, v150
	v_add_f32_e32 v150, v188, v150
	v_add_f32_e32 v150, v189, v150
	v_add_u32_e32 v152, 64, v177
	v_add_f32_e32 v150, v190, v150
	s_waitcnt lgkmcnt(2)
	v_mfma_f32_32x32x16_bf16 v[98:113], v[164:167], v[122:125], v[98:113]
	ds_read_b128 v[164:167], v179 offset:13920
	v_cvt_f32_u32_e32 v152, v152
	v_add_f32_e32 v150, v191, v150
	v_add_f32_e32 v150, v192, v150
	v_add_f32_e32 v150, v195, v150
	v_add_f32_e32 v150, v193, v150
	v_add_f32_e32 v150, v194, v150
	s_waitcnt lgkmcnt(2)
	v_mfma_f32_32x32x16_bf16 v[82:97], v[156:159], v[122:125], v[82:97]
	v_add_f32_e32 v158, v151, v150
	s_waitcnt lgkmcnt(1)
	v_mfma_f32_32x32x16_bf16 v[98:113], v[160:163], v[126:129], v[98:113]
	v_sub_f32_e32 v160, v176, v152
	v_add_f32_e32 v161, -1.0, v160
	v_and_b32_e32 v150, 0x7fffffff, v160
	v_and_b32_e32 v151, 0x7fffffff, v161
	s_waitcnt lgkmcnt(0)
	v_mfma_f32_32x32x16_bf16 v[82:97], v[164:167], v[126:129], v[82:97]
	s_nop 15
	s_nop 7
	s_nop 5
	v_pk_fma_f32 v[150:151], v[142:143], v[150:151], v[98:99] neg_lo:[1,0,0] neg_hi:[1,0,0]
	v_pk_add_f32 v[98:99], v[160:161], s[6:7] op_sel_hi:[1,0]
	s_nop 0
	v_fma_f32 v83, -v143, |v99|, v83
	v_fma_f32 v82, -v142, |v98|, v82
	s_nop 0
	v_pk_add_f32 v[98:99], v[160:161], s[8:9] op_sel_hi:[0,1]
	v_fma_f32 v153, -v143, |v99|, v101
	v_fma_f32 v152, -v142, |v98|, v100
	v_pk_add_f32 v[98:99], v[98:99], s[6:7] op_sel_hi:[1,0]
	v_fma_f32 v99, -v143, |v99|, v85
	v_fma_f32 v98, -v142, |v98|, v84
	v_pk_add_f32 v[84:85], v[160:161], s[10:11] op_sel_hi:[0,1]
	v_fma_f32 v155, -v143, |v85|, v103
	v_fma_f32 v154, -v142, |v84|, v102
	v_pk_add_f32 v[84:85], v[84:85], s[6:7] op_sel_hi:[1,0]
	v_fma_f32 v101, -v143, |v85|, v87
	v_fma_f32 v100, -v142, |v84|, v86
	v_pk_add_f32 v[84:85], v[160:161], s[22:23] op_sel_hi:[0,1]
	v_fma_f32 v157, -v143, |v85|, v105
	v_fma_f32 v156, -v142, |v84|, v104
	v_pk_add_f32 v[84:85], v[84:85], s[6:7] op_sel_hi:[1,0]
	v_fma_f32 v103, -v143, |v85|, v89
	v_fma_f32 v102, -v142, |v84|, v88
	v_pk_add_f32 v[84:85], v[160:161], s[34:35] op_sel_hi:[0,1]
	v_fma_f32 v105, -v143, |v85|, v107
	v_fma_f32 v104, -v142, |v84|, v106
	v_pk_add_f32 v[86:87], v[160:161], s[36:37] op_sel_hi:[0,1]
	v_pk_add_f32 v[84:85], v[84:85], s[6:7] op_sel_hi:[1,0]
	v_fma_f32 v107, -v143, |v87|, v109
	v_fma_f32 v106, -v142, |v86|, v108
	v_fma_f32 v85, -v143, |v85|, v91
	v_fma_f32 v84, -v142, |v84|, v90
	v_pk_add_f32 v[86:87], v[86:87], s[6:7] op_sel_hi:[1,0]
	v_pk_add_f32 v[88:89], v[160:161], s[38:39] op_sel_hi:[0,1]
	v_fma_f32 v87, -v143, |v87|, v93
	v_fma_f32 v86, -v142, |v86|, v92
	v_fma_f32 v93, -v143, |v89|, v111
	v_fma_f32 v92, -v142, |v88|, v110
	v_pk_add_f32 v[88:89], v[88:89], s[6:7] op_sel_hi:[1,0]
	v_fma_f32 v89, -v143, |v89|, v95
	v_fma_f32 v88, -v142, |v88|, v94
	v_pk_add_f32 v[90:91], v[160:161], s[40:41] op_sel_hi:[0,1]
	v_fma_f32 v95, -v143, |v91|, v113
	v_fma_f32 v94, -v142, |v90|, v112
	v_pk_add_f32 v[90:91], v[90:91], s[6:7] op_sel_hi:[1,0]
	v_fma_f32 v91, -v143, |v91|, v97
	v_fma_f32 v90, -v142, |v90|, v96
	v_max3_f32 v96, v150, v151, v82
	v_max3_f32 v97, v152, v153, v83
	v_max3_f32 v96, v96, v98, v99
	v_max3_f32 v97, v97, v156, v157
	v_max3_f32 v96, v96, v154, v155
	v_max3_f32 v97, v97, v102, v103
	v_max3_f32 v96, v96, v100, v101
	v_max3_f32 v97, v97, v106, v107
	v_max3_f32 v96, v96, v104, v105
	v_max3_f32 v97, v97, v86, v87
	v_max3_f32 v96, v96, v84, v85
	v_max3_f32 v97, v97, v94, v95
	v_max3_f32 v96, v96, v92, v93
	v_max3_f32 v97, v97, v90, v91
	v_max3_f32 v96, v96, v88, v89
	v_max_f32_e32 v96, v96, v97
	v_cmp_gt_f32_e32 vcc, 0xc3400000, v96
	s_cmp_eq_u64 vcc, exec
	s_cbranch_scc1 .Lsk2_p4a2
; template <int DQK, int DV, bool BIAS> ...
;     ...
;         if (__any(mx > 8.f)) {
;             mx = fmaxf(mx, __shfl_xor(mx, 32));
;             const float dl = fmaxf(mx, 0.f); mhat += dl;
;             const float f = __builtin_amdgcn_exp2f(-dl);
; #pragma unroll
;             for (int r = 0; r < 16; ++r) { p0[r] -= dl; p1[r] -= dl; negm[r] = -mhat; }
;             l *= f;
; #pragma unroll
;             for (int d = 0; d < NDT; ++d)
; #pragma unroll
;                 for (int r = 0; r < 16; ++r) o[d][r] *= f;
;         }
	v_cmp_lt_f32_e32 vcc, s44, v96
	s_cbranch_vccz .LBB0_587
	ds_bpermute_b32 v66, v168, v96
	s_waitcnt lgkmcnt(0)
	v_max3_f32 v67, v96, v66, 0
	v_exp_f32_e64 v68, -v67
	v_add_f32_e32 v180, v180, v67
	v_xor_b32_e32 v66, 0x80000000, v180
	v_sub_f32_e32 v82, v82, v67
	v_sub_f32_e32 v83, v83, v67
	v_sub_f32_e32 v98, v98, v67
	v_sub_f32_e32 v99, v99, v67
	v_sub_f32_e32 v100, v100, v67
	v_sub_f32_e32 v101, v101, v67
	v_sub_f32_e32 v102, v102, v67
	v_sub_f32_e32 v103, v103, v67
	v_sub_f32_e32 v84, v84, v67
	v_sub_f32_e32 v85, v85, v67
	v_sub_f32_e32 v86, v86, v67
	v_sub_f32_e32 v87, v87, v67
	v_sub_f32_e32 v88, v88, v67
	v_sub_f32_e32 v89, v89, v67
	v_sub_f32_e32 v90, v90, v67
	v_sub_f32_e32 v91, v91, v67
	v_pk_mul_f32 v[16:17], v[16:17], v[68:69] op_sel_hi:[1,0]
	v_pk_mul_f32 v[14:15], v[14:15], v[68:69] op_sel_hi:[1,0]
	v_pk_mul_f32 v[12:13], v[12:13], v[68:69] op_sel_hi:[1,0]
	v_pk_mul_f32 v[10:11], v[10:11], v[68:69] op_sel_hi:[1,0]
	v_pk_mul_f32 v[8:9], v[8:9], v[68:69] op_sel_hi:[1,0]
	v_pk_mul_f32 v[6:7], v[6:7], v[68:69] op_sel_hi:[1,0]
	v_pk_mul_f32 v[4:5], v[4:5], v[68:69] op_sel_hi:[1,0]
	v_pk_mul_f32 v[2:3], v[2:3], v[68:69] op_sel_hi:[1,0]
	v_pk_mul_f32 v[32:33], v[32:33], v[68:69] op_sel_hi:[1,0]
	v_pk_mul_f32 v[30:31], v[30:31], v[68:69] op_sel_hi:[1,0]
	v_pk_mul_f32 v[28:29], v[28:29], v[68:69] op_sel_hi:[1,0]
	v_pk_mul_f32 v[26:27], v[26:27], v[68:69] op_sel_hi:[1,0]
	v_pk_mul_f32 v[24:25], v[24:25], v[68:69] op_sel_hi:[1,0]
	v_pk_mul_f32 v[22:23], v[22:23], v[68:69] op_sel_hi:[1,0]
	v_pk_mul_f32 v[20:21], v[20:21], v[68:69] op_sel_hi:[1,0]
	v_pk_mul_f32 v[18:19], v[18:19], v[68:69] op_sel_hi:[1,0]
	v_pk_mul_f32 v[48:49], v[48:49], v[68:69] op_sel_hi:[1,0]
	v_pk_mul_f32 v[46:47], v[46:47], v[68:69] op_sel_hi:[1,0]
	v_pk_mul_f32 v[44:45], v[44:45], v[68:69] op_sel_hi:[1,0]
	v_pk_mul_f32 v[42:43], v[42:43], v[68:69] op_sel_hi:[1,0]
	v_pk_mul_f32 v[40:41], v[40:41], v[68:69] op_sel_hi:[1,0]
	v_pk_mul_f32 v[38:39], v[38:39], v[68:69] op_sel_hi:[1,0]
	v_pk_mul_f32 v[36:37], v[36:37], v[68:69] op_sel_hi:[1,0]
	v_pk_mul_f32 v[34:35], v[34:35], v[68:69] op_sel_hi:[1,0]
	v_pk_mul_f32 v[64:65], v[64:65], v[68:69] op_sel_hi:[1,0]
	v_pk_mul_f32 v[62:63], v[62:63], v[68:69] op_sel_hi:[1,0]
	v_pk_mul_f32 v[60:61], v[60:61], v[68:69] op_sel_hi:[1,0]
	v_pk_mul_f32 v[58:59], v[58:59], v[68:69] op_sel_hi:[1,0]
	v_pk_mul_f32 v[56:57], v[56:57], v[68:69] op_sel_hi:[1,0]
	v_pk_mul_f32 v[54:55], v[54:55], v[68:69] op_sel_hi:[1,0]
	v_pk_mul_f32 v[52:53], v[52:53], v[68:69] op_sel_hi:[1,0]
	v_pk_mul_f32 v[50:51], v[50:51], v[68:69] op_sel_hi:[1,0]
	v_sub_f32_e32 v150, v150, v67
	v_sub_f32_e32 v151, v151, v67
	v_sub_f32_e32 v152, v152, v67
	v_sub_f32_e32 v153, v153, v67
	v_sub_f32_e32 v154, v154, v67
	v_sub_f32_e32 v155, v155, v67
	v_sub_f32_e32 v156, v156, v67
	v_sub_f32_e32 v157, v157, v67
	v_sub_f32_e32 v104, v104, v67
	v_sub_f32_e32 v105, v105, v67
	v_sub_f32_e32 v106, v106, v67
	v_sub_f32_e32 v107, v107, v67
	v_sub_f32_e32 v92, v92, v67
	v_sub_f32_e32 v93, v93, v67
	v_sub_f32_e32 v94, v94, v67
	v_sub_f32_e32 v95, v95, v67
	v_mul_f32_e32 v158, v158, v68
	v_mov_b32_e32 v67, v66
	v_mov_b32_e32 v68, v66
	v_mov_b32_e32 v69, v66
	v_mov_b32_e32 v70, v66
	v_mov_b32_e32 v71, v66
	v_mov_b32_e32 v72, v66
	v_mov_b32_e32 v73, v66
	v_mov_b32_e32 v74, v66
	v_mov_b32_e32 v75, v66
	v_mov_b32_e32 v76, v66
	v_mov_b32_e32 v77, v66
	v_mov_b32_e32 v78, v66
	v_mov_b32_e32 v79, v66
	v_mov_b32_e32 v80, v66
	v_mov_b32_e32 v81, v66
	s_branch .LBB0_587

; template <int DQK, int DV, bool BIAS> ...
;     ...
;     bf16x8 qf[NKS];
; #pragma unroll
;     for (int ks = 0; ks < NKS; ++ks) qf[ks] = ks < 4 ? *(const bf16x8*)(Qw + (size_t)r32 * ldq + ks * 16 + hi * 8) : *(const bf16x8*)(Q2w + (size_t)r32 * ldq2 + (ks - 4) * 16 + hi * 8);
; #pragma unroll
;     for (int ks = 0; ks < 4; ++ks) qf[ks] = scale_frag(qf[ks], cs);
;     if constexpr (DQK == 96) {
;         const float* rp = ropetab + ((size_t)(qpos0 + r32) * 16) * 2;
; #pragma unroll
;         for (int ks = 4; ks < 6; ++ks) {
;             const f32x4 c0 = *(const f32x4*)(rp + ((ks - 4) * 8 + hi * 4) * 2), c1 = *(const f32x4*)(rp + ((ks - 4) * 8 + hi * 4 + 2) * 2);
;             const u32x4 w = __builtin_bit_cast(u32x4, qf[ks]); u32x4 ow;
;             { const float a = bflo(w.x) * cs, b = bfhi(w.x) * cs; ow.x = cvtpk(a * c0[0] - b * c0[1], a * c0[1] + b * c0[0]); }
;             { const float a = bflo(w.y) * cs, b = bfhi(w.y) * cs; ow.y = cvtpk(a * c0[2] - b * c0[3], a * c0[3] + b * c0[2]); }
;             { const float a = bflo(w.z) * cs, b = bfhi(w.z) * cs; ow.z = cvtpk(a * c1[0] - b * c1[1], a * c1[1] + b * c1[0]); }
;             { const float a = bflo(w.w) * cs, b = bfhi(w.w) * cs; ow.w = cvtpk(a * c1[2] - b * c1[3], a * c1[3] + b * c1[2]); }
;             qf[ks] = __builtin_bit_cast(bf16x8, ow);
;         }
;     }
; #pragma unroll
;     for (int d = 0; d < NDT; ++d)
; #pragma unroll
;         for (int r = 0; r < 16; ++r) o[d][r] = 0.f;
; #pragma unroll
;     for (int ks = 0; ks < NKS; ++ks) asm volatile("" : "+v"(qf[ks]));
;     float mhat = 0.f, l = 0.f; f32x16 negm;
; #pragma unroll
;     for (int r = 0; r < 16; ++r) negm[r] = 0.f;
;     constexpr int TPB = (DV == 64) ? 2 : 1, NG = SEQL / 64 / TPB;
;     u32x4 kreg[TPB], k2reg[TPB], vreg[TPB][NVL];
;     const bf16_t* kptr = Kg + (size_t)(tid >> 3) * ldk + (tid & 7) * 8;
;     const bf16_t* k2ptr = (DQK == 96) ? K2g + (size_t)(tid >> 2) * ldk2 + (tid & 3) * 8 : nullptr;
;     ...
;     u32x4 pw[4];
; #pragma unroll
;     for (int j = 0; j < TPB; ++j) { ATT_LOAD(j, j); ATT_STORE(j, j); }
; #pragma unroll
;     for (int j = 0; j < TPB; ++j) ATT_LOAD(TPB + j, j);
;     const float qp = (float)(qpos0 + r32);
.LBB0_600:
	s_xor_b64 s[8:9], s[10:11], -1
	s_add_i32 s10, s20, s33
	s_ashr_i32 s18, s10, 7
	s_ashr_i32 s19, s18, 31
	s_lshl_b64 s[10:11], s[18:19], 12
	s_add_u32 s10, s10, s27
	s_addc_u32 s11, s11, s48
	s_mulk_i32 s11, 0x1940
	s_mul_hi_u32 s19, s10, 0x1940
	v_mov_b32_e32 v34, v1
	s_add_i32 s19, s19, s11
	s_mulk_i32 s10, 0x1940
	s_add_u32 s10, s35, s10
	v_and_b32_e32 v35, 31, v34
	v_mul_u32_u24_e32 v2, 0xca0, v35
	s_addc_u32 s11, s36, s19
	v_bfe_u32 v36, v34, 5, 1
	v_lshlrev_b32_e32 v130, 1, v2
	v_lshl_add_u64 v[2:3], s[10:11], 0, v[130:131]
	v_lshlrev_b32_e32 v130, 4, v36
	v_lshl_add_u64 v[18:19], v[2:3], 0, v[130:131]
	global_load_dwordx4 v[2:5], v[18:19], off offset:3072
	global_load_dwordx4 v[6:9], v[18:19], off offset:3104
	global_load_dwordx4 v[10:13], v[18:19], off offset:3136
	global_load_dwordx4 v[14:17], v[18:19], off offset:3168
	s_mul_i32 s20, s18, 0x1940000
	s_mul_hi_i32 s19, s18, 0x1940000
	s_add_u32 s20, s16, s20
	s_addc_u32 s19, s17, s19
	s_add_u32 s20, s20, s38
	s_addc_u32 s21, s19, 0
	s_add_u32 s22, s20, 0x1000
	s_addc_u32 s23, s21, 0
	v_lshlrev_b32_e32 v36, 8, v36
	v_mad_u32_u24 v35, v35, s39, 0
	v_add_u32_e32 v130, v35, v130
	v_mov_b32_e32 v144, 0
	v_mov_b32_e32 v143, 0
	v_mov_b32_e32 v50, 0
	v_mov_b32_e32 v51, v131
	v_mov_b32_e32 v52, v131
	v_mov_b32_e32 v53, v131
	v_mov_b32_e32 v54, v131
	v_mov_b32_e32 v55, v131
	v_mov_b32_e32 v56, v131
	v_mov_b32_e32 v57, v131
	v_mov_b32_e32 v58, v131
	v_mov_b32_e32 v59, v131
	v_mov_b32_e32 v60, v131
	v_mov_b32_e32 v61, v131
	v_mov_b32_e32 v62, v131
	v_mov_b32_e32 v63, v131
	v_mov_b32_e32 v64, v131
	v_mov_b32_e32 v65, v131
	s_waitcnt vmcnt(3)
	v_lshlrev_b32_e32 v18, 16, v2
	v_and_b32_e32 v19, 0xffff0000, v2
	v_lshlrev_b32_e32 v2, 16, v3
	v_and_b32_e32 v3, 0xffff0000, v3
	s_waitcnt vmcnt(0)
	v_lshlrev_b32_e32 v30, 16, v14
	v_and_b32_e32 v31, 0xffff0000, v14
	v_lshlrev_b32_e32 v32, 16, v16
	v_and_b32_e32 v33, 0xffff0000, v16
	v_lshlrev_b32_e32 v16, 16, v17
	v_pk_mul_f32 v[2:3], v[2:3], s[6:7] op_sel_hi:[1,0]
	v_and_b32_e32 v17, 0xffff0000, v17
	v_pk_mul_f32 v[30:31], v[30:31], s[6:7] op_sel_hi:[1,0]
	v_pk_mul_f32 v[32:33], v[32:33], s[6:7] op_sel_hi:[1,0]
	v_cvt_pk_bf16_f32 v99, v2, v3
	v_pk_mul_f32 v[2:3], v[16:17], s[6:7] op_sel_hi:[1,0]
	v_lshlrev_b32_e32 v20, 16, v4
	v_and_b32_e32 v21, 0xffff0000, v4
	v_pk_mul_f32 v[18:19], v[18:19], s[6:7] op_sel_hi:[1,0]
	v_cvt_pk_bf16_f32 v110, v30, v31
	v_cvt_pk_bf16_f32 v112, v32, v33
	v_cvt_pk_bf16_f32 v113, v2, v3
	v_ashrrev_i32_e32 v30, 3, v34
	v_mov_b64_e32 v[2:3], s[22:23]
	v_lshlrev_b32_e32 v32, 4, v34
	v_lshlrev_b32_e32 v4, 16, v5
	v_and_b32_e32 v5, 0xffff0000, v5
	v_pk_mul_f32 v[20:21], v[20:21], s[6:7] op_sel_hi:[1,0]
	v_cvt_pk_bf16_f32 v98, v18, v19
	v_mad_i64_i32 v[2:3], s[22:23], v30, s37, v[2:3]
	v_and_b32_e32 v18, 0x70, v32
	v_mov_b32_e32 v19, v131
	v_lshlrev_b32_e32 v22, 16, v6
	v_and_b32_e32 v23, 0xffff0000, v6
	v_pk_mul_f32 v[4:5], v[4:5], s[6:7] op_sel_hi:[1,0]
	v_cvt_pk_bf16_f32 v100, v20, v21
	v_lshl_add_u64 v[20:21], v[2:3], 0, v[18:19]
	v_and_b32_e32 v2, 0xffffffe0, v30
	v_pk_mul_f32 v[22:23], v[22:23], s[6:7] op_sel_hi:[1,0]
	v_cvt_pk_bf16_f32 v101, v4, v5
	v_ashrrev_i32_e32 v3, 31, v2
	v_lshlrev_b32_e32 v4, 3, v34
	v_cvt_pk_bf16_f32 v102, v22, v23
	v_lshlrev_b64 v[22:23], 1, v[2:3]
	v_and_b32_e32 v37, 24, v4
	v_bfe_u32 v33, v34, 2, 6
	v_lshl_add_u64 v[2:3], s[20:21], 0, v[22:23]
	v_lshlrev_b32_e32 v4, 1, v37
	v_mov_b32_e32 v5, v131
	v_lshlrev_b32_e32 v24, 16, v8
	v_and_b32_e32 v25, 0xffff0000, v8
	v_lshl_add_u64 v[2:3], v[2:3], 0, v[4:5]
	v_mul_u32_u24_e32 v4, 0xca0, v33
	v_lshlrev_b32_e32 v26, 16, v10
	v_and_b32_e32 v27, 0xffff0000, v10
	v_lshlrev_b32_e32 v10, 16, v11
	v_and_b32_e32 v11, 0xffff0000, v11
	v_pk_mul_f32 v[24:25], v[24:25], s[6:7] op_sel_hi:[1,0]
	v_lshlrev_b32_e32 v4, 1, v4
	v_pk_mul_f32 v[10:11], v[10:11], s[6:7] op_sel_hi:[1,0]
	v_cvt_pk_bf16_f32 v104, v24, v25
	v_lshl_add_u64 v[24:25], v[2:3], 0, v[4:5]
	v_cvt_pk_bf16_f32 v107, v10, v11
	v_add_co_u32_e32 v10, vcc, s40, v24
	v_pk_mul_f32 v[26:27], v[26:27], s[6:7] op_sel_hi:[1,0]
	s_nop 0
	v_addc_co_u32_e32 v11, vcc, 0, v25, vcc
	v_lshlrev_b32_e32 v28, 16, v12
	v_and_b32_e32 v29, 0xffff0000, v12
	v_cvt_pk_bf16_f32 v106, v26, v27
	v_add_co_u32_e32 v26, vcc, s41, v20
	v_lshlrev_b32_e32 v6, 16, v7
	v_and_b32_e32 v7, 0xffff0000, v7
	v_lshlrev_b32_e32 v8, 16, v9
	v_and_b32_e32 v9, 0xffff0000, v9
	v_lshlrev_b32_e32 v12, 16, v13
	v_and_b32_e32 v13, 0xffff0000, v13
	v_lshlrev_b32_e32 v14, 16, v15
	v_and_b32_e32 v15, 0xffff0000, v15
	v_pk_mul_f32 v[28:29], v[28:29], s[6:7] op_sel_hi:[1,0]
	v_addc_co_u32_e32 v27, vcc, 0, v21, vcc
	v_pk_mul_f32 v[6:7], v[6:7], s[6:7] op_sel_hi:[1,0]
	v_pk_mul_f32 v[8:9], v[8:9], s[6:7] op_sel_hi:[1,0]
	v_pk_mul_f32 v[12:13], v[12:13], s[6:7] op_sel_hi:[1,0]
	v_pk_mul_f32 v[14:15], v[14:15], s[6:7] op_sel_hi:[1,0]
	v_cvt_pk_bf16_f32 v108, v28, v29
	v_add_co_u32_e32 v28, vcc, s42, v24
	v_cvt_pk_bf16_f32 v103, v6, v7
	v_cvt_pk_bf16_f32 v105, v8, v9
	v_cvt_pk_bf16_f32 v109, v12, v13
	v_cvt_pk_bf16_f32 v111, v14, v15
	v_addc_co_u32_e32 v29, vcc, 0, v25, vcc
	global_load_dwordx4 v[2:5], v[20:21], off
	global_load_dwordx4 v[6:9], v[10:11], off offset:256
	s_nop 0
	global_load_dwordx4 v[10:13], v[26:27], off
	global_load_dwordx4 v[14:17], v[28:29], off offset:256
	v_add_co_u32_e32 v28, vcc, s44, v24
	v_mad_i64_i32 v[26:27], s[20:21], v30, s37, 0
	s_nop 0
	v_addc_co_u32_e32 v29, vcc, 0, v25, vcc
	v_add_co_u32_e32 v24, vcc, s46, v24
	v_mul_lo_u32 v38, v30, s39
	s_nop 0
	v_addc_co_u32_e32 v25, vcc, 0, v25, vcc
	v_add_co_u32_e32 v30, vcc, s43, v20
	v_and_b32_e32 v39, 0xfffff000, v32
	s_nop 0
	v_addc_co_u32_e32 v31, vcc, 0, v21, vcc
	v_add_co_u32_e32 v20, vcc, s45, v20
	v_and_b32_e32 v40, 0xfc0, v32
	s_nop 0
	v_addc_co_u32_e32 v21, vcc, 0, v21, vcc
	global_load_dwordx4 v[114:117], v[30:31], off
	global_load_dwordx4 v[118:121], v[28:29], off offset:256
	global_load_dwordx4 v[122:125], v[20:21], off
	global_load_dwordx4 v[126:129], v[24:25], off offset:256
	v_add_u32_e32 v20, 0, v38
	v_and_b32_e32 v41, 48, v32
	v_add3_u32 v21, 0, v39, v40
	v_add_u32_e32 v133, v20, v18
	v_add_u32_e32 v140, v21, v41
	s_waitcnt vmcnt(7)
; #define LAS __attribute__((address_space(3)))
; __device__ __forceinline__ unsigned cvtpk(float lo, float hi) { typedef __bf16 bf2 __attribute__((ext_vector_type(2))); f32x2 v = {lo, hi}; bf2 b = __builtin_convertvector(v, bf2); return __builtin_bit_cast(unsigned, b); }
; template <int DQK, int DV, bool BIAS> ...
;     ...
;     for (int j = 0; j < TPB; ++j) { ATT_LOAD(j, j); ATT_STORE(j, j); }
; #pragma unroll
;     for (int j = 0; j < TPB; ++j) ATT_LOAD(TPB + j, j);
;     const float qp = (float)(qpos0 + r32);
; #pragma unroll 2
;     for (int g = 0; g < NG; ++g) {
;         const int pair = g & 1;
;         __syncthreads();
;         if (g + 1 < NG) {
; #pragma unroll
;             for (int j = 0; j < TPB; ++j) ATT_STORE((pair ^ 1) * TPB + j, j);
;             if (g + 2 < NG) {
; #pragma unroll
;                 for (int j = 0; j < TPB; ++j) ATT_LOAD((g + 2) * TPB + j, j);
;             }
;         }
;     ...
;             float ls = 0.f;
; #pragma unroll
;             for (int hs = 0; hs < 4; ++hs) {
;                 float e[8];
; #pragma unroll
;                 for (int j = 0; j < 8; ++j) { e[j] = __builtin_amdgcn_exp2f(hs < 2 ? p0[8 * (hs & 1) + j] : p1[8 * (hs & 1) + j]); ls += e[j]; }
;                 pw[hs].x = cvtpk(e[0], e[1]); pw[hs].y = cvtpk(e[2], e[3]); pw[hs].z = cvtpk(e[4], e[5]); pw[hs].w = cvtpk(e[6], e[7]);
;                 const bf16x8 pbv = __builtin_bit_cast(bf16x8, pw[hs]);
; #pragma unroll
;                 for (int d = 0; d < NDT; ++d) { const LAS unsigned char* vp = vbase + d * 4096 + hs * 1024;
;                     const v4i16_t a0 = __builtin_amdgcn_ds_read_tr16_b64_v4i16((LAS v4i16_t*)vp), a1 = __builtin_amdgcn_ds_read_tr16_b64_v4i16((LAS v4i16_t*)(vp + 512));
;                     const bf16x8 av = {a0[0], a0[1], a0[2], a0[3], a1[0], a1[1], a1[2], a1[3]};
;                     o[d] = __builtin_amdgcn_mfma_f32_32x32x16_bf16(av, pbv, o[d], 0, 0, 0); }
;                 __builtin_amdgcn_sched_barrier(0);
;             }
;             l += ls;
	ds_write_b128 v133, v[2:5]
	s_waitcnt vmcnt(6)
	ds_write_b128 v140, v[6:9] offset:36864
	s_waitcnt vmcnt(5)
	ds_write_b128 v133, v[10:13] offset:9216
	s_waitcnt vmcnt(4)
	ds_write_b128 v140, v[14:17] offset:45056
	v_and_b32_e32 v2, 0xc0, v32
	v_lshlrev_b32_e32 v3, 1, v34
	v_add3_u32 v2, 0, v36, v2
	v_and_b32_e32 v3, 32, v3
	v_add3_u32 v141, v2, v3, v37
	v_mul_hi_u32_u24_e32 v3, 0x1940, v33
	v_mul_u32_u24_e32 v2, 0x1940, v33
	v_mad_i64_i32 v[2:3], s[20:21], s18, v139, v[2:3]
	v_and_b32_e32 v4, 3, v34
	v_lshl_or_b32 v2, v4, 4, v2
	v_lshl_add_u64 v[2:3], v[2:3], 0, v[22:23]
	v_mov_b32_e32 v224, v2
	v_lshl_add_u64 v[134:135], s[4:5], 0, v[2:3]
	v_mad_i64_i32 v[2:3], s[18:19], s18, v139, v[26:27]
	v_lshl_add_u64 v[2:3], v[2:3], 0, v[18:19]
	v_add_u32_e32 v142, 0x9000, v141
	v_mov_b32_e32 v225, v2
	v_lshl_add_u64 v[136:137], s[4:5], 0, v[2:3]
	v_mov_b32_e32 v18, v131
	v_mov_b32_e32 v20, v131
	v_mov_b32_e32 v21, v131
	v_mov_b32_e32 v22, v131
	v_mov_b32_e32 v23, v131
	v_mov_b32_e32 v24, v131
	v_mov_b32_e32 v25, v131
	v_mov_b32_e32 v26, v131
	v_mov_b32_e32 v27, v131
	v_mov_b32_e32 v28, v131
	v_mov_b32_e32 v29, v131
	v_mov_b32_e32 v30, v131
	v_mov_b32_e32 v31, v131
	v_mov_b32_e32 v32, v131
	v_mov_b32_e32 v33, v131
	v_mov_b32_e32 v2, v131
	v_mov_b32_e32 v3, v131
	v_mov_b32_e32 v4, v131
	v_mov_b32_e32 v5, v131
	v_mov_b32_e32 v6, v131
	v_mov_b32_e32 v7, v131
	v_mov_b32_e32 v8, v131
	v_mov_b32_e32 v9, v131
	v_mov_b32_e32 v10, v131
	v_mov_b32_e32 v11, v131
	v_mov_b32_e32 v12, v131
	v_mov_b32_e32 v13, v131
	v_mov_b32_e32 v14, v131
	v_mov_b32_e32 v15, v131
	v_mov_b32_e32 v16, v131
	v_mov_b32_e32 v17, v131
	s_mov_b64 s[18:19], 0
	s_mov_b32 s22, 0
	s_branch .LBB0_602
.LBB0_601:
	s_nop 4
	v_exp_f32_e32 v83, v66
	v_exp_f32_e32 v88, v67
	v_exp_f32_e32 v89, v68
	v_exp_f32_e32 v90, v69
	v_exp_f32_e32 v91, v70
	v_exp_f32_e32 v92, v71
	ds_read_b64_tr_b16 v[66:67], v141 offset:61440
	ds_read_b64_tr_b16 v[68:69], v141 offset:61952
	v_exp_f32_e32 v93, v72
	v_exp_f32_e32 v94, v73
	ds_read_b64_tr_b16 v[84:85], v142 offset:28672
	ds_read_b64_tr_b16 v[86:87], v142 offset:29184
	v_cvt_pk_bf16_f32 v70, v83, v88
	v_cvt_pk_bf16_f32 v71, v89, v90
	v_cvt_pk_bf16_f32 v72, v91, v92
	v_cvt_pk_bf16_f32 v73, v93, v94
	s_waitcnt lgkmcnt(2)
	s_nop 0
	v_mfma_f32_32x32x16_bf16 v[18:33], v[66:69], v[70:73], v[18:33]
	v_add_f32_e32 v66, v88, v83
	v_add_f32_e32 v66, v89, v66
	v_add_f32_e32 v66, v90, v66
	v_add_f32_e32 v66, v91, v66
	v_add_f32_e32 v66, v92, v66
	v_add_f32_e32 v66, v93, v66
	s_waitcnt lgkmcnt(0)
	v_mfma_f32_32x32x16_bf16 v[2:17], v[84:87], v[70:73], v[2:17]
	v_add_f32_e32 v83, v94, v66
	v_exp_f32_e32 v84, v74
	v_exp_f32_e32 v85, v75
	v_exp_f32_e32 v86, v76
	v_exp_f32_e32 v87, v77
	v_exp_f32_e32 v78, v78
	v_exp_f32_e32 v79, v79
	ds_read_b64_tr_b16 v[66:67], v141 offset:62464
	ds_read_b64_tr_b16 v[68:69], v141 offset:62976
	v_exp_f32_e32 v80, v80
	v_exp_f32_e32 v81, v81
	ds_read_b64_tr_b16 v[74:75], v142 offset:29696
	ds_read_b64_tr_b16 v[76:77], v142 offset:30208
	v_cvt_pk_bf16_f32 v70, v84, v85
	v_cvt_pk_bf16_f32 v71, v86, v87
	v_cvt_pk_bf16_f32 v72, v78, v79
	v_cvt_pk_bf16_f32 v73, v80, v81
	s_waitcnt lgkmcnt(2)
	s_nop 0
	v_mfma_f32_32x32x16_bf16 v[18:33], v[66:69], v[70:73], v[18:33]
	v_add_f32_e32 v66, v84, v83
	v_add_f32_e32 v66, v85, v66
	v_add_f32_e32 v66, v86, v66
	v_add_f32_e32 v66, v87, v66
	v_add_f32_e32 v66, v78, v66
	v_add_f32_e32 v66, v79, v66
	v_add_f32_e32 v66, v80, v66
	s_waitcnt lgkmcnt(0)
	v_mfma_f32_32x32x16_bf16 v[2:17], v[74:77], v[70:73], v[2:17]
	v_add_f32_e32 v70, v81, v66
	v_exp_f32_e32 v71, v34
	v_exp_f32_e32 v72, v35
	v_exp_f32_e32 v73, v36
	v_exp_f32_e32 v74, v37
	v_exp_f32_e32 v75, v38
	v_exp_f32_e32 v76, v39
	ds_read_b64_tr_b16 v[34:35], v141 offset:63488
	ds_read_b64_tr_b16 v[36:37], v141 offset:64000
	v_exp_f32_e32 v77, v40
	v_exp_f32_e32 v78, v41
	ds_read_b64_tr_b16 v[66:67], v142 offset:30720
	ds_read_b64_tr_b16 v[68:69], v142 offset:31232
	v_cvt_pk_bf16_f32 v38, v71, v72
	v_cvt_pk_bf16_f32 v39, v73, v74
	v_cvt_pk_bf16_f32 v40, v75, v76
	v_cvt_pk_bf16_f32 v41, v77, v78
	s_waitcnt lgkmcnt(2)
	s_nop 0
	v_mfma_f32_32x32x16_bf16 v[18:33], v[34:37], v[38:41], v[18:33]
	v_add_f32_e32 v34, v71, v70
	v_add_f32_e32 v34, v72, v34
	v_add_f32_e32 v34, v73, v34
	v_add_f32_e32 v34, v74, v34
	v_add_f32_e32 v34, v75, v34
	v_add_f32_e32 v34, v76, v34
	v_add_f32_e32 v34, v77, v34
	s_waitcnt lgkmcnt(0)
	v_mfma_f32_32x32x16_bf16 v[2:17], v[66:69], v[38:41], v[2:17]
	v_add_f32_e32 v66, v78, v34
	v_exp_f32_e32 v67, v42
	v_exp_f32_e32 v68, v43
	v_exp_f32_e32 v69, v44
	v_exp_f32_e32 v70, v45
	v_exp_f32_e32 v46, v46
	v_exp_f32_e32 v47, v47
	ds_read_b64_tr_b16 v[34:35], v141 offset:64512
	ds_read_b64_tr_b16 v[36:37], v141 offset:65024
	v_exp_f32_e32 v48, v48
	v_exp_f32_e32 v49, v49
	ds_read_b64_tr_b16 v[42:43], v142 offset:31744
	ds_read_b64_tr_b16 v[44:45], v142 offset:32256
	v_cvt_pk_bf16_f32 v38, v67, v68
	v_cvt_pk_bf16_f32 v39, v69, v70
	v_cvt_pk_bf16_f32 v40, v46, v47
	v_cvt_pk_bf16_f32 v41, v48, v49
	s_waitcnt lgkmcnt(2)
	s_nop 0
	v_mfma_f32_32x32x16_bf16 v[18:33], v[34:37], v[38:41], v[18:33]
	v_add_f32_e32 v34, v67, v66
	v_add_f32_e32 v34, v68, v34
	v_add_f32_e32 v34, v69, v34
	v_add_f32_e32 v34, v70, v34
	v_add_f32_e32 v34, v46, v34
	v_add_f32_e32 v34, v47, v34
	v_add_f32_e32 v34, v48, v34
	s_waitcnt lgkmcnt(0)
	v_mfma_f32_32x32x16_bf16 v[2:17], v[42:45], v[38:41], v[2:17]
	v_add_f32_e32 v34, v49, v34
	s_add_u32 s18, s18, 0x194000
	s_addc_u32 s19, s19, 0
	s_add_i32 s22, s22, 2
	s_cmp_lg_u32 s18, 0x1940000
	v_add_f32_e32 v144, v82, v34
	s_cbranch_scc0 .LBB0_599
.LBB0_602:
	s_cmp_lt_u32 s22, 30
	s_cselect_b64 s[20:21], -1, 0
	s_cmp_gt_u32 s22, 29
	s_waitcnt lgkmcnt(0)
	s_barrier
	s_waitcnt vmcnt(3)
	ds_write_b128 v133, v[114:117] offset:18432
	s_waitcnt vmcnt(2)
	ds_write_b128 v140, v[118:121] offset:53248
	s_waitcnt vmcnt(1)
	ds_write_b128 v133, v[122:125] offset:27648
	s_waitcnt vmcnt(0)
	ds_write_b128 v140, v[126:129] offset:61440
	s_cbranch_scc1 .LBB0_604
	s_add_u32 s100, s4, s18
	s_addc_u32 s101, s5, s19
	s_add_u32 s100, s100, 0x195000
	s_addc_u32 s101, s101, 0
	global_load_dwordx4 v[114:117], v225, s[100:101]
	global_load_dwordx4 v[118:121], v224, s[100:101] offset:256
	s_add_u32 s100, s100, 0x65000
	s_addc_u32 s101, s101, 0
	global_load_dwordx4 v[122:125], v225, s[100:101]
	global_load_dwordx4 v[126:129], v224, s[100:101] offset:256

; #define LAS __attribute__((address_space(3)))
; template <int DQK, int DV, bool BIAS> ...
;     ...
;         const LAS unsigned char* kb = lds + buf * KBUF + r32 * KP + hi * 16;
; #pragma unroll
;         for (int ks = 0; ks < NKS; ++ks) {
;             const bf16x8 k0 = *(const LAS bf16x8*)(kb + ks * 32), k1 = *(const LAS bf16x8*)(kb + 32 * KP + ks * 32);
;             if (ks == 0) { p0 = __builtin_amdgcn_mfma_f32_32x32x16_bf16(k0, qf[0], negm, 0, 0, 0); p1 = __builtin_amdgcn_mfma_f32_32x32x16_bf16(k1, qf[0], negm, 0, 0, 0); }
;             else { p0 = __builtin_amdgcn_mfma_f32_32x32x16_bf16(k0, qf[ks], p0, 0, 0, 0); p1 = __builtin_amdgcn_mfma_f32_32x32x16_bf16(k1, qf[ks], p1, 0, 0, 0); }
;         }
;         if (BIAS) {
;             asm volatile("s_nop 15\n\ts_nop 7" : "+v"(p0), "+v"(p1));
;             const float d0 = qp - (float)(t * 64 + 4 * hi);
; #pragma unroll
;             for (int r = 0; r < 16; ++r) { const float dk = d0 - (float)((r & 3) + 8 * (r >> 2)); p0[r] = p0[r] - sl2 * fabsf(dk); p1[r] = p1[r] - sl2 * fabsf(dk - 32.f); }
;         } else {
;             asm volatile("s_nop 15\n\ts_nop 7" : "+v"(p0), "+v"(p1));
;         }
;         float mxa = max3f(p0[0], p0[1], p1[0]), mxb = max3f(p0[2], p0[3], p1[1]); mxa = max3f(mxa, p1[2], p1[3]);
; #pragma unroll
;         for (int r = 4; r < 16; r += 4) { mxa = max3f(mxa, p0[r], p0[r + 1]); mxb = max3f(mxb, p0[r + 2], p0[r + 3]); mxa = max3f(mxa, p1[r], p1[r + 1]); mxb = max3f(mxb, p1[r + 2], p1[r + 3]); }
;         float mx = fmaxf(mxa, mxb);
;         if (__any(mx > 8.f)) {
;             mx = fmaxf(mx, __shfl_xor(mx, 32));
;             const float dl = fmaxf(mx, 0.f); mhat += dl;
;             const float f = __builtin_amdgcn_exp2f(-dl);
; #pragma unroll
;             for (int r = 0; r < 16; ++r) { p0[r] -= dl; p1[r] -= dl; negm[r] = -mhat; }
;             l *= f;
; #pragma unroll
;             for (int d = 0; d < NDT; ++d)
; #pragma unroll
;                 for (int r = 0; r < 16; ++r) o[d][r] *= f;
;         }
;         if (!isY) {
;             const LAS unsigned char* vbase = lds + VOFF + vcur * VBUF + (4 * hi + ((lane & 15) >> 2)) * 64 + ((lane >> 4) & 1) * 32 + (lane & 3) * 8;
;             float ls = 0.f;
; #pragma unroll
;             for (int hs = 0; hs < 4; ++hs) {
;                 float e[8];
; #pragma unroll
.LBB0_607:
	v_exp_f32_e32 v145, v82
	v_exp_f32_e32 v147, v83
	v_exp_f32_e32 v152, v84
	v_exp_f32_e32 v153, v85
	v_exp_f32_e32 v154, v86
	v_exp_f32_e32 v155, v87
	ds_read_b64_tr_b16 v[82:83], v141 offset:36864
	ds_read_b64_tr_b16 v[84:85], v141 offset:37376
	v_exp_f32_e32 v156, v88
	v_exp_f32_e32 v157, v89
	ds_read_b64_tr_b16 v[148:149], v141 offset:40960
	ds_read_b64_tr_b16 v[150:151], v141 offset:41472
	v_cvt_pk_bf16_f32 v86, v145, v147
	v_cvt_pk_bf16_f32 v87, v152, v153
	v_cvt_pk_bf16_f32 v88, v154, v155
	v_cvt_pk_bf16_f32 v89, v156, v157
	s_waitcnt lgkmcnt(2)
	s_nop 0
	v_mfma_f32_32x32x16_bf16 v[18:33], v[82:85], v[86:89], v[18:33]
	v_add_f32_e32 v82, v147, v145
	v_add_f32_e32 v82, v152, v82
	v_add_f32_e32 v82, v153, v82
	v_add_f32_e32 v82, v154, v82
	v_add_f32_e32 v82, v155, v82
	v_add_f32_e32 v82, v156, v82
	s_waitcnt lgkmcnt(0)
	v_mfma_f32_32x32x16_bf16 v[2:17], v[148:151], v[86:89], v[2:17]
	v_add_f32_e32 v145, v157, v82
	v_exp_f32_e32 v147, v90
	v_exp_f32_e32 v148, v91
	v_exp_f32_e32 v149, v92
	v_exp_f32_e32 v150, v93
	v_exp_f32_e32 v94, v94
	v_exp_f32_e32 v95, v95
	ds_read_b64_tr_b16 v[82:83], v141 offset:37888
	ds_read_b64_tr_b16 v[84:85], v141 offset:38400
	v_exp_f32_e32 v96, v96
	v_exp_f32_e32 v97, v97
	ds_read_b64_tr_b16 v[90:91], v141 offset:41984
	ds_read_b64_tr_b16 v[92:93], v141 offset:42496
	v_cvt_pk_bf16_f32 v86, v147, v148
	v_cvt_pk_bf16_f32 v87, v149, v150
	v_cvt_pk_bf16_f32 v88, v94, v95
	v_cvt_pk_bf16_f32 v89, v96, v97
	s_waitcnt lgkmcnt(2)
	s_nop 0
	v_mfma_f32_32x32x16_bf16 v[18:33], v[82:85], v[86:89], v[18:33]
	v_add_f32_e32 v82, v147, v145
	v_add_f32_e32 v82, v148, v82
	v_add_f32_e32 v82, v149, v82
	v_add_f32_e32 v82, v150, v82
	v_add_f32_e32 v82, v94, v82
	v_add_f32_e32 v82, v95, v82
	v_add_f32_e32 v82, v96, v82
	s_waitcnt lgkmcnt(0)
	v_mfma_f32_32x32x16_bf16 v[2:17], v[90:93], v[86:89], v[2:17]
	v_add_f32_e32 v86, v97, v82
	v_exp_f32_e32 v87, v66
	v_exp_f32_e32 v88, v67
	v_exp_f32_e32 v89, v68
	v_exp_f32_e32 v90, v69
	v_exp_f32_e32 v91, v70
	v_exp_f32_e32 v92, v71
	ds_read_b64_tr_b16 v[66:67], v141 offset:38912
	ds_read_b64_tr_b16 v[68:69], v141 offset:39424
	v_exp_f32_e32 v93, v72
	v_exp_f32_e32 v94, v73
	ds_read_b64_tr_b16 v[82:83], v141 offset:43008
	ds_read_b64_tr_b16 v[84:85], v141 offset:43520
	v_cvt_pk_bf16_f32 v70, v87, v88
	v_cvt_pk_bf16_f32 v71, v89, v90
	v_cvt_pk_bf16_f32 v72, v91, v92
	v_cvt_pk_bf16_f32 v73, v93, v94
	s_waitcnt lgkmcnt(2)
	s_nop 0
	v_mfma_f32_32x32x16_bf16 v[18:33], v[66:69], v[70:73], v[18:33]
	v_add_f32_e32 v66, v87, v86
	v_add_f32_e32 v66, v88, v66
	v_add_f32_e32 v66, v89, v66
	v_add_f32_e32 v66, v90, v66
	v_add_f32_e32 v66, v91, v66
	v_add_f32_e32 v66, v92, v66
	v_add_f32_e32 v66, v93, v66
	s_waitcnt lgkmcnt(0)
	v_mfma_f32_32x32x16_bf16 v[2:17], v[82:85], v[70:73], v[2:17]
	v_add_f32_e32 v82, v94, v66
	v_exp_f32_e32 v83, v74
	v_exp_f32_e32 v84, v75
	v_exp_f32_e32 v85, v76
	v_exp_f32_e32 v86, v77
	v_exp_f32_e32 v78, v78
	v_exp_f32_e32 v79, v79
	ds_read_b64_tr_b16 v[66:67], v141 offset:39936
	ds_read_b64_tr_b16 v[68:69], v141 offset:40448
	v_exp_f32_e32 v80, v80
	v_exp_f32_e32 v81, v81
	ds_read_b64_tr_b16 v[74:75], v141 offset:44032
	ds_read_b64_tr_b16 v[76:77], v141 offset:44544
	v_cvt_pk_bf16_f32 v70, v83, v84
	v_cvt_pk_bf16_f32 v71, v85, v86
	v_cvt_pk_bf16_f32 v72, v78, v79
	v_cvt_pk_bf16_f32 v73, v80, v81
	s_waitcnt lgkmcnt(2)
	s_nop 0
	v_mfma_f32_32x32x16_bf16 v[18:33], v[66:69], v[70:73], v[18:33]
	v_add_f32_e32 v66, v83, v82
	v_add_f32_e32 v66, v84, v66
	v_add_f32_e32 v66, v85, v66
	v_add_f32_e32 v66, v86, v66
	v_add_f32_e32 v66, v78, v66
	v_add_f32_e32 v66, v79, v66
	v_add_f32_e32 v66, v80, v66
	s_waitcnt lgkmcnt(0)
	v_mfma_f32_32x32x16_bf16 v[2:17], v[74:77], v[70:73], v[2:17]
	v_add_f32_e32 v145, v81, v66
	ds_read_b128 v[66:69], v130 offset:9216
	ds_read_b128 v[148:151], v130 offset:9248
	ds_read_b128 v[152:155], v130 offset:13824
	ds_read_b128 v[156:159], v130 offset:13856
	v_add_f32_e32 v144, v144, v145
	s_waitcnt lgkmcnt(3)
	v_mfma_f32_32x32x16_bf16 v[82:97], v[66:69], v[98:101], v[34:49]
	s_waitcnt lgkmcnt(1)
	v_mfma_f32_32x32x16_bf16 v[66:81], v[152:155], v[98:101], v[34:49]
	v_mfma_f32_32x32x16_bf16 v[82:97], v[148:151], v[102:105], v[82:97]
	ds_read_b128 v[148:151], v130 offset:9280
	ds_read_b128 v[152:155], v130 offset:9312
	s_waitcnt lgkmcnt(2)
	v_mfma_f32_32x32x16_bf16 v[66:81], v[156:159], v[102:105], v[66:81]
	s_waitcnt lgkmcnt(1)
	v_mfma_f32_32x32x16_bf16 v[82:97], v[148:151], v[106:109], v[82:97]
	ds_read_b128 v[148:151], v130 offset:13888
	ds_read_b128 v[156:159], v130 offset:13920
	s_waitcnt lgkmcnt(1)
	v_mfma_f32_32x32x16_bf16 v[66:81], v[148:151], v[106:109], v[66:81]
	v_mfma_f32_32x32x16_bf16 v[82:97], v[152:155], v[110:113], v[82:97]
	s_waitcnt lgkmcnt(0)
	v_mfma_f32_32x32x16_bf16 v[66:81], v[156:159], v[110:113], v[66:81]
	s_nop 15
	s_nop 7
	s_nop 0
	v_max3_f32 v145, v82, v83, v66
	v_max3_f32 v147, v84, v85, v67
	v_max3_f32 v145, v145, v68, v69
	v_max3_f32 v147, v147, v88, v89
	v_max3_f32 v145, v145, v86, v87
	v_max3_f32 v147, v147, v72, v73
	v_max3_f32 v145, v145, v70, v71
	v_max3_f32 v147, v147, v92, v93
	v_max3_f32 v145, v145, v90, v91
	v_max3_f32 v147, v147, v76, v77
	v_max3_f32 v145, v145, v74, v75
	v_max3_f32 v147, v147, v96, v97
	v_max3_f32 v145, v145, v94, v95
	v_max3_f32 v147, v147, v80, v81
	v_max3_f32 v145, v145, v78, v79
	v_max_f32_e32 v145, v145, v147
	v_cmp_lt_f32_e32 vcc, s47, v145
	s_cbranch_vccz .LBB0_609
; #define LAS __attribute__((address_space(3)))
; template <int DQK, int DV, bool BIAS> ...
;     ...
;     for (int g = 0; g < NG; ++g) {
;         const int pair = g & 1;
;         __syncthreads();
;         if (g + 1 < NG) {
; #pragma unroll
;             for (int j = 0; j < TPB; ++j) ATT_STORE((pair ^ 1) * TPB + j, j);
;             if (g + 2 < NG) {
; #pragma unroll
;                 for (int j = 0; j < TPB; ++j) ATT_LOAD((g + 2) * TPB + j, j);
;             }
;         }
;     ...
;         if (__any(mx > 8.f)) {
;             mx = fmaxf(mx, __shfl_xor(mx, 32));
;             const float dl = fmaxf(mx, 0.f); mhat += dl;
;             const float f = __builtin_amdgcn_exp2f(-dl);
; #pragma unroll
;             for (int r = 0; r < 16; ++r) { p0[r] -= dl; p1[r] -= dl; negm[r] = -mhat; }
;             l *= f;
; #pragma unroll
;             for (int d = 0; d < NDT; ++d)
; #pragma unroll
;                 for (int r = 0; r < 16; ++r) o[d][r] *= f;
;         }
;         if (!isY) {
;             const LAS unsigned char* vbase = lds + VOFF + vcur * VBUF + (4 * hi + ((lane & 15) >> 2)) * 64 + ((lane >> 4) & 1) * 32 + (lane & 3) * 8;
;             float ls = 0.f;
; #pragma unroll
;             for (int hs = 0; hs < 4; ++hs) {
;                 float e[8];
; #pragma unroll
;                 for (int j = 0; j < 8; ++j) { e[j] = __builtin_amdgcn_exp2f(hs < 2 ? p0[8 * (hs & 1) + j] : p1[8 * (hs & 1) + j]); ls += e[j]; }
;                 pw[hs].x = cvtpk(e[0], e[1]); pw[hs].y = cvtpk(e[2], e[3]); pw[hs].z = cvtpk(e[4], e[5]); pw[hs].w = cvtpk(e[6], e[7]);
;                 const bf16x8 pbv = __builtin_bit_cast(bf16x8, pw[hs]);
; #pragma unroll
;                 for (int d = 0; d < NDT; ++d) { const LAS unsigned char* vp = vbase + d * 4096 + hs * 1024;
;                     const v4i16_t a0 = __builtin_amdgcn_ds_read_tr16_b64_v4i16((LAS v4i16_t*)vp), a1 = __builtin_amdgcn_ds_read_tr16_b64_v4i16((LAS v4i16_t*)(vp + 512));
;                     const bf16x8 av = {a0[0], a0[1], a0[2], a0[3], a1[0], a1[1], a1[2], a1[3]};
;                     o[d] = __builtin_amdgcn_mfma_f32_32x32x16_bf16(av, pbv, o[d], 0, 0, 0); }
;                 __builtin_amdgcn_sched_barrier(0);
;             }
;             l += ls;
	ds_bpermute_b32 v34, v168, v145
	s_waitcnt lgkmcnt(0)
	v_max3_f32 v36, v145, v34, 0
	v_exp_f32_e64 v38, -v36
	v_add_f32_e32 v143, v143, v36
	v_xor_b32_e32 v34, 0x80000000, v143
	v_pk_add_f32 v[82:83], v[82:83], v[36:37] op_sel_hi:[1,0] neg_lo:[0,1] neg_hi:[0,1]
	v_pk_add_f32 v[66:67], v[66:67], v[36:37] op_sel_hi:[1,0] neg_lo:[0,1] neg_hi:[0,1]
	v_pk_add_f32 v[84:85], v[84:85], v[36:37] op_sel_hi:[1,0] neg_lo:[0,1] neg_hi:[0,1]
	v_pk_add_f32 v[68:69], v[68:69], v[36:37] op_sel_hi:[1,0] neg_lo:[0,1] neg_hi:[0,1]
	v_pk_add_f32 v[86:87], v[86:87], v[36:37] op_sel_hi:[1,0] neg_lo:[0,1] neg_hi:[0,1]
	v_pk_add_f32 v[70:71], v[70:71], v[36:37] op_sel_hi:[1,0] neg_lo:[0,1] neg_hi:[0,1]
	v_pk_add_f32 v[88:89], v[88:89], v[36:37] op_sel_hi:[1,0] neg_lo:[0,1] neg_hi:[0,1]
	v_pk_add_f32 v[72:73], v[72:73], v[36:37] op_sel_hi:[1,0] neg_lo:[0,1] neg_hi:[0,1]
	v_pk_add_f32 v[90:91], v[90:91], v[36:37] op_sel_hi:[1,0] neg_lo:[0,1] neg_hi:[0,1]
	v_pk_add_f32 v[74:75], v[74:75], v[36:37] op_sel_hi:[1,0] neg_lo:[0,1] neg_hi:[0,1]
	v_pk_add_f32 v[92:93], v[92:93], v[36:37] op_sel_hi:[1,0] neg_lo:[0,1] neg_hi:[0,1]
	v_pk_add_f32 v[76:77], v[76:77], v[36:37] op_sel_hi:[1,0] neg_lo:[0,1] neg_hi:[0,1]
	v_pk_add_f32 v[94:95], v[94:95], v[36:37] op_sel_hi:[1,0] neg_lo:[0,1] neg_hi:[0,1]
	v_pk_add_f32 v[78:79], v[78:79], v[36:37] op_sel_hi:[1,0] neg_lo:[0,1] neg_hi:[0,1]
	v_pk_add_f32 v[96:97], v[96:97], v[36:37] op_sel_hi:[1,0] neg_lo:[0,1] neg_hi:[0,1]
	v_pk_add_f32 v[80:81], v[80:81], v[36:37] op_sel_hi:[1,0] neg_lo:[0,1] neg_hi:[0,1]
	v_pk_mul_f32 v[16:17], v[16:17], v[38:39] op_sel_hi:[1,0]
	v_pk_mul_f32 v[14:15], v[14:15], v[38:39] op_sel_hi:[1,0]
	v_pk_mul_f32 v[12:13], v[12:13], v[38:39] op_sel_hi:[1,0]
	v_pk_mul_f32 v[10:11], v[10:11], v[38:39] op_sel_hi:[1,0]
	v_pk_mul_f32 v[8:9], v[8:9], v[38:39] op_sel_hi:[1,0]
	v_pk_mul_f32 v[6:7], v[6:7], v[38:39] op_sel_hi:[1,0]
	v_pk_mul_f32 v[4:5], v[4:5], v[38:39] op_sel_hi:[1,0]
	v_pk_mul_f32 v[2:3], v[2:3], v[38:39] op_sel_hi:[1,0]
	v_pk_mul_f32 v[32:33], v[32:33], v[38:39] op_sel_hi:[1,0]
	v_pk_mul_f32 v[30:31], v[30:31], v[38:39] op_sel_hi:[1,0]
	v_pk_mul_f32 v[28:29], v[28:29], v[38:39] op_sel_hi:[1,0]
	v_pk_mul_f32 v[26:27], v[26:27], v[38:39] op_sel_hi:[1,0]
	v_pk_mul_f32 v[24:25], v[24:25], v[38:39] op_sel_hi:[1,0]
	v_pk_mul_f32 v[22:23], v[22:23], v[38:39] op_sel_hi:[1,0]
	v_pk_mul_f32 v[20:21], v[20:21], v[38:39] op_sel_hi:[1,0]
	v_pk_mul_f32 v[18:19], v[18:19], v[38:39] op_sel_hi:[1,0]
	v_mul_f32_e32 v144, v144, v38
	v_mov_b32_e32 v35, v34
	v_mov_b32_e32 v36, v34
	v_mov_b32_e32 v37, v34
	v_mov_b32_e32 v38, v34
	v_mov_b32_e32 v39, v34
	v_mov_b32_e32 v40, v34
	v_mov_b32_e32 v41, v34
	v_mov_b32_e32 v42, v34
	v_mov_b32_e32 v43, v34
	v_mov_b32_e32 v44, v34
	v_mov_b32_e32 v45, v34
	v_mov_b32_e32 v46, v34
	v_mov_b32_e32 v47, v34
	v_mov_b32_e32 v48, v34
	v_mov_b32_e32 v49, v34
	v_mov_b32_e32 v50, v34
	v_mov_b32_e32 v51, v34
	v_mov_b32_e32 v52, v34
	v_mov_b32_e32 v53, v34
	v_mov_b32_e32 v54, v34
	v_mov_b32_e32 v55, v34
	v_mov_b32_e32 v56, v34
	v_mov_b32_e32 v57, v34
	v_mov_b32_e32 v58, v34
	v_mov_b32_e32 v59, v34
	v_mov_b32_e32 v60, v34
	v_mov_b32_e32 v61, v34
	v_mov_b32_e32 v62, v34
	v_mov_b32_e32 v63, v34
	v_mov_b32_e32 v64, v34
	v_mov_b32_e32 v65, v34
.LBB0_609:
	v_exp_f32_e32 v150, v82
	v_exp_f32_e32 v151, v83
	v_exp_f32_e32 v145, v84
	v_exp_f32_e32 v147, v85
	v_exp_f32_e32 v148, v86
	v_exp_f32_e32 v149, v87
	ds_read_b64_tr_b16 v[82:83], v141 offset:45056
	ds_read_b64_tr_b16 v[84:85], v141 offset:45568
	v_exp_f32_e32 v152, v88
	v_exp_f32_e32 v153, v89
	ds_read_b64_tr_b16 v[154:155], v141 offset:49152
	ds_read_b64_tr_b16 v[156:157], v141 offset:49664
	v_cvt_pk_bf16_f32 v86, v150, v151
	v_cvt_pk_bf16_f32 v87, v145, v147
	v_cvt_pk_bf16_f32 v88, v148, v149
	v_cvt_pk_bf16_f32 v89, v152, v153
	s_waitcnt lgkmcnt(2)
	s_nop 0
	v_mfma_f32_32x32x16_bf16 v[18:33], v[82:85], v[86:89], v[18:33]
	s_waitcnt lgkmcnt(0)
	v_mfma_f32_32x32x16_bf16 v[2:17], v[154:157], v[86:89], v[2:17]
	v_exp_f32_e32 v155, v90
	v_exp_f32_e32 v156, v91
	v_exp_f32_e32 v157, v92
	v_exp_f32_e32 v158, v93
	v_exp_f32_e32 v159, v94
	v_exp_f32_e32 v154, v95
	ds_read_b64_tr_b16 v[82:83], v141 offset:46080
	ds_read_b64_tr_b16 v[84:85], v141 offset:46592
	v_exp_f32_e32 v160, v96
	v_exp_f32_e32 v161, v97
	ds_read_b64_tr_b16 v[90:91], v141 offset:50176
	ds_read_b64_tr_b16 v[92:93], v141 offset:50688
	v_cvt_pk_bf16_f32 v86, v155, v156
	v_cvt_pk_bf16_f32 v87, v157, v158
	v_cvt_pk_bf16_f32 v88, v159, v154
	v_cvt_pk_bf16_f32 v89, v160, v161
	s_waitcnt lgkmcnt(2)
	s_nop 0
	v_mfma_f32_32x32x16_bf16 v[18:33], v[82:85], v[86:89], v[18:33]
	s_waitcnt lgkmcnt(0)
	v_mfma_f32_32x32x16_bf16 v[2:17], v[90:93], v[86:89], v[2:17]
	v_exp_f32_e32 v165, v66
	v_exp_f32_e32 v166, v67
	v_exp_f32_e32 v167, v68
	v_exp_f32_e32 v162, v69
	v_exp_f32_e32 v163, v70
	v_exp_f32_e32 v164, v71
	ds_read_b64_tr_b16 v[66:67], v141 offset:47104
	ds_read_b64_tr_b16 v[68:69], v141 offset:47616
	v_exp_f32_e32 v169, v72
	v_exp_f32_e32 v170, v73
	ds_read_b64_tr_b16 v[82:83], v141 offset:51200
	ds_read_b64_tr_b16 v[84:85], v141 offset:51712
	v_cvt_pk_bf16_f32 v70, v165, v166
	v_cvt_pk_bf16_f32 v71, v167, v162
	v_cvt_pk_bf16_f32 v72, v163, v164
	v_cvt_pk_bf16_f32 v73, v169, v170
	s_waitcnt lgkmcnt(2)
	s_nop 0
	v_mfma_f32_32x32x16_bf16 v[18:33], v[66:69], v[70:73], v[18:33]
	s_waitcnt lgkmcnt(0)
	v_mfma_f32_32x32x16_bf16 v[2:17], v[82:85], v[70:73], v[2:17]
	v_exp_f32_e32 v175, v74
	v_exp_f32_e32 v176, v75
	v_exp_f32_e32 v171, v76
	v_exp_f32_e32 v172, v77
	v_exp_f32_e32 v173, v78
	v_exp_f32_e32 v174, v79
	ds_read_b64_tr_b16 v[66:67], v141 offset:48128
	ds_read_b64_tr_b16 v[68:69], v141 offset:48640
	v_exp_f32_e32 v177, v80
	v_exp_f32_e32 v178, v81
	ds_read_b64_tr_b16 v[74:75], v141 offset:52224
	ds_read_b64_tr_b16 v[76:77], v141 offset:52736
	v_cvt_pk_bf16_f32 v70, v175, v176
	v_cvt_pk_bf16_f32 v71, v171, v172
	v_cvt_pk_bf16_f32 v72, v173, v174
	v_cvt_pk_bf16_f32 v73, v177, v178
	s_waitcnt lgkmcnt(2)
	s_nop 0
	v_mfma_f32_32x32x16_bf16 v[18:33], v[66:69], v[70:73], v[18:33]
	s_waitcnt lgkmcnt(0)
	v_mfma_f32_32x32x16_bf16 v[2:17], v[74:77], v[70:73], v[2:17]
	s_cmp_eq_u32 s18, 0x17ac000
	s_barrier
	s_cbranch_scc1 .LBB0_612
	s_andn2_b64 vcc, exec, s[20:21]
	s_waitcnt vmcnt(3)
	ds_write_b128 v133, v[114:117]
	s_waitcnt vmcnt(2)
	ds_write_b128 v140, v[118:121] offset:36864
	s_waitcnt vmcnt(1)
	ds_write_b128 v133, v[122:125] offset:9216
	s_waitcnt vmcnt(0)
	ds_write_b128 v140, v[126:129] offset:45056
	s_cbranch_vccnz .LBB0_612
	s_add_u32 s100, s4, s18
	s_addc_u32 s101, s5, s19
	s_add_u32 s100, s100, 0x25f000
	s_addc_u32 s101, s101, 0
	global_load_dwordx4 v[114:117], v225, s[100:101]
	global_load_dwordx4 v[118:121], v224, s[100:101] offset:256
	s_add_u32 s100, s100, 0x65000
	s_addc_u32 s101, s101, 0
	global_load_dwordx4 v[122:125], v225, s[100:101]
	global_load_dwordx4 v[126:129], v224, s[100:101] offset:256
; #define LAS __attribute__((address_space(3)))
; __device__ __forceinline__ float max3f(float a, float b, float c) { float r; asm("v_max3_f32 %0, %1, %2, %3" : "=v"(r) : "v"(a), "v"(b), "v"(c)); return r; }
; template <int DQK, int DV, bool BIAS> ...
;     ...
;         const LAS unsigned char* kb = lds + buf * KBUF + r32 * KP + hi * 16;
; #pragma unroll
;         for (int ks = 0; ks < NKS; ++ks) {
;             const bf16x8 k0 = *(const LAS bf16x8*)(kb + ks * 32), k1 = *(const LAS bf16x8*)(kb + 32 * KP + ks * 32);
;             if (ks == 0) { p0 = __builtin_amdgcn_mfma_f32_32x32x16_bf16(k0, qf[0], negm, 0, 0, 0); p1 = __builtin_amdgcn_mfma_f32_32x32x16_bf16(k1, qf[0], negm, 0, 0, 0); }
;             else { p0 = __builtin_amdgcn_mfma_f32_32x32x16_bf16(k0, qf[ks], p0, 0, 0, 0); p1 = __builtin_amdgcn_mfma_f32_32x32x16_bf16(k1, qf[ks], p1, 0, 0, 0); }
;         }
;         if (BIAS) {
;             asm volatile("s_nop 15\n\ts_nop 7" : "+v"(p0), "+v"(p1));
;             const float d0 = qp - (float)(t * 64 + 4 * hi);
; #pragma unroll
;             for (int r = 0; r < 16; ++r) { const float dk = d0 - (float)((r & 3) + 8 * (r >> 2)); p0[r] = p0[r] - sl2 * fabsf(dk); p1[r] = p1[r] - sl2 * fabsf(dk - 32.f); }
;         } else {
;             asm volatile("s_nop 15\n\ts_nop 7" : "+v"(p0), "+v"(p1));
;         }
;         float mxa = max3f(p0[0], p0[1], p1[0]), mxb = max3f(p0[2], p0[3], p1[1]); mxa = max3f(mxa, p1[2], p1[3]);
; #pragma unroll
;         for (int r = 4; r < 16; r += 4) { mxa = max3f(mxa, p0[r], p0[r + 1]); mxb = max3f(mxb, p0[r + 2], p0[r + 3]); mxa = max3f(mxa, p1[r], p1[r + 1]); mxb = max3f(mxb, p1[r + 2], p1[r + 3]); }
;         float mx = fmaxf(mxa, mxb);
;         if (__any(mx > 8.f)) {
;             mx = fmaxf(mx, __shfl_xor(mx, 32));
;             const float dl = fmaxf(mx, 0.f); mhat += dl;
;             const float f = __builtin_amdgcn_exp2f(-dl);
; #pragma unroll
;             for (int r = 0; r < 16; ++r) { p0[r] -= dl; p1[r] -= dl; negm[r] = -mhat; }
;             l *= f;
; #pragma unroll
;             for (int d = 0; d < NDT; ++d)
; #pragma unroll
;                 for (int r = 0; r < 16; ++r) o[d][r] *= f;
;         }
.LBB0_612:
	v_add_f32_e32 v150, v151, v150
	ds_read_b128 v[66:69], v130 offset:18432
	ds_read_b128 v[180:183], v130 offset:18464
	v_add_f32_e32 v145, v145, v150
	ds_read_b128 v[184:187], v130 offset:23040
	ds_read_b128 v[188:191], v130 offset:23072
	v_add_f32_e32 v145, v147, v145
	v_add_f32_e32 v145, v148, v145
	v_add_f32_e32 v145, v149, v145
	s_waitcnt lgkmcnt(3)
	v_mfma_f32_32x32x16_bf16 v[82:97], v[66:69], v[98:101], v[34:49]
	v_add_f32_e32 v145, v152, v145
	v_add_f32_e32 v145, v153, v145
	v_add_f32_e32 v145, v155, v145
	v_add_f32_e32 v145, v156, v145
	v_add_f32_e32 v145, v157, v145
	v_add_f32_e32 v145, v158, v145
	v_add_f32_e32 v145, v159, v145
	s_waitcnt lgkmcnt(1)
	v_mfma_f32_32x32x16_bf16 v[66:81], v[184:187], v[98:101], v[34:49]
	ds_read_b128 v[148:151], v130 offset:18496
	v_add_f32_e32 v145, v154, v145
	v_add_f32_e32 v145, v160, v145
	v_add_f32_e32 v145, v161, v145
	v_add_f32_e32 v145, v165, v145
	v_add_f32_e32 v145, v166, v145
	v_add_f32_e32 v145, v167, v145
	v_mfma_f32_32x32x16_bf16 v[82:97], v[180:183], v[102:105], v[82:97]
	ds_read_b128 v[156:159], v130 offset:23104
	ds_read_b128 v[180:183], v130 offset:18528
	v_add_f32_e32 v145, v162, v145
	v_add_f32_e32 v145, v163, v145
	v_add_f32_e32 v145, v164, v145
	v_add_f32_e32 v145, v169, v145
	v_add_f32_e32 v145, v170, v145
	v_add_f32_e32 v145, v175, v145
	s_waitcnt lgkmcnt(3)
	v_mfma_f32_32x32x16_bf16 v[66:81], v[188:191], v[102:105], v[66:81]
	v_add_f32_e32 v145, v176, v145
	v_add_f32_e32 v145, v171, v145
	v_add_f32_e32 v145, v172, v145
	v_add_f32_e32 v145, v173, v145
	v_add_f32_e32 v145, v174, v145
	v_add_f32_e32 v145, v177, v145
	v_add_f32_e32 v145, v178, v145
	s_waitcnt lgkmcnt(2)
	v_mfma_f32_32x32x16_bf16 v[82:97], v[148:151], v[106:109], v[82:97]
	ds_read_b128 v[148:151], v130 offset:23136
	v_add_f32_e32 v144, v144, v145
	s_waitcnt lgkmcnt(2)
	v_mfma_f32_32x32x16_bf16 v[66:81], v[156:159], v[106:109], v[66:81]
	s_waitcnt lgkmcnt(1)
	v_mfma_f32_32x32x16_bf16 v[82:97], v[180:183], v[110:113], v[82:97]
	s_waitcnt lgkmcnt(0)
	v_mfma_f32_32x32x16_bf16 v[66:81], v[148:151], v[110:113], v[66:81]
	s_nop 15
	s_nop 7
	s_nop 0
	v_max3_f32 v145, v82, v83, v66
	v_max3_f32 v147, v84, v85, v67
	v_max3_f32 v145, v145, v68, v69
	v_max3_f32 v147, v147, v88, v89
	v_max3_f32 v145, v145, v86, v87
	v_max3_f32 v147, v147, v72, v73
	v_max3_f32 v145, v145, v70, v71
	v_max3_f32 v147, v147, v92, v93
	v_max3_f32 v145, v145, v90, v91
	v_max3_f32 v147, v147, v76, v77
	v_max3_f32 v145, v145, v74, v75
	v_max3_f32 v147, v147, v96, v97
	v_max3_f32 v145, v145, v94, v95
	v_max3_f32 v147, v147, v80, v81
	v_max3_f32 v145, v145, v78, v79
	v_max_f32_e32 v145, v145, v147
	v_cmp_lt_f32_e32 vcc, s47, v145
	s_cbranch_vccz .LBB0_614
	ds_bpermute_b32 v34, v168, v145
	s_waitcnt lgkmcnt(0)
	v_max3_f32 v36, v145, v34, 0
	v_exp_f32_e64 v38, -v36
	v_add_f32_e32 v143, v143, v36
	v_xor_b32_e32 v34, 0x80000000, v143
	v_pk_add_f32 v[82:83], v[82:83], v[36:37] op_sel_hi:[1,0] neg_lo:[0,1] neg_hi:[0,1]
	v_pk_add_f32 v[66:67], v[66:67], v[36:37] op_sel_hi:[1,0] neg_lo:[0,1] neg_hi:[0,1]
	v_pk_add_f32 v[84:85], v[84:85], v[36:37] op_sel_hi:[1,0] neg_lo:[0,1] neg_hi:[0,1]
	v_pk_add_f32 v[68:69], v[68:69], v[36:37] op_sel_hi:[1,0] neg_lo:[0,1] neg_hi:[0,1]
	v_pk_add_f32 v[86:87], v[86:87], v[36:37] op_sel_hi:[1,0] neg_lo:[0,1] neg_hi:[0,1]
	v_pk_add_f32 v[70:71], v[70:71], v[36:37] op_sel_hi:[1,0] neg_lo:[0,1] neg_hi:[0,1]
	v_pk_add_f32 v[88:89], v[88:89], v[36:37] op_sel_hi:[1,0] neg_lo:[0,1] neg_hi:[0,1]
	v_pk_add_f32 v[72:73], v[72:73], v[36:37] op_sel_hi:[1,0] neg_lo:[0,1] neg_hi:[0,1]
	v_pk_add_f32 v[90:91], v[90:91], v[36:37] op_sel_hi:[1,0] neg_lo:[0,1] neg_hi:[0,1]
	v_pk_add_f32 v[74:75], v[74:75], v[36:37] op_sel_hi:[1,0] neg_lo:[0,1] neg_hi:[0,1]
	v_pk_add_f32 v[92:93], v[92:93], v[36:37] op_sel_hi:[1,0] neg_lo:[0,1] neg_hi:[0,1]
	v_pk_add_f32 v[76:77], v[76:77], v[36:37] op_sel_hi:[1,0] neg_lo:[0,1] neg_hi:[0,1]
	v_pk_add_f32 v[94:95], v[94:95], v[36:37] op_sel_hi:[1,0] neg_lo:[0,1] neg_hi:[0,1]
	v_pk_add_f32 v[78:79], v[78:79], v[36:37] op_sel_hi:[1,0] neg_lo:[0,1] neg_hi:[0,1]
	v_pk_add_f32 v[96:97], v[96:97], v[36:37] op_sel_hi:[1,0] neg_lo:[0,1] neg_hi:[0,1]
	v_pk_add_f32 v[80:81], v[80:81], v[36:37] op_sel_hi:[1,0] neg_lo:[0,1] neg_hi:[0,1]
	v_pk_mul_f32 v[16:17], v[16:17], v[38:39] op_sel_hi:[1,0]
	v_pk_mul_f32 v[14:15], v[14:15], v[38:39] op_sel_hi:[1,0]
	v_pk_mul_f32 v[12:13], v[12:13], v[38:39] op_sel_hi:[1,0]
	v_pk_mul_f32 v[10:11], v[10:11], v[38:39] op_sel_hi:[1,0]
	v_pk_mul_f32 v[8:9], v[8:9], v[38:39] op_sel_hi:[1,0]
	v_pk_mul_f32 v[6:7], v[6:7], v[38:39] op_sel_hi:[1,0]
	v_pk_mul_f32 v[4:5], v[4:5], v[38:39] op_sel_hi:[1,0]
	v_pk_mul_f32 v[2:3], v[2:3], v[38:39] op_sel_hi:[1,0]
	v_pk_mul_f32 v[32:33], v[32:33], v[38:39] op_sel_hi:[1,0]
	v_pk_mul_f32 v[30:31], v[30:31], v[38:39] op_sel_hi:[1,0]
	v_pk_mul_f32 v[28:29], v[28:29], v[38:39] op_sel_hi:[1,0]
	v_pk_mul_f32 v[26:27], v[26:27], v[38:39] op_sel_hi:[1,0]
	v_pk_mul_f32 v[24:25], v[24:25], v[38:39] op_sel_hi:[1,0]
	v_pk_mul_f32 v[22:23], v[22:23], v[38:39] op_sel_hi:[1,0]
	v_pk_mul_f32 v[20:21], v[20:21], v[38:39] op_sel_hi:[1,0]
	v_pk_mul_f32 v[18:19], v[18:19], v[38:39] op_sel_hi:[1,0]
	v_mul_f32_e32 v144, v144, v38
	v_mov_b32_e32 v35, v34
	v_mov_b32_e32 v36, v34
	v_mov_b32_e32 v37, v34
	v_mov_b32_e32 v38, v34
	v_mov_b32_e32 v39, v34
	v_mov_b32_e32 v40, v34
	v_mov_b32_e32 v41, v34
	v_mov_b32_e32 v42, v34
	v_mov_b32_e32 v43, v34
	v_mov_b32_e32 v44, v34
	v_mov_b32_e32 v45, v34
	v_mov_b32_e32 v46, v34
	v_mov_b32_e32 v47, v34
	v_mov_b32_e32 v48, v34
	v_mov_b32_e32 v49, v34
	v_mov_b32_e32 v50, v34
	v_mov_b32_e32 v51, v34
	v_mov_b32_e32 v52, v34
	v_mov_b32_e32 v53, v34
	v_mov_b32_e32 v54, v34
	v_mov_b32_e32 v55, v34
	v_mov_b32_e32 v56, v34
	v_mov_b32_e32 v57, v34
	v_mov_b32_e32 v58, v34
	v_mov_b32_e32 v59, v34
	v_mov_b32_e32 v60, v34
	v_mov_b32_e32 v61, v34
	v_mov_b32_e32 v62, v34
	v_mov_b32_e32 v63, v34
	v_mov_b32_e32 v64, v34
	v_mov_b32_e32 v65, v34
; #define LAS __attribute__((address_space(3)))
; template <int DQK, int DV, bool BIAS> ...
;     ...
;         const LAS unsigned char* kb = lds + buf * KBUF + r32 * KP + hi * 16;
; #pragma unroll
;         for (int ks = 0; ks < NKS; ++ks) {
;             const bf16x8 k0 = *(const LAS bf16x8*)(kb + ks * 32), k1 = *(const LAS bf16x8*)(kb + 32 * KP + ks * 32);
;             if (ks == 0) { p0 = __builtin_amdgcn_mfma_f32_32x32x16_bf16(k0, qf[0], negm, 0, 0, 0); p1 = __builtin_amdgcn_mfma_f32_32x32x16_bf16(k1, qf[0], negm, 0, 0, 0); }
;             else { p0 = __builtin_amdgcn_mfma_f32_32x32x16_bf16(k0, qf[ks], p0, 0, 0, 0); p1 = __builtin_amdgcn_mfma_f32_32x32x16_bf16(k1, qf[ks], p1, 0, 0, 0); }
;         }
;         if (BIAS) {
;             asm volatile("s_nop 15\n\ts_nop 7" : "+v"(p0), "+v"(p1));
;             const float d0 = qp - (float)(t * 64 + 4 * hi);
; #pragma unroll
;             for (int r = 0; r < 16; ++r) { const float dk = d0 - (float)((r & 3) + 8 * (r >> 2)); p0[r] = p0[r] - sl2 * fabsf(dk); p1[r] = p1[r] - sl2 * fabsf(dk - 32.f); }
;         } else {
;             asm volatile("s_nop 15\n\ts_nop 7" : "+v"(p0), "+v"(p1));
;         }
;         float mxa = max3f(p0[0], p0[1], p1[0]), mxb = max3f(p0[2], p0[3], p1[1]); mxa = max3f(mxa, p1[2], p1[3]);
; #pragma unroll
;     ...
;             float ls = 0.f;
; #pragma unroll
;             for (int hs = 0; hs < 4; ++hs) {
;                 float e[8];
; #pragma unroll
;                 for (int j = 0; j < 8; ++j) { e[j] = __builtin_amdgcn_exp2f(hs < 2 ? p0[8 * (hs & 1) + j] : p1[8 * (hs & 1) + j]); ls += e[j]; }
;                 pw[hs].x = cvtpk(e[0], e[1]); pw[hs].y = cvtpk(e[2], e[3]); pw[hs].z = cvtpk(e[4], e[5]); pw[hs].w = cvtpk(e[6], e[7]);
;                 const bf16x8 pbv = __builtin_bit_cast(bf16x8, pw[hs]);
; #pragma unroll
;                 for (int d = 0; d < NDT; ++d) { const LAS unsigned char* vp = vbase + d * 4096 + hs * 1024;
;                     const v4i16_t a0 = __builtin_amdgcn_ds_read_tr16_b64_v4i16((LAS v4i16_t*)vp), a1 = __builtin_amdgcn_ds_read_tr16_b64_v4i16((LAS v4i16_t*)(vp + 512));
;                     const bf16x8 av = {a0[0], a0[1], a0[2], a0[3], a1[0], a1[1], a1[2], a1[3]};
;                     o[d] = __builtin_amdgcn_mfma_f32_32x32x16_bf16(av, pbv, o[d], 0, 0, 0); }
;                 __builtin_amdgcn_sched_barrier(0);
;             }
;             l += ls;
.LBB0_614:
	v_exp_f32_e32 v145, v82
	v_exp_f32_e32 v147, v83
	v_exp_f32_e32 v152, v84
	v_exp_f32_e32 v153, v85
	v_exp_f32_e32 v154, v86
	v_exp_f32_e32 v155, v87
	ds_read_b64_tr_b16 v[82:83], v141 offset:53248
	ds_read_b64_tr_b16 v[84:85], v141 offset:53760
	v_exp_f32_e32 v156, v88
	v_exp_f32_e32 v157, v89
	ds_read_b64_tr_b16 v[148:149], v141 offset:57344
	ds_read_b64_tr_b16 v[150:151], v141 offset:57856
	v_cvt_pk_bf16_f32 v86, v145, v147
	v_cvt_pk_bf16_f32 v87, v152, v153
	v_cvt_pk_bf16_f32 v88, v154, v155
	v_cvt_pk_bf16_f32 v89, v156, v157
	s_waitcnt lgkmcnt(2)
	s_nop 0
	v_mfma_f32_32x32x16_bf16 v[18:33], v[82:85], v[86:89], v[18:33]
	v_add_f32_e32 v82, v147, v145
	v_add_f32_e32 v82, v152, v82
	v_add_f32_e32 v82, v153, v82
	v_add_f32_e32 v82, v154, v82
	v_add_f32_e32 v82, v155, v82
	v_add_f32_e32 v82, v156, v82
	s_waitcnt lgkmcnt(0)
	v_mfma_f32_32x32x16_bf16 v[2:17], v[148:151], v[86:89], v[2:17]
	v_add_f32_e32 v145, v157, v82
	v_exp_f32_e32 v147, v90
	v_exp_f32_e32 v148, v91
	v_exp_f32_e32 v149, v92
	v_exp_f32_e32 v150, v93
	v_exp_f32_e32 v94, v94
	v_exp_f32_e32 v95, v95
	ds_read_b64_tr_b16 v[82:83], v141 offset:54272
	ds_read_b64_tr_b16 v[84:85], v141 offset:54784
	v_exp_f32_e32 v96, v96
	v_exp_f32_e32 v97, v97
	ds_read_b64_tr_b16 v[90:91], v141 offset:58368
	ds_read_b64_tr_b16 v[92:93], v141 offset:58880
	v_cvt_pk_bf16_f32 v86, v147, v148
	v_cvt_pk_bf16_f32 v87, v149, v150
	v_cvt_pk_bf16_f32 v88, v94, v95
	v_cvt_pk_bf16_f32 v89, v96, v97
	s_waitcnt lgkmcnt(2)
	s_nop 0
	v_mfma_f32_32x32x16_bf16 v[18:33], v[82:85], v[86:89], v[18:33]
	v_add_f32_e32 v82, v147, v145
	v_add_f32_e32 v82, v148, v82
	v_add_f32_e32 v82, v149, v82
	v_add_f32_e32 v82, v150, v82
	v_add_f32_e32 v82, v94, v82
	v_add_f32_e32 v82, v95, v82
	v_add_f32_e32 v82, v96, v82
	s_waitcnt lgkmcnt(0)
	v_mfma_f32_32x32x16_bf16 v[2:17], v[90:93], v[86:89], v[2:17]
	v_add_f32_e32 v86, v97, v82
	v_exp_f32_e32 v87, v66
	v_exp_f32_e32 v88, v67
	v_exp_f32_e32 v89, v68
	v_exp_f32_e32 v90, v69
	v_exp_f32_e32 v91, v70
	v_exp_f32_e32 v92, v71
	ds_read_b64_tr_b16 v[66:67], v141 offset:55296
	ds_read_b64_tr_b16 v[68:69], v141 offset:55808
	v_exp_f32_e32 v93, v72
	v_exp_f32_e32 v94, v73
	ds_read_b64_tr_b16 v[82:83], v141 offset:59392
	ds_read_b64_tr_b16 v[84:85], v141 offset:59904
	v_cvt_pk_bf16_f32 v70, v87, v88
	v_cvt_pk_bf16_f32 v71, v89, v90
	v_cvt_pk_bf16_f32 v72, v91, v92
	v_cvt_pk_bf16_f32 v73, v93, v94
	s_waitcnt lgkmcnt(2)
	s_nop 0
	v_mfma_f32_32x32x16_bf16 v[18:33], v[66:69], v[70:73], v[18:33]
	v_add_f32_e32 v66, v87, v86
	v_add_f32_e32 v66, v88, v66
	v_add_f32_e32 v66, v89, v66
	v_add_f32_e32 v66, v90, v66
	v_add_f32_e32 v66, v91, v66
	v_add_f32_e32 v66, v92, v66
	v_add_f32_e32 v66, v93, v66
	s_waitcnt lgkmcnt(0)
	v_mfma_f32_32x32x16_bf16 v[2:17], v[82:85], v[70:73], v[2:17]
	v_add_f32_e32 v82, v94, v66
	v_exp_f32_e32 v83, v74
	v_exp_f32_e32 v84, v75
	v_exp_f32_e32 v85, v76
	v_exp_f32_e32 v86, v77
	v_exp_f32_e32 v78, v78
	v_exp_f32_e32 v79, v79
	ds_read_b64_tr_b16 v[66:67], v141 offset:56320
	ds_read_b64_tr_b16 v[68:69], v141 offset:56832
	v_exp_f32_e32 v80, v80
	v_exp_f32_e32 v81, v81
	ds_read_b64_tr_b16 v[74:75], v141 offset:60416
	ds_read_b64_tr_b16 v[76:77], v141 offset:60928
	v_cvt_pk_bf16_f32 v70, v83, v84
	v_cvt_pk_bf16_f32 v71, v85, v86
	v_cvt_pk_bf16_f32 v72, v78, v79
	v_cvt_pk_bf16_f32 v73, v80, v81
	s_waitcnt lgkmcnt(2)
	s_nop 0
	v_mfma_f32_32x32x16_bf16 v[18:33], v[66:69], v[70:73], v[18:33]
	v_add_f32_e32 v66, v83, v82
	v_add_f32_e32 v66, v84, v66
	v_add_f32_e32 v66, v85, v66
	v_add_f32_e32 v66, v86, v66
	v_add_f32_e32 v66, v78, v66
	v_add_f32_e32 v66, v79, v66
	v_add_f32_e32 v66, v80, v66
	s_waitcnt lgkmcnt(0)
	v_mfma_f32_32x32x16_bf16 v[2:17], v[74:77], v[70:73], v[2:17]
	v_add_f32_e32 v94, v81, v66
	ds_read_b128 v[82:85], v130 offset:27648
	ds_read_b128 v[86:89], v130 offset:27680
	s_waitcnt lgkmcnt(1)
	v_mfma_f32_32x32x16_bf16 v[66:81], v[82:85], v[98:101], v[34:49]
	ds_read_b128 v[82:85], v130 offset:32256
	ds_read_b128 v[90:93], v130 offset:32288
	s_waitcnt lgkmcnt(1)
	v_mfma_f32_32x32x16_bf16 v[34:49], v[82:85], v[98:101], v[34:49]
	v_mfma_f32_32x32x16_bf16 v[66:81], v[86:89], v[102:105], v[66:81]
	ds_read_b128 v[82:85], v130 offset:27712
	ds_read_b128 v[86:89], v130 offset:27744
	s_waitcnt lgkmcnt(2)
	v_mfma_f32_32x32x16_bf16 v[34:49], v[90:93], v[102:105], v[34:49]
	s_waitcnt lgkmcnt(1)
	v_mfma_f32_32x32x16_bf16 v[66:81], v[82:85], v[106:109], v[66:81]
	ds_read_b128 v[82:85], v130 offset:32320
	ds_read_b128 v[90:93], v130 offset:32352
	s_waitcnt lgkmcnt(1)
	v_mfma_f32_32x32x16_bf16 v[34:49], v[82:85], v[106:109], v[34:49]
	v_add_f32_e32 v82, v144, v94
	v_mfma_f32_32x32x16_bf16 v[66:81], v[86:89], v[110:113], v[66:81]
	s_waitcnt lgkmcnt(0)
	v_mfma_f32_32x32x16_bf16 v[34:49], v[90:93], v[110:113], v[34:49]
	s_nop 15
	s_nop 7
	s_nop 0
	v_max3_f32 v83, v66, v67, v34
	v_max3_f32 v84, v68, v69, v35
	v_max3_f32 v83, v83, v36, v37
	v_max3_f32 v84, v84, v72, v73
	v_max3_f32 v83, v83, v70, v71
	v_max3_f32 v84, v84, v40, v41
	v_max3_f32 v83, v83, v38, v39
	v_max3_f32 v84, v84, v76, v77
	v_max3_f32 v83, v83, v74, v75
	v_max3_f32 v84, v84, v44, v45
	v_max3_f32 v83, v83, v42, v43
	v_max3_f32 v84, v84, v80, v81
	v_max3_f32 v83, v83, v78, v79
	v_max3_f32 v84, v84, v48, v49
	v_max3_f32 v83, v83, v46, v47
	v_max_f32_e32 v83, v83, v84
	v_cmp_lt_f32_e32 vcc, s47, v83
	s_cbranch_vccz .LBB0_601
; template <int DQK, int DV, bool BIAS> ...
;     ...
;         if (__any(mx > 8.f)) {
;             mx = fmaxf(mx, __shfl_xor(mx, 32));
;             const float dl = fmaxf(mx, 0.f); mhat += dl;
;             const float f = __builtin_amdgcn_exp2f(-dl);
; #pragma unroll
;             for (int r = 0; r < 16; ++r) { p0[r] -= dl; p1[r] -= dl; negm[r] = -mhat; }
;             l *= f;
; #pragma unroll
;             for (int d = 0; d < NDT; ++d)
; #pragma unroll
;                 for (int r = 0; r < 16; ++r) o[d][r] *= f;
;         }
	ds_bpermute_b32 v50, v168, v83
	s_waitcnt lgkmcnt(0)
	v_max3_f32 v52, v83, v50, 0
	v_exp_f32_e64 v54, -v52
	v_add_f32_e32 v143, v143, v52
	v_xor_b32_e32 v50, 0x80000000, v143
	v_pk_add_f32 v[66:67], v[66:67], v[52:53] op_sel_hi:[1,0] neg_lo:[0,1] neg_hi:[0,1]
	v_pk_add_f32 v[34:35], v[34:35], v[52:53] op_sel_hi:[1,0] neg_lo:[0,1] neg_hi:[0,1]
	v_pk_add_f32 v[68:69], v[68:69], v[52:53] op_sel_hi:[1,0] neg_lo:[0,1] neg_hi:[0,1]
	v_pk_add_f32 v[36:37], v[36:37], v[52:53] op_sel_hi:[1,0] neg_lo:[0,1] neg_hi:[0,1]
	v_pk_add_f32 v[70:71], v[70:71], v[52:53] op_sel_hi:[1,0] neg_lo:[0,1] neg_hi:[0,1]
	v_pk_add_f32 v[38:39], v[38:39], v[52:53] op_sel_hi:[1,0] neg_lo:[0,1] neg_hi:[0,1]
	v_pk_add_f32 v[72:73], v[72:73], v[52:53] op_sel_hi:[1,0] neg_lo:[0,1] neg_hi:[0,1]
	v_pk_add_f32 v[40:41], v[40:41], v[52:53] op_sel_hi:[1,0] neg_lo:[0,1] neg_hi:[0,1]
	v_pk_add_f32 v[74:75], v[74:75], v[52:53] op_sel_hi:[1,0] neg_lo:[0,1] neg_hi:[0,1]
	v_pk_add_f32 v[42:43], v[42:43], v[52:53] op_sel_hi:[1,0] neg_lo:[0,1] neg_hi:[0,1]
	v_pk_add_f32 v[76:77], v[76:77], v[52:53] op_sel_hi:[1,0] neg_lo:[0,1] neg_hi:[0,1]
	v_pk_add_f32 v[44:45], v[44:45], v[52:53] op_sel_hi:[1,0] neg_lo:[0,1] neg_hi:[0,1]
	v_pk_add_f32 v[78:79], v[78:79], v[52:53] op_sel_hi:[1,0] neg_lo:[0,1] neg_hi:[0,1]
	v_pk_add_f32 v[46:47], v[46:47], v[52:53] op_sel_hi:[1,0] neg_lo:[0,1] neg_hi:[0,1]
	v_pk_add_f32 v[80:81], v[80:81], v[52:53] op_sel_hi:[1,0] neg_lo:[0,1] neg_hi:[0,1]
	v_pk_add_f32 v[48:49], v[48:49], v[52:53] op_sel_hi:[1,0] neg_lo:[0,1] neg_hi:[0,1]
	v_pk_mul_f32 v[16:17], v[16:17], v[54:55] op_sel_hi:[1,0]
	v_pk_mul_f32 v[14:15], v[14:15], v[54:55] op_sel_hi:[1,0]
	v_pk_mul_f32 v[12:13], v[12:13], v[54:55] op_sel_hi:[1,0]
	v_pk_mul_f32 v[10:11], v[10:11], v[54:55] op_sel_hi:[1,0]
	v_pk_mul_f32 v[8:9], v[8:9], v[54:55] op_sel_hi:[1,0]
	v_pk_mul_f32 v[6:7], v[6:7], v[54:55] op_sel_hi:[1,0]
	v_pk_mul_f32 v[4:5], v[4:5], v[54:55] op_sel_hi:[1,0]
	v_pk_mul_f32 v[2:3], v[2:3], v[54:55] op_sel_hi:[1,0]
	v_pk_mul_f32 v[32:33], v[32:33], v[54:55] op_sel_hi:[1,0]
	v_pk_mul_f32 v[30:31], v[30:31], v[54:55] op_sel_hi:[1,0]
	v_pk_mul_f32 v[28:29], v[28:29], v[54:55] op_sel_hi:[1,0]
	v_pk_mul_f32 v[26:27], v[26:27], v[54:55] op_sel_hi:[1,0]
	v_pk_mul_f32 v[24:25], v[24:25], v[54:55] op_sel_hi:[1,0]
	v_pk_mul_f32 v[22:23], v[22:23], v[54:55] op_sel_hi:[1,0]
	v_pk_mul_f32 v[20:21], v[20:21], v[54:55] op_sel_hi:[1,0]
	v_pk_mul_f32 v[18:19], v[18:19], v[54:55] op_sel_hi:[1,0]
	v_mul_f32_e32 v82, v82, v54
	v_mov_b32_e32 v51, v50
	v_mov_b32_e32 v52, v50
	v_mov_b32_e32 v53, v50
	v_mov_b32_e32 v54, v50
	v_mov_b32_e32 v55, v50
	v_mov_b32_e32 v56, v50
	v_mov_b32_e32 v57, v50
	v_mov_b32_e32 v58, v50
	v_mov_b32_e32 v59, v50
	v_mov_b32_e32 v60, v50
	v_mov_b32_e32 v61, v50
	v_mov_b32_e32 v62, v50
	v_mov_b32_e32 v63, v50
	v_mov_b32_e32 v64, v50
	v_mov_b32_e32 v65, v50
	s_branch .LBB0_601

; #define LAS __attribute__((address_space(3)))
; __device__ __forceinline__ unsigned cvtpk(float lo, float hi) { typedef __bf16 bf2 __attribute__((ext_vector_type(2))); f32x2 v = {lo, hi}; bf2 b = __builtin_convertvector(v, bf2); return __builtin_bit_cast(unsigned, b); }
; template <int DQK, int DV, bool BIAS> ...
;     ...
;     for (int g = 0; g < NG; ++g) {
;         const int pair = g & 1;
;     ...
;             float ls = 0.f;
; #pragma unroll
;             for (int hs = 0; hs < 4; ++hs) {
;                 float e[8];
; #pragma unroll
;                 for (int j = 0; j < 8; ++j) { e[j] = __builtin_amdgcn_exp2f(hs < 2 ? p0[8 * (hs & 1) + j] : p1[8 * (hs & 1) + j]); ls += e[j]; }
;                 pw[hs].x = cvtpk(e[0], e[1]); pw[hs].y = cvtpk(e[2], e[3]); pw[hs].z = cvtpk(e[4], e[5]); pw[hs].w = cvtpk(e[6], e[7]);
;                 const bf16x8 pbv = __builtin_bit_cast(bf16x8, pw[hs]);
; #pragma unroll
;                 for (int d = 0; d < NDT; ++d) { const LAS unsigned char* vp = vbase + d * 4096 + hs * 1024;
;                     const v4i16_t a0 = __builtin_amdgcn_ds_read_tr16_b64_v4i16((LAS v4i16_t*)vp), a1 = __builtin_amdgcn_ds_read_tr16_b64_v4i16((LAS v4i16_t*)(vp + 512));
;                     const bf16x8 av = {a0[0], a0[1], a0[2], a0[3], a1[0], a1[1], a1[2], a1[3]};
;                     o[d] = __builtin_amdgcn_mfma_f32_32x32x16_bf16(av, pbv, o[d], 0, 0, 0); }
;                 __builtin_amdgcn_sched_barrier(0);
;             }
;             l += ls;
.LBB0_631:
	s_nop 4
	v_exp_f32_e32 v83, v66
	v_exp_f32_e32 v88, v67
	v_exp_f32_e32 v89, v68
	v_exp_f32_e32 v90, v69
	v_exp_f32_e32 v91, v70
	v_exp_f32_e32 v92, v71
	ds_read_b64_tr_b16 v[66:67], v162 offset:24576
	ds_read_b64_tr_b16 v[68:69], v162 offset:25088
	v_exp_f32_e32 v93, v72
	v_exp_f32_e32 v94, v73
	ds_read_b64_tr_b16 v[84:85], v162 offset:28672
	ds_read_b64_tr_b16 v[86:87], v162 offset:29184
	v_cvt_pk_bf16_f32 v70, v83, v88
	v_cvt_pk_bf16_f32 v71, v89, v90
	v_cvt_pk_bf16_f32 v72, v91, v92
	v_cvt_pk_bf16_f32 v73, v93, v94
	s_add_i32 s46, s46, 2
	s_waitcnt lgkmcnt(2)
	v_mfma_f32_32x32x16_bf16 v[18:33], v[66:69], v[70:73], v[18:33]
	v_add_f32_e32 v66, v88, v83
	v_add_f32_e32 v66, v89, v66
	v_add_f32_e32 v66, v90, v66
	v_add_f32_e32 v66, v91, v66
	v_add_f32_e32 v66, v92, v66
	v_add_f32_e32 v66, v93, v66
	s_waitcnt lgkmcnt(0)
	v_mfma_f32_32x32x16_bf16 v[2:17], v[84:87], v[70:73], v[2:17]
	v_add_f32_e32 v83, v94, v66
	v_exp_f32_e32 v84, v74
	v_exp_f32_e32 v85, v75
	v_exp_f32_e32 v86, v76
	v_exp_f32_e32 v87, v77
	v_exp_f32_e32 v78, v78
	v_exp_f32_e32 v79, v79
	ds_read_b64_tr_b16 v[66:67], v162 offset:25600
	ds_read_b64_tr_b16 v[68:69], v162 offset:26112
	v_exp_f32_e32 v80, v80
	v_exp_f32_e32 v81, v81
	ds_read_b64_tr_b16 v[74:75], v162 offset:29696
	ds_read_b64_tr_b16 v[76:77], v162 offset:30208
	v_cvt_pk_bf16_f32 v70, v84, v85
	v_cvt_pk_bf16_f32 v71, v86, v87
	v_cvt_pk_bf16_f32 v72, v78, v79
	v_cvt_pk_bf16_f32 v73, v80, v81
	s_waitcnt lgkmcnt(2)
	s_nop 0
	v_mfma_f32_32x32x16_bf16 v[18:33], v[66:69], v[70:73], v[18:33]
	v_add_f32_e32 v66, v84, v83
	v_add_f32_e32 v66, v85, v66
	v_add_f32_e32 v66, v86, v66
	v_add_f32_e32 v66, v87, v66
	v_add_f32_e32 v66, v78, v66
	v_add_f32_e32 v66, v79, v66
	v_add_f32_e32 v66, v80, v66
	s_waitcnt lgkmcnt(0)
	v_mfma_f32_32x32x16_bf16 v[2:17], v[74:77], v[70:73], v[2:17]
	v_add_f32_e32 v70, v81, v66
	v_exp_f32_e32 v71, v34
	v_exp_f32_e32 v72, v35
	v_exp_f32_e32 v73, v36
	v_exp_f32_e32 v74, v37
	v_exp_f32_e32 v75, v38
	v_exp_f32_e32 v76, v39
	ds_read_b64_tr_b16 v[34:35], v162 offset:26624
	ds_read_b64_tr_b16 v[36:37], v162 offset:27136
	v_exp_f32_e32 v77, v40
	v_exp_f32_e32 v78, v41
	ds_read_b64_tr_b16 v[66:67], v162 offset:30720
	ds_read_b64_tr_b16 v[68:69], v162 offset:31232
	v_cvt_pk_bf16_f32 v38, v71, v72
	v_cvt_pk_bf16_f32 v39, v73, v74
	v_cvt_pk_bf16_f32 v40, v75, v76
	v_cvt_pk_bf16_f32 v41, v77, v78
	s_waitcnt lgkmcnt(2)
	s_nop 0
	v_mfma_f32_32x32x16_bf16 v[18:33], v[34:37], v[38:41], v[18:33]
	v_add_f32_e32 v34, v71, v70
	v_add_f32_e32 v34, v72, v34
	v_add_f32_e32 v34, v73, v34
	v_add_f32_e32 v34, v74, v34
	v_add_f32_e32 v34, v75, v34
	v_add_f32_e32 v34, v76, v34
	v_add_f32_e32 v34, v77, v34
	s_waitcnt lgkmcnt(0)
	v_mfma_f32_32x32x16_bf16 v[2:17], v[66:69], v[38:41], v[2:17]
	v_add_f32_e32 v66, v78, v34
	v_exp_f32_e32 v67, v42
	v_exp_f32_e32 v68, v43
	v_exp_f32_e32 v69, v44
	v_exp_f32_e32 v70, v45
	v_exp_f32_e32 v46, v46
	v_exp_f32_e32 v47, v47
	ds_read_b64_tr_b16 v[34:35], v162 offset:27648
	ds_read_b64_tr_b16 v[36:37], v162 offset:28160
	v_exp_f32_e32 v48, v48
	v_exp_f32_e32 v49, v49
	ds_read_b64_tr_b16 v[42:43], v162 offset:31744
	ds_read_b64_tr_b16 v[44:45], v162 offset:32256
	v_cvt_pk_bf16_f32 v38, v67, v68
	v_cvt_pk_bf16_f32 v39, v69, v70
	v_cvt_pk_bf16_f32 v40, v46, v47
	v_cvt_pk_bf16_f32 v41, v48, v49
	s_waitcnt lgkmcnt(2)
	s_nop 0
	v_mfma_f32_32x32x16_bf16 v[18:33], v[34:37], v[38:41], v[18:33]
	v_add_f32_e32 v34, v67, v66
	v_add_f32_e32 v34, v68, v34
	v_add_f32_e32 v34, v69, v34
	v_add_f32_e32 v34, v70, v34
	v_add_f32_e32 v34, v46, v34
	v_add_f32_e32 v34, v47, v34
	v_add_f32_e32 v34, v48, v34
	s_waitcnt lgkmcnt(0)
	v_mfma_f32_32x32x16_bf16 v[2:17], v[42:45], v[38:41], v[2:17]
	v_add_f32_e32 v34, v49, v34
	v_add_f32_e32 v164, v82, v34
	v_lshl_add_u64 v[154:155], v[154:155], 0, s[22:23]
	v_lshl_add_u64 v[156:157], v[156:157], 0, s[34:35]
	s_cmp_lg_u32 s46, 32
	v_lshl_add_u64 v[158:159], v[158:159], 0, s[34:35]
	s_cbranch_scc0 .LBB0_617

; template <int DQK, int DV, bool BIAS> ...
;     ...
;         __syncthreads();
;         if (g + 1 < NG) {
; #pragma unroll
;             for (int j = 0; j < TPB; ++j) ATT_STORE((pair ^ 1) * TPB + j, j);
;             if (g + 2 < NG) {
; #pragma unroll
;                 for (int j = 0; j < TPB; ++j) ATT_LOAD((g + 2) * TPB + j, j);
;             }
;         }
.LBB0_636:
	s_or_b64 exec, exec, s[40:41]
	s_cmp_lt_u32 s46, 30
	s_cselect_b64 s[40:41], -1, 0
	s_and_b64 vcc, exec, s[40:41]
	s_waitcnt vmcnt(0)
	ds_write_b128 v160, v[142:145] offset:24576
	s_cbranch_vccz .LBB0_642
	s_add_u32 s100, s16, 0x7d80000
	s_addc_u32 s101, s17, 0
	global_load_dwordx4 v[130:133], v156, s[100:101]
	s_and_saveexec_b64 s[42:43], s[6:7]
	s_cbranch_execz .LBB0_639
	s_add_u32 s100, s16, 0x195000
	s_addc_u32 s101, s17, 0
	global_load_dwordx4 v[122:125], v154, s[100:101] offset:1280
.LBB0_639:
	s_or_b64 exec, exec, s[42:43]
	s_add_u32 s100, s16, 0x7d80000
	s_addc_u32 s101, s17, 0
	global_load_dwordx4 v[134:137], v158, s[100:101] offset:128
	s_add_u32 s100, s16, 0x7da0000
	s_addc_u32 s101, s17, 0
	global_load_dwordx4 v[138:141], v156, s[100:101]
	s_and_saveexec_b64 s[42:43], s[6:7]
	s_cbranch_execz .LBB0_641
	s_add_u32 s100, s16, 0x1fa000
	s_addc_u32 s101, s17, 0
	global_load_dwordx4 v[126:129], v154, s[100:101] offset:1280
.LBB0_641:
	s_or_b64 exec, exec, s[42:43]
	s_add_u32 s100, s16, 0x7da0000
	s_addc_u32 s101, s17, 0
	global_load_dwordx4 v[142:145], v158, s[100:101] offset:128

; #define LAS __attribute__((address_space(3)))
; template <int DQK, int DV, bool BIAS> ...
;     ...
;         const LAS unsigned char* kb = lds + buf * KBUF + r32 * KP + hi * 16;
; #pragma unroll
;         for (int ks = 0; ks < NKS; ++ks) {
;             const bf16x8 k0 = *(const LAS bf16x8*)(kb + ks * 32), k1 = *(const LAS bf16x8*)(kb + 32 * KP + ks * 32);
;             if (ks == 0) { p0 = __builtin_amdgcn_mfma_f32_32x32x16_bf16(k0, qf[0], negm, 0, 0, 0); p1 = __builtin_amdgcn_mfma_f32_32x32x16_bf16(k1, qf[0], negm, 0, 0, 0); }
;             else { p0 = __builtin_amdgcn_mfma_f32_32x32x16_bf16(k0, qf[ks], p0, 0, 0, 0); p1 = __builtin_amdgcn_mfma_f32_32x32x16_bf16(k1, qf[ks], p1, 0, 0, 0); }
;         }
;         if (BIAS) {
;             asm volatile("s_nop 15\n\ts_nop 7" : "+v"(p0), "+v"(p1));
;             const float d0 = qp - (float)(t * 64 + 4 * hi);
; #pragma unroll
;             for (int r = 0; r < 16; ++r) { const float dk = d0 - (float)((r & 3) + 8 * (r >> 2)); p0[r] = p0[r] - sl2 * fabsf(dk); p1[r] = p1[r] - sl2 * fabsf(dk - 32.f); }
;         } else {
;             asm volatile("s_nop 15\n\ts_nop 7" : "+v"(p0), "+v"(p1));
;         }
;         float mxa = max3f(p0[0], p0[1], p1[0]), mxb = max3f(p0[2], p0[3], p1[1]); mxa = max3f(mxa, p1[2], p1[3]);
; #pragma unroll
;     ...
;             float ls = 0.f;
; #pragma unroll
;             for (int hs = 0; hs < 4; ++hs) {
;                 float e[8];
; #pragma unroll
;                 for (int j = 0; j < 8; ++j) { e[j] = __builtin_amdgcn_exp2f(hs < 2 ? p0[8 * (hs & 1) + j] : p1[8 * (hs & 1) + j]); ls += e[j]; }
;                 pw[hs].x = cvtpk(e[0], e[1]); pw[hs].y = cvtpk(e[2], e[3]); pw[hs].z = cvtpk(e[4], e[5]); pw[hs].w = cvtpk(e[6], e[7]);
;                 const bf16x8 pbv = __builtin_bit_cast(bf16x8, pw[hs]);
; #pragma unroll
;                 for (int d = 0; d < NDT; ++d) { const LAS unsigned char* vp = vbase + d * 4096 + hs * 1024;
;                     const v4i16_t a0 = __builtin_amdgcn_ds_read_tr16_b64_v4i16((LAS v4i16_t*)vp), a1 = __builtin_amdgcn_ds_read_tr16_b64_v4i16((LAS v4i16_t*)(vp + 512));
;                     const bf16x8 av = {a0[0], a0[1], a0[2], a0[3], a1[0], a1[1], a1[2], a1[3]};
;                     o[d] = __builtin_amdgcn_mfma_f32_32x32x16_bf16(av, pbv, o[d], 0, 0, 0); }
;                 __builtin_amdgcn_sched_barrier(0);
;             }
;             l += ls;
.LBB0_645:
	v_exp_f32_e32 v165, v82
	v_exp_f32_e32 v166, v83
	v_exp_f32_e32 v167, v84
	v_exp_f32_e32 v169, v85
	v_exp_f32_e32 v174, v86
	v_exp_f32_e32 v175, v87
	ds_read_b64_tr_b16 v[82:83], v161 offset:53248
	ds_read_b64_tr_b16 v[84:85], v161 offset:53760
	v_exp_f32_e32 v176, v88
	v_exp_f32_e32 v177, v89
	ds_read_b64_tr_b16 v[170:171], v161 offset:57344
	ds_read_b64_tr_b16 v[172:173], v161 offset:57856
	v_cvt_pk_bf16_f32 v86, v165, v166
	v_cvt_pk_bf16_f32 v87, v167, v169
	v_cvt_pk_bf16_f32 v88, v174, v175
	v_cvt_pk_bf16_f32 v89, v176, v177
	s_waitcnt lgkmcnt(2)
	s_nop 0
	v_mfma_f32_32x32x16_bf16 v[18:33], v[82:85], v[86:89], v[18:33]
	v_add_f32_e32 v82, v166, v165
	v_add_f32_e32 v82, v167, v82
	v_add_f32_e32 v82, v169, v82
	v_add_f32_e32 v82, v174, v82
	v_add_f32_e32 v82, v175, v82
	v_add_f32_e32 v82, v176, v82
	s_waitcnt lgkmcnt(0)
	v_mfma_f32_32x32x16_bf16 v[2:17], v[170:173], v[86:89], v[2:17]
	v_add_f32_e32 v165, v177, v82
	v_exp_f32_e32 v166, v90
	v_exp_f32_e32 v167, v91
	v_exp_f32_e32 v169, v92
	v_exp_f32_e32 v170, v93
	v_exp_f32_e32 v94, v94
	v_exp_f32_e32 v95, v95
	ds_read_b64_tr_b16 v[82:83], v161 offset:54272
	ds_read_b64_tr_b16 v[84:85], v161 offset:54784
	v_exp_f32_e32 v96, v96
	v_exp_f32_e32 v97, v97
	ds_read_b64_tr_b16 v[90:91], v161 offset:58368
	ds_read_b64_tr_b16 v[92:93], v161 offset:58880
	v_cvt_pk_bf16_f32 v86, v166, v167
	v_cvt_pk_bf16_f32 v87, v169, v170
	v_cvt_pk_bf16_f32 v88, v94, v95
	v_cvt_pk_bf16_f32 v89, v96, v97
	s_waitcnt lgkmcnt(2)
	s_nop 0
	v_mfma_f32_32x32x16_bf16 v[18:33], v[82:85], v[86:89], v[18:33]
	v_add_f32_e32 v82, v166, v165
	v_add_f32_e32 v82, v167, v82
	v_add_f32_e32 v82, v169, v82
	v_add_f32_e32 v82, v170, v82
	v_add_f32_e32 v82, v94, v82
	v_add_f32_e32 v82, v95, v82
	v_add_f32_e32 v82, v96, v82
	s_waitcnt lgkmcnt(0)
	v_mfma_f32_32x32x16_bf16 v[2:17], v[90:93], v[86:89], v[2:17]
	v_add_f32_e32 v86, v97, v82
	v_exp_f32_e32 v87, v66
	v_exp_f32_e32 v88, v67
	v_exp_f32_e32 v89, v68
	v_exp_f32_e32 v90, v69
	v_exp_f32_e32 v91, v70
	v_exp_f32_e32 v92, v71
	ds_read_b64_tr_b16 v[66:67], v161 offset:55296
	ds_read_b64_tr_b16 v[68:69], v161 offset:55808
	v_exp_f32_e32 v93, v72
	v_exp_f32_e32 v94, v73
	ds_read_b64_tr_b16 v[82:83], v161 offset:59392
	ds_read_b64_tr_b16 v[84:85], v161 offset:59904
	v_cvt_pk_bf16_f32 v70, v87, v88
	v_cvt_pk_bf16_f32 v71, v89, v90
	v_cvt_pk_bf16_f32 v72, v91, v92
	v_cvt_pk_bf16_f32 v73, v93, v94
	s_waitcnt lgkmcnt(2)
	s_nop 0
	v_mfma_f32_32x32x16_bf16 v[18:33], v[66:69], v[70:73], v[18:33]
	v_add_f32_e32 v66, v87, v86
	v_add_f32_e32 v66, v88, v66
	v_add_f32_e32 v66, v89, v66
	v_add_f32_e32 v66, v90, v66
	v_add_f32_e32 v66, v91, v66
	v_add_f32_e32 v66, v92, v66
	v_add_f32_e32 v66, v93, v66
	s_waitcnt lgkmcnt(0)
	v_mfma_f32_32x32x16_bf16 v[2:17], v[82:85], v[70:73], v[2:17]
	v_add_f32_e32 v82, v94, v66
	v_exp_f32_e32 v83, v74
	v_exp_f32_e32 v84, v75
	v_exp_f32_e32 v85, v76
	v_exp_f32_e32 v86, v77
	v_exp_f32_e32 v78, v78
	v_exp_f32_e32 v79, v79
	ds_read_b64_tr_b16 v[66:67], v161 offset:56320
	ds_read_b64_tr_b16 v[68:69], v161 offset:56832
	v_exp_f32_e32 v80, v80
	v_exp_f32_e32 v81, v81
	ds_read_b64_tr_b16 v[74:75], v161 offset:60416
	ds_read_b64_tr_b16 v[76:77], v161 offset:60928
	v_cvt_pk_bf16_f32 v70, v83, v84
	v_cvt_pk_bf16_f32 v71, v85, v86
	v_cvt_pk_bf16_f32 v72, v78, v79
	v_cvt_pk_bf16_f32 v73, v80, v81
	s_waitcnt lgkmcnt(2)
	s_nop 0
	v_mfma_f32_32x32x16_bf16 v[18:33], v[66:69], v[70:73], v[18:33]
	v_add_f32_e32 v66, v83, v82
	v_add_f32_e32 v66, v84, v66
	v_add_f32_e32 v66, v85, v66
	v_add_f32_e32 v66, v86, v66
	v_add_f32_e32 v66, v78, v66
	v_add_f32_e32 v66, v79, v66
	v_add_f32_e32 v66, v80, v66
	s_waitcnt lgkmcnt(0)
	v_mfma_f32_32x32x16_bf16 v[2:17], v[74:77], v[70:73], v[2:17]
	v_add_f32_e32 v165, v81, v66
	ds_read_b128 v[66:69], v148 offset:13312
	ds_read_b128 v[170:173], v148 offset:13344
	ds_read_b128 v[174:177], v148 offset:19968
	ds_read_b128 v[178:181], v148 offset:20000
	v_add_f32_e32 v164, v164, v165
	s_waitcnt lgkmcnt(3)
	v_mfma_f32_32x32x16_bf16 v[82:97], v[66:69], v[98:101], v[34:49]
	s_waitcnt lgkmcnt(1)
	v_mfma_f32_32x32x16_bf16 v[66:81], v[174:177], v[98:101], v[34:49]
	v_mfma_f32_32x32x16_bf16 v[82:97], v[170:173], v[102:105], v[82:97]
	ds_read_b128 v[170:173], v148 offset:13376
	ds_read_b128 v[174:177], v148 offset:13408
	s_waitcnt lgkmcnt(2)
	v_mfma_f32_32x32x16_bf16 v[66:81], v[178:181], v[102:105], v[66:81]
	s_waitcnt lgkmcnt(1)
	v_mfma_f32_32x32x16_bf16 v[82:97], v[170:173], v[106:109], v[82:97]
	ds_read_b128 v[170:173], v148 offset:20032
	ds_read_b128 v[178:181], v148 offset:20064
	s_waitcnt lgkmcnt(1)
	v_mfma_f32_32x32x16_bf16 v[66:81], v[170:173], v[106:109], v[66:81]
	v_mfma_f32_32x32x16_bf16 v[82:97], v[174:177], v[110:113], v[82:97]
	ds_read_b128 v[170:173], v148 offset:13440
	ds_read_b128 v[174:177], v148 offset:13472
	s_waitcnt lgkmcnt(2)
	v_mfma_f32_32x32x16_bf16 v[66:81], v[178:181], v[110:113], v[66:81]
	s_waitcnt lgkmcnt(1)
	v_mfma_f32_32x32x16_bf16 v[82:97], v[170:173], v[114:117], v[82:97]
	ds_read_b128 v[170:173], v148 offset:20096
	ds_read_b128 v[178:181], v148 offset:20128
	s_waitcnt lgkmcnt(1)
	v_mfma_f32_32x32x16_bf16 v[66:81], v[170:173], v[114:117], v[66:81]
	v_mfma_f32_32x32x16_bf16 v[82:97], v[174:177], v[118:121], v[82:97]
	s_waitcnt lgkmcnt(0)
	v_mfma_f32_32x32x16_bf16 v[66:81], v[178:181], v[118:121], v[66:81]
	s_nop 15
	s_nop 7
	s_nop 0
	v_max3_f32 v165, v82, v83, v66
	v_max3_f32 v166, v84, v85, v67
	v_max3_f32 v165, v165, v68, v69
	v_max3_f32 v166, v166, v88, v89
	v_max3_f32 v165, v165, v86, v87
	v_max3_f32 v166, v166, v72, v73
	v_max3_f32 v165, v165, v70, v71
	v_max3_f32 v166, v166, v92, v93
	v_max3_f32 v165, v165, v90, v91
	v_max3_f32 v166, v166, v76, v77
	v_max3_f32 v165, v165, v74, v75
	v_max3_f32 v166, v166, v96, v97
	v_max3_f32 v165, v165, v94, v95
	v_max3_f32 v166, v166, v80, v81
	v_max3_f32 v165, v165, v78, v79
	v_max_f32_e32 v165, v165, v166
	v_cmp_lt_f32_e32 vcc, s59, v165
	s_cbranch_vccz .LBB0_647
; template <int DQK, int DV, bool BIAS> ...
;     ...
;         if (__any(mx > 8.f)) {
;             mx = fmaxf(mx, __shfl_xor(mx, 32));
;             const float dl = fmaxf(mx, 0.f); mhat += dl;
;             const float f = __builtin_amdgcn_exp2f(-dl);
; #pragma unroll
;             for (int r = 0; r < 16; ++r) { p0[r] -= dl; p1[r] -= dl; negm[r] = -mhat; }
;             l *= f;
; #pragma unroll
;             for (int d = 0; d < NDT; ++d)
; #pragma unroll
;                 for (int r = 0; r < 16; ++r) o[d][r] *= f;
;         }
	ds_bpermute_b32 v34, v168, v165
	s_waitcnt lgkmcnt(0)
	v_max3_f32 v36, v165, v34, 0
	v_exp_f32_e64 v38, -v36
	v_add_f32_e32 v153, v153, v36
	v_xor_b32_e32 v34, 0x80000000, v153
	v_pk_add_f32 v[82:83], v[82:83], v[36:37] op_sel_hi:[1,0] neg_lo:[0,1] neg_hi:[0,1]
	v_pk_add_f32 v[66:67], v[66:67], v[36:37] op_sel_hi:[1,0] neg_lo:[0,1] neg_hi:[0,1]
	v_pk_add_f32 v[84:85], v[84:85], v[36:37] op_sel_hi:[1,0] neg_lo:[0,1] neg_hi:[0,1]
	v_pk_add_f32 v[68:69], v[68:69], v[36:37] op_sel_hi:[1,0] neg_lo:[0,1] neg_hi:[0,1]
	v_pk_add_f32 v[86:87], v[86:87], v[36:37] op_sel_hi:[1,0] neg_lo:[0,1] neg_hi:[0,1]
	v_pk_add_f32 v[70:71], v[70:71], v[36:37] op_sel_hi:[1,0] neg_lo:[0,1] neg_hi:[0,1]
	v_pk_add_f32 v[88:89], v[88:89], v[36:37] op_sel_hi:[1,0] neg_lo:[0,1] neg_hi:[0,1]
	v_pk_add_f32 v[72:73], v[72:73], v[36:37] op_sel_hi:[1,0] neg_lo:[0,1] neg_hi:[0,1]
	v_pk_add_f32 v[90:91], v[90:91], v[36:37] op_sel_hi:[1,0] neg_lo:[0,1] neg_hi:[0,1]
	v_pk_add_f32 v[74:75], v[74:75], v[36:37] op_sel_hi:[1,0] neg_lo:[0,1] neg_hi:[0,1]
	v_pk_add_f32 v[92:93], v[92:93], v[36:37] op_sel_hi:[1,0] neg_lo:[0,1] neg_hi:[0,1]
	v_pk_add_f32 v[76:77], v[76:77], v[36:37] op_sel_hi:[1,0] neg_lo:[0,1] neg_hi:[0,1]
	v_pk_add_f32 v[94:95], v[94:95], v[36:37] op_sel_hi:[1,0] neg_lo:[0,1] neg_hi:[0,1]
	v_pk_add_f32 v[78:79], v[78:79], v[36:37] op_sel_hi:[1,0] neg_lo:[0,1] neg_hi:[0,1]
	v_pk_add_f32 v[96:97], v[96:97], v[36:37] op_sel_hi:[1,0] neg_lo:[0,1] neg_hi:[0,1]
	v_pk_add_f32 v[80:81], v[80:81], v[36:37] op_sel_hi:[1,0] neg_lo:[0,1] neg_hi:[0,1]
	v_pk_mul_f32 v[32:33], v[32:33], v[38:39] op_sel_hi:[1,0]
	v_pk_mul_f32 v[30:31], v[30:31], v[38:39] op_sel_hi:[1,0]
	v_pk_mul_f32 v[28:29], v[28:29], v[38:39] op_sel_hi:[1,0]
	v_pk_mul_f32 v[26:27], v[26:27], v[38:39] op_sel_hi:[1,0]
	v_pk_mul_f32 v[24:25], v[24:25], v[38:39] op_sel_hi:[1,0]
	v_pk_mul_f32 v[22:23], v[22:23], v[38:39] op_sel_hi:[1,0]
	v_pk_mul_f32 v[20:21], v[20:21], v[38:39] op_sel_hi:[1,0]
	v_pk_mul_f32 v[18:19], v[18:19], v[38:39] op_sel_hi:[1,0]
	v_pk_mul_f32 v[16:17], v[16:17], v[38:39] op_sel_hi:[1,0]
	v_pk_mul_f32 v[14:15], v[14:15], v[38:39] op_sel_hi:[1,0]
	v_pk_mul_f32 v[12:13], v[12:13], v[38:39] op_sel_hi:[1,0]
	v_pk_mul_f32 v[10:11], v[10:11], v[38:39] op_sel_hi:[1,0]
	v_pk_mul_f32 v[8:9], v[8:9], v[38:39] op_sel_hi:[1,0]
	v_pk_mul_f32 v[6:7], v[6:7], v[38:39] op_sel_hi:[1,0]
	v_pk_mul_f32 v[4:5], v[4:5], v[38:39] op_sel_hi:[1,0]
	v_pk_mul_f32 v[2:3], v[2:3], v[38:39] op_sel_hi:[1,0]
	v_mul_f32_e32 v164, v164, v38
	v_mov_b32_e32 v35, v34
	v_mov_b32_e32 v36, v34
	v_mov_b32_e32 v37, v34
	v_mov_b32_e32 v38, v34
	v_mov_b32_e32 v39, v34
	v_mov_b32_e32 v40, v34
	v_mov_b32_e32 v41, v34
	v_mov_b32_e32 v42, v34
	v_mov_b32_e32 v43, v34
	v_mov_b32_e32 v44, v34
	v_mov_b32_e32 v45, v34
	v_mov_b32_e32 v46, v34
	v_mov_b32_e32 v47, v34
	v_mov_b32_e32 v48, v34
	v_mov_b32_e32 v49, v34
	v_mov_b32_e32 v50, v34
	v_mov_b32_e32 v51, v34
	v_mov_b32_e32 v52, v34
	v_mov_b32_e32 v53, v34
	v_mov_b32_e32 v54, v34
	v_mov_b32_e32 v55, v34
	v_mov_b32_e32 v56, v34
	v_mov_b32_e32 v57, v34
	v_mov_b32_e32 v58, v34
	v_mov_b32_e32 v59, v34
	v_mov_b32_e32 v60, v34
	v_mov_b32_e32 v61, v34
	v_mov_b32_e32 v62, v34
	v_mov_b32_e32 v63, v34
	v_mov_b32_e32 v64, v34
	v_mov_b32_e32 v65, v34

; #define LAS __attribute__((address_space(3)))
; __device__ __forceinline__ float max3f(float a, float b, float c) { float r; asm("v_max3_f32 %0, %1, %2, %3" : "=v"(r) : "v"(a), "v"(b), "v"(c)); return r; }
; template <int DQK, int DV, bool BIAS> ...
;     ...
; #pragma unroll
;       for (int sub = 0; sub < TPB; ++sub) {
;         const int t = g * TPB + sub, buf = pair * TPB + sub, vcur = buf;
;         f32x16 p0, p1;
;         const LAS unsigned char* kb = lds + buf * KBUF + r32 * KP + hi * 16;
; #pragma unroll
;         for (int ks = 0; ks < NKS; ++ks) {
;             const bf16x8 k0 = *(const LAS bf16x8*)(kb + ks * 32), k1 = *(const LAS bf16x8*)(kb + 32 * KP + ks * 32);
;             if (ks == 0) { p0 = __builtin_amdgcn_mfma_f32_32x32x16_bf16(k0, qf[0], negm, 0, 0, 0); p1 = __builtin_amdgcn_mfma_f32_32x32x16_bf16(k1, qf[0], negm, 0, 0, 0); }
;             else { p0 = __builtin_amdgcn_mfma_f32_32x32x16_bf16(k0, qf[ks], p0, 0, 0, 0); p1 = __builtin_amdgcn_mfma_f32_32x32x16_bf16(k1, qf[ks], p1, 0, 0, 0); }
;         }
;         if (BIAS) {
;             asm volatile("s_nop 15\n\ts_nop 7" : "+v"(p0), "+v"(p1));
;             const float d0 = qp - (float)(t * 64 + 4 * hi);
; #pragma unroll
;             for (int r = 0; r < 16; ++r) { const float dk = d0 - (float)((r & 3) + 8 * (r >> 2)); p0[r] = p0[r] - sl2 * fabsf(dk); p1[r] = p1[r] - sl2 * fabsf(dk - 32.f); }
;         } else {
;             asm volatile("s_nop 15\n\ts_nop 7" : "+v"(p0), "+v"(p1));
;         }
;         float mxa = max3f(p0[0], p0[1], p1[0]), mxb = max3f(p0[2], p0[3], p1[1]); mxa = max3f(mxa, p1[2], p1[3]);
; #pragma unroll
;         for (int r = 4; r < 16; r += 4) { mxa = max3f(mxa, p0[r], p0[r + 1]); mxb = max3f(mxb, p0[r + 2], p0[r + 3]); mxa = max3f(mxa, p1[r], p1[r + 1]); mxb = max3f(mxb, p1[r + 2], p1[r + 3]); }
;         float mx = fmaxf(mxa, mxb);
;         if (__any(mx > 8.f)) {
;             mx = fmaxf(mx, __shfl_xor(mx, 32));
;             const float dl = fmaxf(mx, 0.f); mhat += dl;
;             const float f = __builtin_amdgcn_exp2f(-dl);
; #pragma unroll
;             for (int r = 0; r < 16; ++r) { p0[r] -= dl; p1[r] -= dl; negm[r] = -mhat; }
.LBB0_653:
	s_add_u32 s100, s16, 0x7dc0000
	s_addc_u32 s101, s17, 0
	global_load_dwordx4 v[130:133], v156, s[100:101]
	s_and_saveexec_b64 s[40:41], s[6:7]
	s_cbranch_execz .LBB0_655
	s_add_u32 s100, s16, 0x25f000
	s_addc_u32 s101, s17, 0
	global_load_dwordx4 v[122:125], v154, s[100:101] offset:1280
.LBB0_655:
	s_or_b64 exec, exec, s[40:41]
	s_add_u32 s100, s16, 0x7dc0000
	s_addc_u32 s101, s17, 0
	global_load_dwordx4 v[134:137], v158, s[100:101] offset:128
	s_add_u32 s100, s16, 0x7de0000
	s_addc_u32 s101, s17, 0
	global_load_dwordx4 v[138:141], v156, s[100:101]
	s_and_saveexec_b64 s[40:41], s[6:7]
	s_cbranch_execz .LBB0_657
	s_add_u32 s100, s16, 0x2c4000
	s_addc_u32 s101, s17, 0
	global_load_dwordx4 v[126:129], v154, s[100:101] offset:1280
.LBB0_657:
	s_or_b64 exec, exec, s[40:41]
	s_add_u32 s100, s16, 0x7de0000
	s_addc_u32 s101, s17, 0
	global_load_dwordx4 v[142:145], v158, s[100:101] offset:128
.LBB0_658:
	ds_read_b128 v[66:69], v148 offset:26624
	ds_read_b128 v[198:201], v148 offset:26656
	ds_read_b128 v[202:205], v148 offset:33280
	ds_read_b128 v[206:209], v148 offset:33312
	v_add_f32_e32 v170, v171, v170
	s_waitcnt lgkmcnt(3)
	v_mfma_f32_32x32x16_bf16 v[82:97], v[66:69], v[98:101], v[34:49]
	v_add_f32_e32 v165, v165, v170
	v_add_f32_e32 v165, v166, v165
	v_add_f32_e32 v165, v167, v165
	v_add_f32_e32 v165, v169, v165
	v_add_f32_e32 v165, v172, v165
	v_add_f32_e32 v165, v173, v165
	v_add_f32_e32 v165, v175, v165
	s_waitcnt lgkmcnt(1)
	v_mfma_f32_32x32x16_bf16 v[66:81], v[202:205], v[98:101], v[34:49]
	v_add_f32_e32 v165, v176, v165
	v_add_f32_e32 v165, v177, v165
	v_add_f32_e32 v165, v178, v165
	v_add_f32_e32 v165, v179, v165
	v_add_f32_e32 v165, v174, v165
	v_add_f32_e32 v165, v180, v165
	v_add_f32_e32 v165, v181, v165
	v_mfma_f32_32x32x16_bf16 v[82:97], v[198:201], v[102:105], v[82:97]
	ds_read_b128 v[198:201], v148 offset:26688
	ds_read_b128 v[202:205], v148 offset:26720
	v_add_f32_e32 v165, v185, v165
	v_add_f32_e32 v165, v186, v165
	v_add_f32_e32 v165, v187, v165
	v_add_f32_e32 v165, v182, v165
	v_add_f32_e32 v165, v183, v165
	v_add_f32_e32 v165, v184, v165
	s_waitcnt lgkmcnt(2)
	v_mfma_f32_32x32x16_bf16 v[66:81], v[206:209], v[102:105], v[66:81]
	v_add_f32_e32 v165, v188, v165
	v_add_f32_e32 v165, v189, v165
	v_add_f32_e32 v165, v194, v165
	v_add_f32_e32 v165, v195, v165
	v_add_f32_e32 v165, v190, v165
	v_add_f32_e32 v165, v191, v165
	v_add_f32_e32 v165, v192, v165
	s_waitcnt lgkmcnt(1)
	v_mfma_f32_32x32x16_bf16 v[82:97], v[198:201], v[106:109], v[82:97]
	ds_read_b128 v[198:201], v148 offset:33344
	ds_read_b128 v[206:209], v148 offset:33376
	ds_read_b128 v[170:173], v148 offset:26752
	v_add_f32_e32 v165, v193, v165
	v_add_f32_e32 v165, v196, v165
	v_add_f32_e32 v165, v197, v165
	v_add_f32_e32 v164, v164, v165
	s_waitcnt lgkmcnt(2)
	v_mfma_f32_32x32x16_bf16 v[66:81], v[198:201], v[106:109], v[66:81]
	ds_read_b128 v[176:179], v148 offset:33408
	ds_read_b128 v[198:201], v148 offset:26784
	v_mfma_f32_32x32x16_bf16 v[82:97], v[202:205], v[110:113], v[82:97]
	s_waitcnt lgkmcnt(3)
	v_mfma_f32_32x32x16_bf16 v[66:81], v[206:209], v[110:113], v[66:81]
	s_waitcnt lgkmcnt(2)
	v_mfma_f32_32x32x16_bf16 v[82:97], v[170:173], v[114:117], v[82:97]
	ds_read_b128 v[170:173], v148 offset:33440
	s_waitcnt lgkmcnt(2)
	v_mfma_f32_32x32x16_bf16 v[66:81], v[176:179], v[114:117], v[66:81]
	s_waitcnt lgkmcnt(1)
	v_mfma_f32_32x32x16_bf16 v[82:97], v[198:201], v[118:121], v[82:97]
	s_waitcnt lgkmcnt(0)
	v_mfma_f32_32x32x16_bf16 v[66:81], v[170:173], v[118:121], v[66:81]
	s_nop 15
	s_nop 7
	s_nop 0
	v_max3_f32 v165, v82, v83, v66
	v_max3_f32 v166, v84, v85, v67
	v_max3_f32 v165, v165, v68, v69
	v_max3_f32 v166, v166, v88, v89
	v_max3_f32 v165, v165, v86, v87
	v_max3_f32 v166, v166, v72, v73
	v_max3_f32 v165, v165, v70, v71
	v_max3_f32 v166, v166, v92, v93
	v_max3_f32 v165, v165, v90, v91
	v_max3_f32 v166, v166, v76, v77
	v_max3_f32 v165, v165, v74, v75
	v_max3_f32 v166, v166, v96, v97
	v_max3_f32 v165, v165, v94, v95
	v_max3_f32 v166, v166, v80, v81
	v_max3_f32 v165, v165, v78, v79
	v_max_f32_e32 v165, v165, v166
	v_cmp_lt_f32_e32 vcc, s59, v165
	s_cbranch_vccz .LBB0_660
	ds_bpermute_b32 v34, v168, v165
	s_waitcnt lgkmcnt(0)
	v_max3_f32 v36, v165, v34, 0
	v_exp_f32_e64 v38, -v36
	v_add_f32_e32 v153, v153, v36
	v_xor_b32_e32 v34, 0x80000000, v153
	v_pk_add_f32 v[82:83], v[82:83], v[36:37] op_sel_hi:[1,0] neg_lo:[0,1] neg_hi:[0,1]
	v_pk_add_f32 v[66:67], v[66:67], v[36:37] op_sel_hi:[1,0] neg_lo:[0,1] neg_hi:[0,1]
	v_pk_add_f32 v[84:85], v[84:85], v[36:37] op_sel_hi:[1,0] neg_lo:[0,1] neg_hi:[0,1]
	v_pk_add_f32 v[68:69], v[68:69], v[36:37] op_sel_hi:[1,0] neg_lo:[0,1] neg_hi:[0,1]
	v_pk_add_f32 v[86:87], v[86:87], v[36:37] op_sel_hi:[1,0] neg_lo:[0,1] neg_hi:[0,1]
	v_pk_add_f32 v[70:71], v[70:71], v[36:37] op_sel_hi:[1,0] neg_lo:[0,1] neg_hi:[0,1]
	v_pk_add_f32 v[88:89], v[88:89], v[36:37] op_sel_hi:[1,0] neg_lo:[0,1] neg_hi:[0,1]
	v_pk_add_f32 v[72:73], v[72:73], v[36:37] op_sel_hi:[1,0] neg_lo:[0,1] neg_hi:[0,1]
	v_pk_add_f32 v[90:91], v[90:91], v[36:37] op_sel_hi:[1,0] neg_lo:[0,1] neg_hi:[0,1]
	v_pk_add_f32 v[74:75], v[74:75], v[36:37] op_sel_hi:[1,0] neg_lo:[0,1] neg_hi:[0,1]
	v_pk_add_f32 v[92:93], v[92:93], v[36:37] op_sel_hi:[1,0] neg_lo:[0,1] neg_hi:[0,1]
	v_pk_add_f32 v[76:77], v[76:77], v[36:37] op_sel_hi:[1,0] neg_lo:[0,1] neg_hi:[0,1]
	v_pk_add_f32 v[94:95], v[94:95], v[36:37] op_sel_hi:[1,0] neg_lo:[0,1] neg_hi:[0,1]
	v_pk_add_f32 v[78:79], v[78:79], v[36:37] op_sel_hi:[1,0] neg_lo:[0,1] neg_hi:[0,1]
	v_pk_add_f32 v[96:97], v[96:97], v[36:37] op_sel_hi:[1,0] neg_lo:[0,1] neg_hi:[0,1]
	v_pk_add_f32 v[80:81], v[80:81], v[36:37] op_sel_hi:[1,0] neg_lo:[0,1] neg_hi:[0,1]
; #define LAS __attribute__((address_space(3)))
; __device__ __forceinline__ unsigned cvtpk(float lo, float hi) { typedef __bf16 bf2 __attribute__((ext_vector_type(2))); f32x2 v = {lo, hi}; bf2 b = __builtin_convertvector(v, bf2); return __builtin_bit_cast(unsigned, b); }
; template <int DQK, int DV, bool BIAS> ...
;     ...
;         if (__any(mx > 8.f)) {
;             mx = fmaxf(mx, __shfl_xor(mx, 32));
;             const float dl = fmaxf(mx, 0.f); mhat += dl;
;             const float f = __builtin_amdgcn_exp2f(-dl);
; #pragma unroll
;             for (int r = 0; r < 16; ++r) { p0[r] -= dl; p1[r] -= dl; negm[r] = -mhat; }
;             l *= f;
; #pragma unroll
;             for (int d = 0; d < NDT; ++d)
; #pragma unroll
;                 for (int r = 0; r < 16; ++r) o[d][r] *= f;
;         }
;         if (!isY) {
;             const LAS unsigned char* vbase = lds + VOFF + vcur * VBUF + (4 * hi + ((lane & 15) >> 2)) * 64 + ((lane >> 4) & 1) * 32 + (lane & 3) * 8;
;             float ls = 0.f;
; #pragma unroll
;             for (int hs = 0; hs < 4; ++hs) {
;                 float e[8];
; #pragma unroll
;                 for (int j = 0; j < 8; ++j) { e[j] = __builtin_amdgcn_exp2f(hs < 2 ? p0[8 * (hs & 1) + j] : p1[8 * (hs & 1) + j]); ls += e[j]; }
;                 pw[hs].x = cvtpk(e[0], e[1]); pw[hs].y = cvtpk(e[2], e[3]); pw[hs].z = cvtpk(e[4], e[5]); pw[hs].w = cvtpk(e[6], e[7]);
;                 const bf16x8 pbv = __builtin_bit_cast(bf16x8, pw[hs]);
; #pragma unroll
;                 for (int d = 0; d < NDT; ++d) { const LAS unsigned char* vp = vbase + d * 4096 + hs * 1024;
;                     const v4i16_t a0 = __builtin_amdgcn_ds_read_tr16_b64_v4i16((LAS v4i16_t*)vp), a1 = __builtin_amdgcn_ds_read_tr16_b64_v4i16((LAS v4i16_t*)(vp + 512));
;                     const bf16x8 av = {a0[0], a0[1], a0[2], a0[3], a1[0], a1[1], a1[2], a1[3]};
;                     o[d] = __builtin_amdgcn_mfma_f32_32x32x16_bf16(av, pbv, o[d], 0, 0, 0); }
;                 __builtin_amdgcn_sched_barrier(0);
;             }
;             l += ls;
	v_pk_mul_f32 v[32:33], v[32:33], v[38:39] op_sel_hi:[1,0]
	v_pk_mul_f32 v[30:31], v[30:31], v[38:39] op_sel_hi:[1,0]
	v_pk_mul_f32 v[28:29], v[28:29], v[38:39] op_sel_hi:[1,0]
	v_pk_mul_f32 v[26:27], v[26:27], v[38:39] op_sel_hi:[1,0]
	v_pk_mul_f32 v[24:25], v[24:25], v[38:39] op_sel_hi:[1,0]
	v_pk_mul_f32 v[22:23], v[22:23], v[38:39] op_sel_hi:[1,0]
	v_pk_mul_f32 v[20:21], v[20:21], v[38:39] op_sel_hi:[1,0]
	v_pk_mul_f32 v[18:19], v[18:19], v[38:39] op_sel_hi:[1,0]
	v_pk_mul_f32 v[16:17], v[16:17], v[38:39] op_sel_hi:[1,0]
	v_pk_mul_f32 v[14:15], v[14:15], v[38:39] op_sel_hi:[1,0]
	v_pk_mul_f32 v[12:13], v[12:13], v[38:39] op_sel_hi:[1,0]
	v_pk_mul_f32 v[10:11], v[10:11], v[38:39] op_sel_hi:[1,0]
	v_pk_mul_f32 v[8:9], v[8:9], v[38:39] op_sel_hi:[1,0]
	v_pk_mul_f32 v[6:7], v[6:7], v[38:39] op_sel_hi:[1,0]
	v_pk_mul_f32 v[4:5], v[4:5], v[38:39] op_sel_hi:[1,0]
	v_pk_mul_f32 v[2:3], v[2:3], v[38:39] op_sel_hi:[1,0]
	v_mul_f32_e32 v164, v164, v38
	v_mov_b32_e32 v35, v34
	v_mov_b32_e32 v36, v34
	v_mov_b32_e32 v37, v34
	v_mov_b32_e32 v38, v34
	v_mov_b32_e32 v39, v34
	v_mov_b32_e32 v40, v34
	v_mov_b32_e32 v41, v34
	v_mov_b32_e32 v42, v34
	v_mov_b32_e32 v43, v34
	v_mov_b32_e32 v44, v34
	v_mov_b32_e32 v45, v34
	v_mov_b32_e32 v46, v34
	v_mov_b32_e32 v47, v34
	v_mov_b32_e32 v48, v34
	v_mov_b32_e32 v49, v34
	v_mov_b32_e32 v50, v34
	v_mov_b32_e32 v51, v34
	v_mov_b32_e32 v52, v34
	v_mov_b32_e32 v53, v34
	v_mov_b32_e32 v54, v34
	v_mov_b32_e32 v55, v34
	v_mov_b32_e32 v56, v34
	v_mov_b32_e32 v57, v34
	v_mov_b32_e32 v58, v34
	v_mov_b32_e32 v59, v34
	v_mov_b32_e32 v60, v34
	v_mov_b32_e32 v61, v34
	v_mov_b32_e32 v62, v34
	v_mov_b32_e32 v63, v34
	v_mov_b32_e32 v64, v34
	v_mov_b32_e32 v65, v34
.LBB0_660:
	v_exp_f32_e32 v165, v82
	v_exp_f32_e32 v166, v83
	v_exp_f32_e32 v167, v84
	v_exp_f32_e32 v169, v85
	v_exp_f32_e32 v174, v86
	v_exp_f32_e32 v175, v87
	ds_read_b64_tr_b16 v[82:83], v162 offset:16384
	ds_read_b64_tr_b16 v[84:85], v162 offset:16896
	v_exp_f32_e32 v176, v88
	v_exp_f32_e32 v177, v89
	ds_read_b64_tr_b16 v[170:171], v162 offset:20480
	ds_read_b64_tr_b16 v[172:173], v162 offset:20992
	v_cvt_pk_bf16_f32 v86, v165, v166
	v_cvt_pk_bf16_f32 v87, v167, v169
	v_cvt_pk_bf16_f32 v88, v174, v175
	v_cvt_pk_bf16_f32 v89, v176, v177
	s_waitcnt lgkmcnt(2)
	s_nop 0
	v_mfma_f32_32x32x16_bf16 v[18:33], v[82:85], v[86:89], v[18:33]
	v_add_f32_e32 v82, v166, v165
	v_add_f32_e32 v82, v167, v82
	v_add_f32_e32 v82, v169, v82
	v_add_f32_e32 v82, v174, v82
	v_add_f32_e32 v82, v175, v82
	v_add_f32_e32 v82, v176, v82
	s_waitcnt lgkmcnt(0)
	v_mfma_f32_32x32x16_bf16 v[2:17], v[170:173], v[86:89], v[2:17]
	v_add_f32_e32 v165, v177, v82
	v_exp_f32_e32 v166, v90
	v_exp_f32_e32 v167, v91
	v_exp_f32_e32 v169, v92
	v_exp_f32_e32 v170, v93
	v_exp_f32_e32 v94, v94
	v_exp_f32_e32 v95, v95
	ds_read_b64_tr_b16 v[82:83], v162 offset:17408
	ds_read_b64_tr_b16 v[84:85], v162 offset:17920
	v_exp_f32_e32 v96, v96
	v_exp_f32_e32 v97, v97
	ds_read_b64_tr_b16 v[90:91], v162 offset:21504
	ds_read_b64_tr_b16 v[92:93], v162 offset:22016
	v_cvt_pk_bf16_f32 v86, v166, v167
	v_cvt_pk_bf16_f32 v87, v169, v170
	v_cvt_pk_bf16_f32 v88, v94, v95
	v_cvt_pk_bf16_f32 v89, v96, v97
	s_waitcnt lgkmcnt(2)
	s_nop 0
	v_mfma_f32_32x32x16_bf16 v[18:33], v[82:85], v[86:89], v[18:33]
	v_add_f32_e32 v82, v166, v165
	v_add_f32_e32 v82, v167, v82
	v_add_f32_e32 v82, v169, v82
	v_add_f32_e32 v82, v170, v82
	v_add_f32_e32 v82, v94, v82
	v_add_f32_e32 v82, v95, v82
	v_add_f32_e32 v82, v96, v82
	s_waitcnt lgkmcnt(0)
	v_mfma_f32_32x32x16_bf16 v[2:17], v[90:93], v[86:89], v[2:17]
	v_add_f32_e32 v86, v97, v82
	v_exp_f32_e32 v87, v66
	v_exp_f32_e32 v88, v67
	v_exp_f32_e32 v89, v68
	v_exp_f32_e32 v90, v69
	v_exp_f32_e32 v91, v70
	v_exp_f32_e32 v92, v71
	ds_read_b64_tr_b16 v[66:67], v162 offset:18432
	ds_read_b64_tr_b16 v[68:69], v162 offset:18944
	v_exp_f32_e32 v93, v72
	v_exp_f32_e32 v94, v73
	ds_read_b64_tr_b16 v[82:83], v162 offset:22528
	ds_read_b64_tr_b16 v[84:85], v162 offset:23040
	v_cvt_pk_bf16_f32 v70, v87, v88
	v_cvt_pk_bf16_f32 v71, v89, v90
	v_cvt_pk_bf16_f32 v72, v91, v92
	v_cvt_pk_bf16_f32 v73, v93, v94
	s_waitcnt lgkmcnt(2)
	s_nop 0
	v_mfma_f32_32x32x16_bf16 v[18:33], v[66:69], v[70:73], v[18:33]
	v_add_f32_e32 v66, v87, v86
	v_add_f32_e32 v66, v88, v66
	v_add_f32_e32 v66, v89, v66
	v_add_f32_e32 v66, v90, v66
	v_add_f32_e32 v66, v91, v66
	v_add_f32_e32 v66, v92, v66
	v_add_f32_e32 v66, v93, v66
	s_waitcnt lgkmcnt(0)
	v_mfma_f32_32x32x16_bf16 v[2:17], v[82:85], v[70:73], v[2:17]
	v_add_f32_e32 v82, v94, v66
	v_exp_f32_e32 v83, v74
	v_exp_f32_e32 v84, v75
	v_exp_f32_e32 v85, v76
	v_exp_f32_e32 v86, v77
	v_exp_f32_e32 v78, v78
	v_exp_f32_e32 v79, v79
	ds_read_b64_tr_b16 v[66:67], v162 offset:19456
	ds_read_b64_tr_b16 v[68:69], v162 offset:19968
	v_exp_f32_e32 v80, v80
	v_exp_f32_e32 v81, v81
	ds_read_b64_tr_b16 v[74:75], v162 offset:23552
	ds_read_b64_tr_b16 v[76:77], v162 offset:24064
	v_cvt_pk_bf16_f32 v70, v83, v84
	v_cvt_pk_bf16_f32 v71, v85, v86
	v_cvt_pk_bf16_f32 v72, v78, v79
	v_cvt_pk_bf16_f32 v73, v80, v81
	s_waitcnt lgkmcnt(2)
	s_nop 0
	v_mfma_f32_32x32x16_bf16 v[18:33], v[66:69], v[70:73], v[18:33]
	v_add_f32_e32 v66, v83, v82
	v_add_f32_e32 v66, v84, v66
	v_add_f32_e32 v66, v85, v66
	v_add_f32_e32 v66, v86, v66
	v_add_f32_e32 v66, v78, v66
	v_add_f32_e32 v66, v79, v66
	v_add_f32_e32 v66, v80, v66
	s_waitcnt lgkmcnt(0)
; #define LAS __attribute__((address_space(3)))
; __device__ __forceinline__ float max3f(float a, float b, float c) { float r; asm("v_max3_f32 %0, %1, %2, %3" : "=v"(r) : "v"(a), "v"(b), "v"(c)); return r; }
; template <int DQK, int DV, bool BIAS> ...
;     ...
; #pragma unroll
;       for (int sub = 0; sub < TPB; ++sub) {
;         const int t = g * TPB + sub, buf = pair * TPB + sub, vcur = buf;
;         f32x16 p0, p1;
;         const LAS unsigned char* kb = lds + buf * KBUF + r32 * KP + hi * 16;
; #pragma unroll
;         for (int ks = 0; ks < NKS; ++ks) {
;             const bf16x8 k0 = *(const LAS bf16x8*)(kb + ks * 32), k1 = *(const LAS bf16x8*)(kb + 32 * KP + ks * 32);
;             if (ks == 0) { p0 = __builtin_amdgcn_mfma_f32_32x32x16_bf16(k0, qf[0], negm, 0, 0, 0); p1 = __builtin_amdgcn_mfma_f32_32x32x16_bf16(k1, qf[0], negm, 0, 0, 0); }
;             else { p0 = __builtin_amdgcn_mfma_f32_32x32x16_bf16(k0, qf[ks], p0, 0, 0, 0); p1 = __builtin_amdgcn_mfma_f32_32x32x16_bf16(k1, qf[ks], p1, 0, 0, 0); }
;         }
;         if (BIAS) {
;             asm volatile("s_nop 15\n\ts_nop 7" : "+v"(p0), "+v"(p1));
;             const float d0 = qp - (float)(t * 64 + 4 * hi);
; #pragma unroll
;             for (int r = 0; r < 16; ++r) { const float dk = d0 - (float)((r & 3) + 8 * (r >> 2)); p0[r] = p0[r] - sl2 * fabsf(dk); p1[r] = p1[r] - sl2 * fabsf(dk - 32.f); }
;         } else {
;             asm volatile("s_nop 15\n\ts_nop 7" : "+v"(p0), "+v"(p1));
;         }
;         float mxa = max3f(p0[0], p0[1], p1[0]), mxb = max3f(p0[2], p0[3], p1[1]); mxa = max3f(mxa, p1[2], p1[3]);
; #pragma unroll
;         for (int r = 4; r < 16; r += 4) { mxa = max3f(mxa, p0[r], p0[r + 1]); mxb = max3f(mxb, p0[r + 2], p0[r + 3]); mxa = max3f(mxa, p1[r], p1[r + 1]); mxb = max3f(mxb, p1[r + 2], p1[r + 3]); }
;         float mx = fmaxf(mxa, mxb);
;         if (__any(mx > 8.f)) {
;             mx = fmaxf(mx, __shfl_xor(mx, 32));
;             const float dl = fmaxf(mx, 0.f); mhat += dl;
;             const float f = __builtin_amdgcn_exp2f(-dl);
; #pragma unroll
;             for (int r = 0; r < 16; ++r) { p0[r] -= dl; p1[r] -= dl; negm[r] = -mhat; }
;             l *= f;
; #pragma unroll
;             for (int d = 0; d < NDT; ++d)
; #pragma unroll
;                 for (int r = 0; r < 16; ++r) o[d][r] *= f;
;         }
	v_mfma_f32_32x32x16_bf16 v[2:17], v[74:77], v[70:73], v[2:17]
	v_add_f32_e32 v94, v81, v66
	ds_read_b128 v[82:85], v148 offset:39936
	ds_read_b128 v[86:89], v148 offset:39968
	s_waitcnt lgkmcnt(1)
	v_mfma_f32_32x32x16_bf16 v[66:81], v[82:85], v[98:101], v[34:49]
	ds_read_b128 v[82:85], v148 offset:46592
	ds_read_b128 v[90:93], v148 offset:46624
	s_waitcnt lgkmcnt(1)
	v_mfma_f32_32x32x16_bf16 v[34:49], v[82:85], v[98:101], v[34:49]
	v_mfma_f32_32x32x16_bf16 v[66:81], v[86:89], v[102:105], v[66:81]
	ds_read_b128 v[82:85], v148 offset:40000
	ds_read_b128 v[86:89], v148 offset:40032
	s_waitcnt lgkmcnt(2)
	v_mfma_f32_32x32x16_bf16 v[34:49], v[90:93], v[102:105], v[34:49]
	s_waitcnt lgkmcnt(1)
	v_mfma_f32_32x32x16_bf16 v[66:81], v[82:85], v[106:109], v[66:81]
	ds_read_b128 v[82:85], v148 offset:46656
	ds_read_b128 v[90:93], v148 offset:46688
	s_waitcnt lgkmcnt(1)
	v_mfma_f32_32x32x16_bf16 v[34:49], v[82:85], v[106:109], v[34:49]
	v_mfma_f32_32x32x16_bf16 v[66:81], v[86:89], v[110:113], v[66:81]
	ds_read_b128 v[82:85], v148 offset:40064
	ds_read_b128 v[86:89], v148 offset:40096
	s_waitcnt lgkmcnt(2)
	v_mfma_f32_32x32x16_bf16 v[34:49], v[90:93], v[110:113], v[34:49]
	s_waitcnt lgkmcnt(1)
	v_mfma_f32_32x32x16_bf16 v[66:81], v[82:85], v[114:117], v[66:81]
	ds_read_b128 v[82:85], v148 offset:46720
	ds_read_b128 v[90:93], v148 offset:46752
	s_waitcnt lgkmcnt(1)
	v_mfma_f32_32x32x16_bf16 v[34:49], v[82:85], v[114:117], v[34:49]
	v_add_f32_e32 v82, v164, v94
	v_mfma_f32_32x32x16_bf16 v[66:81], v[86:89], v[118:121], v[66:81]
	s_waitcnt lgkmcnt(0)
	v_mfma_f32_32x32x16_bf16 v[34:49], v[90:93], v[118:121], v[34:49]
	s_nop 15
	s_nop 7
	s_nop 0
	v_max3_f32 v83, v66, v67, v34
	v_max3_f32 v84, v68, v69, v35
	v_max3_f32 v83, v83, v36, v37
	v_max3_f32 v84, v84, v72, v73
	v_max3_f32 v83, v83, v70, v71
	v_max3_f32 v84, v84, v40, v41
	v_max3_f32 v83, v83, v38, v39
	v_max3_f32 v84, v84, v76, v77
	v_max3_f32 v83, v83, v74, v75
	v_max3_f32 v84, v84, v44, v45
	v_max3_f32 v83, v83, v42, v43
	v_max3_f32 v84, v84, v80, v81
	v_max3_f32 v83, v83, v78, v79
	v_max3_f32 v84, v84, v48, v49
	v_max3_f32 v83, v83, v46, v47
	v_max_f32_e32 v83, v83, v84
	v_cmp_lt_f32_e32 vcc, s59, v83
	s_cbranch_vccz .LBB0_631
	ds_bpermute_b32 v50, v168, v83
	s_waitcnt lgkmcnt(0)
	v_max3_f32 v52, v83, v50, 0
	v_exp_f32_e64 v54, -v52
	v_add_f32_e32 v153, v153, v52
	v_xor_b32_e32 v50, 0x80000000, v153
	v_pk_add_f32 v[66:67], v[66:67], v[52:53] op_sel_hi:[1,0] neg_lo:[0,1] neg_hi:[0,1]
	v_pk_add_f32 v[34:35], v[34:35], v[52:53] op_sel_hi:[1,0] neg_lo:[0,1] neg_hi:[0,1]
	v_pk_add_f32 v[68:69], v[68:69], v[52:53] op_sel_hi:[1,0] neg_lo:[0,1] neg_hi:[0,1]
	v_pk_add_f32 v[36:37], v[36:37], v[52:53] op_sel_hi:[1,0] neg_lo:[0,1] neg_hi:[0,1]
	v_pk_add_f32 v[70:71], v[70:71], v[52:53] op_sel_hi:[1,0] neg_lo:[0,1] neg_hi:[0,1]
	v_pk_add_f32 v[38:39], v[38:39], v[52:53] op_sel_hi:[1,0] neg_lo:[0,1] neg_hi:[0,1]
	v_pk_add_f32 v[72:73], v[72:73], v[52:53] op_sel_hi:[1,0] neg_lo:[0,1] neg_hi:[0,1]
	v_pk_add_f32 v[40:41], v[40:41], v[52:53] op_sel_hi:[1,0] neg_lo:[0,1] neg_hi:[0,1]
	v_pk_add_f32 v[74:75], v[74:75], v[52:53] op_sel_hi:[1,0] neg_lo:[0,1] neg_hi:[0,1]
	v_pk_add_f32 v[42:43], v[42:43], v[52:53] op_sel_hi:[1,0] neg_lo:[0,1] neg_hi:[0,1]
	v_pk_add_f32 v[76:77], v[76:77], v[52:53] op_sel_hi:[1,0] neg_lo:[0,1] neg_hi:[0,1]
	v_pk_add_f32 v[44:45], v[44:45], v[52:53] op_sel_hi:[1,0] neg_lo:[0,1] neg_hi:[0,1]
	v_pk_add_f32 v[78:79], v[78:79], v[52:53] op_sel_hi:[1,0] neg_lo:[0,1] neg_hi:[0,1]
	v_pk_add_f32 v[46:47], v[46:47], v[52:53] op_sel_hi:[1,0] neg_lo:[0,1] neg_hi:[0,1]
	v_pk_add_f32 v[80:81], v[80:81], v[52:53] op_sel_hi:[1,0] neg_lo:[0,1] neg_hi:[0,1]
	v_pk_add_f32 v[48:49], v[48:49], v[52:53] op_sel_hi:[1,0] neg_lo:[0,1] neg_hi:[0,1]
	v_pk_mul_f32 v[32:33], v[32:33], v[54:55] op_sel_hi:[1,0]
	v_pk_mul_f32 v[30:31], v[30:31], v[54:55] op_sel_hi:[1,0]
	v_pk_mul_f32 v[28:29], v[28:29], v[54:55] op_sel_hi:[1,0]
	v_pk_mul_f32 v[26:27], v[26:27], v[54:55] op_sel_hi:[1,0]
	v_pk_mul_f32 v[24:25], v[24:25], v[54:55] op_sel_hi:[1,0]
	v_pk_mul_f32 v[22:23], v[22:23], v[54:55] op_sel_hi:[1,0]
	v_pk_mul_f32 v[20:21], v[20:21], v[54:55] op_sel_hi:[1,0]
	v_pk_mul_f32 v[18:19], v[18:19], v[54:55] op_sel_hi:[1,0]
	v_pk_mul_f32 v[16:17], v[16:17], v[54:55] op_sel_hi:[1,0]
	v_pk_mul_f32 v[14:15], v[14:15], v[54:55] op_sel_hi:[1,0]
	v_pk_mul_f32 v[12:13], v[12:13], v[54:55] op_sel_hi:[1,0]
	v_pk_mul_f32 v[10:11], v[10:11], v[54:55] op_sel_hi:[1,0]
	v_pk_mul_f32 v[8:9], v[8:9], v[54:55] op_sel_hi:[1,0]
	v_pk_mul_f32 v[6:7], v[6:7], v[54:55] op_sel_hi:[1,0]
	v_pk_mul_f32 v[4:5], v[4:5], v[54:55] op_sel_hi:[1,0]
	v_pk_mul_f32 v[2:3], v[2:3], v[54:55] op_sel_hi:[1,0]
	v_mul_f32_e32 v82, v82, v54
	v_mov_b32_e32 v51, v50
	v_mov_b32_e32 v52, v50
	v_mov_b32_e32 v53, v50
	v_mov_b32_e32 v54, v50
	v_mov_b32_e32 v55, v50
	v_mov_b32_e32 v56, v50
	v_mov_b32_e32 v57, v50
	v_mov_b32_e32 v58, v50
	v_mov_b32_e32 v59, v50
	v_mov_b32_e32 v60, v50
	v_mov_b32_e32 v61, v50
	v_mov_b32_e32 v62, v50
	v_mov_b32_e32 v63, v50
	v_mov_b32_e32 v64, v50
	v_mov_b32_e32 v65, v50
	s_branch .LBB0_631

; #define LAS __attribute__((address_space(3)))
; __global__ void __launch_bounds__(512, 2) fwd_mega(Params Pv) {
;     extern __shared__ __attribute__((aligned(16))) unsigned char lds_raw[];
;     LAS unsigned char* lds = (LAS unsigned char*)lds_raw;
;     const int G = gridDim.x, bx = blockIdx.x; const int vcu = (G % 8 == 0) ? (bx % 8) * (G / 8) + bx / 8 : bx; const int NGW = G * 8;
	.amdhsa_kernel _Z8fwd_mega6Params
		.amdhsa_group_segment_fixed_size 0
		.amdhsa_private_segment_fixed_size 0
		.amdhsa_kernarg_size 552
		.amdhsa_user_sgpr_count 2
		.amdhsa_user_sgpr_dispatch_ptr 0
		.amdhsa_user_sgpr_queue_ptr 0
		.amdhsa_user_sgpr_kernarg_segment_ptr 1
		.amdhsa_user_sgpr_dispatch_id 0
		.amdhsa_user_sgpr_kernarg_preload_length 0
		.amdhsa_user_sgpr_kernarg_preload_offset 0
		.amdhsa_user_sgpr_private_segment_size 0
		.amdhsa_uses_dynamic_stack 0
		.amdhsa_enable_private_segment 0
		.amdhsa_system_sgpr_workgroup_id_x 1
		.amdhsa_system_sgpr_workgroup_id_y 0
		.amdhsa_system_sgpr_workgroup_id_z 0
		.amdhsa_system_sgpr_workgroup_info 0
		.amdhsa_system_vgpr_workitem_id 2
		.amdhsa_next_free_vgpr 232
		.amdhsa_next_free_sgpr 102
		.amdhsa_accum_offset 232
		.amdhsa_reserve_vcc 1
		.amdhsa_float_round_mode_32 0
		.amdhsa_float_round_mode_16_64 0
		.amdhsa_float_denorm_mode_32 3
		.amdhsa_float_denorm_mode_16_64 3
		.amdhsa_dx10_clamp 1
		.amdhsa_ieee_mode 1
		.amdhsa_fp16_overflow 0
		.amdhsa_tg_split 0
		.amdhsa_exception_fp_ieee_invalid_op 0
		.amdhsa_exception_fp_denorm_src 0
		.amdhsa_exception_fp_ieee_div_zero 0
		.amdhsa_exception_fp_ieee_overflow 0
		.amdhsa_exception_fp_ieee_underflow 0
		.amdhsa_exception_fp_ieee_inexact 0
		.amdhsa_exception_int_div_zero 0
	.end_amdhsa_kernel

; #define LAS __attribute__((address_space(3)))
; __global__ void __launch_bounds__(512, 2) fwd_mega(Params Pv) {
;     extern __shared__ __attribute__((aligned(16))) unsigned char lds_raw[];
;     LAS unsigned char* lds = (LAS unsigned char*)lds_raw;
amdhsa.kernels:
  - .agpr_count:     0
    .args:
      - .offset:         0
        .size:           296
        .value_kind:     by_value
      - .offset:         296
        .size:           4
        .value_kind:     hidden_block_count_x
      - .offset:         300
        .size:           4
        .value_kind:     hidden_block_count_y
      - .offset:         304
        .size:           4
        .value_kind:     hidden_block_count_z
      - .offset:         308
        .size:           2
        .value_kind:     hidden_group_size_x
      - .offset:         310
        .size:           2
        .value_kind:     hidden_group_size_y
      - .offset:         312
        .size:           2
        .value_kind:     hidden_group_size_z
      - .offset:         314
        .size:           2
        .value_kind:     hidden_remainder_x
      - .offset:         316
        .size:           2
        .value_kind:     hidden_remainder_y
      - .offset:         318
        .size:           2
        .value_kind:     hidden_remainder_z
      - .offset:         336
        .size:           8
        .value_kind:     hidden_global_offset_x
      - .offset:         344
        .size:           8
        .value_kind:     hidden_global_offset_y
      - .offset:         352
        .size:           8
        .value_kind:     hidden_global_offset_z
      - .offset:         360
        .size:           2
        .value_kind:     hidden_grid_dims
      - .offset:         384
        .size:           8
        .value_kind:     hidden_multigrid_sync_arg
      - .offset:         416
        .size:           4
        .value_kind:     hidden_dynamic_lds_size
    .group_segment_fixed_size: 0
    .kernarg_segment_align: 8
    .kernarg_segment_size: 552
    .language:       OpenCL C
    .language_version:
      - 2
      - 0
    .max_flat_workgroup_size: 512
    .name:           _Z8fwd_mega6Params
    .private_segment_fixed_size: 0
    .sgpr_count:     108
    .sgpr_spill_count: 0
    .symbol:         _Z8fwd_mega6Params.kd
    .uniform_work_group_size: 1
    .uses_dynamic_stack: false
    .vgpr_count:     232
    .vgpr_spill_count: 0
    .wavefront_size: 64
